# softmax row sums: drop additions of +0.0 (x+0 -> x)
# speedup vs baseline: 1.0257x; 1.0041x over previous
; __device__ __forceinline__ float ex2(float x) { return __builtin_amdgcn_exp2f(x); }
;   __device__ __forceinline__ bf16_t* W() const { return (bf16_t*)(ws + WS_W); }
; template <int NT, int NKK, int NDT, int MODE, bool MASK> ...
;     ...
;   for (int j = 0; j < NT; ++j) {
;     float mx = -INFINITY;
; #pragma unroll
;     for (int t = 0; t < 4; ++t)
; #pragma unroll
;       for (int i = 0; i < 4; ++i) {
;         if (MASK) { const int kp = kpos0 + 16 * t + 4 * lg + i; if (!mask_ok<MODE>(tq[j], kp, W)) s[j][t][i] = -INFINITY; }
;         mx = fmaxf(mx, s[j][t][i]);
;       }
;     mx = max_x16_x32(mx);
;     if (__any(mx > m[j] + 8.0f / c)) {
;       const float mnew = fmaxf(m[j], mx);
;       const float ms2 = (mnew == -INFINITY) ? 0.f : mnew;
;       const float alpha = ex2((m[j] - ms2) * c);
;       m[j] = mnew; l[j] *= alpha;
; #pragma unroll
;       for (int dt = 0; dt < NDT; ++dt) o[j][dt] *= alpha;
;     }
;     const float mc = ((m[j] == -INFINITY) ? 0.f : m[j]) * c;
;     float p[4][4], ps = 0.f;
; #pragma unroll
;     for (int t = 0; t < 4; ++t)
; #pragma unroll
;       for (int i = 0; i < 4; ++i) { p[t][i] = ex2(s[j][t][i] * c - mc); ps += p[t][i]; }
;     l[j] += ps;
;     pf[j][0] = pack8(p[0], p[1]); pf[j][1] = pack8(p[2], p[3]);
.LBB0_772:
	v_mul_f32_e32 v186, 0x3e16c740, v187
	v_cmp_neq_f32_e32 vcc, s81, v187
	s_nop 1
	v_cndmask_b32_e32 v186, 0, v186, vcc
	v_fma_f32 v182, v182, s88, -v186
	v_exp_f32_e32 v205, v182
	v_fma_f32 v182, v183, s88, -v186
	v_exp_f32_e32 v207, v182
	v_fma_f32 v182, v184, s88, -v186
	v_exp_f32_e32 v246, v182
	v_fma_f32 v182, v185, s88, -v186
	v_exp_f32_e32 v247, v182
	v_fma_f32 v178, v178, s88, -v186
	v_exp_f32_e32 v248, v178
	v_fma_f32 v178, v179, s88, -v186
	v_add_f32_e32 v182, v207, v205
	v_exp_f32_e32 v249, v178
	v_fma_f32 v178, v180, s88, -v186
	v_add_f32_e32 v182, v246, v182
	v_exp_f32_e32 v250, v178
	v_fma_f32 v178, v181, s88, -v186
	v_add_f32_e32 v182, v247, v182
	v_exp_f32_e32 v251, v178
	v_fma_f32 v174, v174, s88, -v186
	v_add_f32_e32 v178, v248, v182
	v_exp_f32_e32 v252, v174
	v_fma_f32 v174, v175, s88, -v186
	v_add_f32_e32 v178, v249, v178
	v_exp_f32_e32 v231, v174
	v_fma_f32 v174, v176, s88, -v186
	v_add_f32_e32 v178, v250, v178
	v_exp_f32_e32 v229, v174
	v_fma_f32 v174, v177, s88, -v186
	v_add_f32_e32 v178, v251, v178
	v_exp_f32_e32 v230, v174
	v_fma_f32 v170, v170, s88, -v186
	v_add_f32_e32 v174, v252, v178
	v_exp_f32_e32 v232, v170
	v_fma_f32 v170, v171, s88, -v186
	v_add_f32_e32 v174, v231, v174
	v_exp_f32_e32 v228, v170
	v_fma_f32 v170, v172, s88, -v186
	v_add_f32_e32 v174, v229, v174
	v_exp_f32_e32 v196, v170
	v_fma_f32 v170, v173, s88, -v186
	v_add_f32_e32 v174, v230, v174
	v_exp_f32_e32 v173, v170
	v_add_f32_e32 v170, v232, v174
	v_add_f32_e32 v170, v228, v170
	v_add_f32_e32 v170, v196, v170
	v_add_f32_e32 v170, v173, v170
	v_add_f32_e32 v224, v224, v170
	v_max3_f32 v170, v166, s81, v167
	v_max3_f32 v170, v170, v168, v169
	v_max3_f32 v170, v170, v154, v155
	v_max3_f32 v170, v170, v156, v157
	v_max3_f32 v170, v170, v150, v151
	v_max3_f32 v170, v170, v152, v153
	v_max3_f32 v170, v170, v142, v143
	v_max3_f32 v170, v170, v144, v145
	v_mov_b32_e32 v171, v170
	s_nop 1
	v_permlane16_swap_b32_e32 v170, v171
	v_max_f32_e32 v170, v170, v171
	v_mov_b32_e32 v171, v170
	s_nop 1
	v_permlane32_swap_b32_e32 v170, v171
	v_max_f32_e32 v170, v170, v171
	v_add_f32_e32 v171, 0x4259535f, v223
	v_cmp_gt_f32_e32 vcc, v170, v171
	s_cbranch_vccz .LBB0_786
	v_max_f32_e32 v170, v170, v170
	v_max_f32_e32 v171, v223, v223
	v_max_f32_e32 v197, v171, v170
	v_cmp_neq_f32_e32 vcc, s81, v197
	s_nop 1
	v_cndmask_b32_e32 v170, 0, v197, vcc
	v_sub_f32_e32 v170, v223, v170
	v_mul_f32_e32 v170, 0x3e16c740, v170
	v_exp_f32_e32 v170, v170
	v_mov_b32_e32 v223, v197
	v_mul_f32_e32 v225, v225, v170
	v_pk_mul_f32 v[84:85], v[84:85], v[170:171] op_sel_hi:[1,0]
	v_pk_mul_f32 v[82:83], v[82:83], v[170:171] op_sel_hi:[1,0]
	v_pk_mul_f32 v[80:81], v[80:81], v[170:171] op_sel_hi:[1,0]
	v_pk_mul_f32 v[78:79], v[78:79], v[170:171] op_sel_hi:[1,0]
	v_pk_mul_f32 v[72:73], v[72:73], v[170:171] op_sel_hi:[1,0]
	v_pk_mul_f32 v[70:71], v[70:71], v[170:171] op_sel_hi:[1,0]
	v_pk_mul_f32 v[64:65], v[64:65], v[170:171] op_sel_hi:[1,0]
	v_pk_mul_f32 v[62:63], v[62:63], v[170:171] op_sel_hi:[1,0]
	s_branch .LBB0_787

; __device__ __forceinline__ float ex2(float x) { return __builtin_amdgcn_exp2f(x); }
; __device__ __forceinline__ f32x4 mfma16(bf16x8 a, bf16x8 b, f32x4 c) { return __builtin_amdgcn_mfma_f32_16x16x32_bf16(a, b, c, 0, 0, 0); }
; __device__ __forceinline__ s16x4 ds_tr(LAS const unsigned char* p) { return __builtin_bit_cast(s16x4, __builtin_amdgcn_ds_read_tr16_b64_v4i16((LAS v4i16_t*)p)); }
; template <int NT, int NKK, int NDT, int MODE, bool MASK> ...
;     ...
;     const float mc = ((m[j] == -INFINITY) ? 0.f : m[j]) * c;
;     float p[4][4], ps = 0.f;
; #pragma unroll
;     for (int t = 0; t < 4; ++t)
; #pragma unroll
;       for (int i = 0; i < 4; ++i) { p[t][i] = ex2(s[j][t][i] * c - mc); ps += p[t][i]; }
;     l[j] += ps;
;     pf[j][0] = pack8(p[0], p[1]); pf[j][1] = pack8(p[2], p[3]);
;   }
;   __builtin_amdgcn_s_setprio(1);
; #pragma unroll
;   for (int st = 0; st < 2; ++st)
; #pragma unroll
;     for (int dt = 0; dt < NDT; ++dt) {
;       const s16x4 v0 = ds_tr(Vl + (32 * st + 4 * lg + vq) * VSTR + (16 * dt + 4 * vp) * 2);
;       const s16x4 v1 = ds_tr(Vl + (32 * st + 16 + 4 * lg + vq) * VSTR + (16 * dt + 4 * vp) * 2);
;       const bf16x8 vf = (bf16x8){v0[0], v0[1], v0[2], v0[3], v1[0], v1[1], v1[2], v1[3]};
; #pragma unroll
;       for (int j = 0; j < NT; ++j) o[j][dt] = mfma16(vf, pf[j][st], o[j][dt]);
;     }
;   __builtin_amdgcn_s_setprio(0);
.LBB0_787:
	v_cvt_pk_bf16_f32 v173, v196, v173
	v_mul_f32_e32 v196, 0x3e16c740, v197
	v_cmp_neq_f32_e32 vcc, s81, v197
	v_cvt_pk_bf16_f32 v172, v232, v228
	v_cvt_pk_bf16_f32 v228, v205, v207
	v_cndmask_b32_e32 v196, 0, v196, vcc
	v_fma_f32 v166, v166, s88, -v196
	v_exp_f32_e32 v166, v166
	v_fma_f32 v167, v167, s88, -v196
	v_exp_f32_e32 v167, v167
	v_fma_f32 v168, v168, s88, -v196
	v_exp_f32_e32 v168, v168
	v_fma_f32 v169, v169, s88, -v196
	v_exp_f32_e32 v169, v169
	v_fma_f32 v154, v154, s88, -v196
	v_exp_f32_e32 v154, v154
	v_fma_f32 v155, v155, s88, -v196
	v_add_f32_e32 v197, v167, v166
	v_exp_f32_e32 v155, v155
	v_fma_f32 v156, v156, s88, -v196
	v_add_f32_e32 v197, v168, v197
	v_exp_f32_e32 v156, v156
	v_fma_f32 v157, v157, s88, -v196
	v_add_f32_e32 v197, v169, v197
	v_exp_f32_e32 v157, v157
	v_fma_f32 v150, v150, s88, -v196
	v_add_f32_e32 v197, v154, v197
	v_exp_f32_e32 v150, v150
	v_fma_f32 v151, v151, s88, -v196
	v_add_f32_e32 v197, v155, v197
	v_exp_f32_e32 v151, v151
	v_fma_f32 v152, v152, s88, -v196
	v_add_f32_e32 v197, v156, v197
	v_exp_f32_e32 v152, v152
	v_fma_f32 v153, v153, s88, -v196
	v_add_f32_e32 v197, v157, v197
	v_exp_f32_e32 v153, v153
	v_fma_f32 v142, v142, s88, -v196
	v_add_f32_e32 v197, v150, v197
	v_exp_f32_e32 v198, v142
	v_fma_f32 v142, v143, s88, -v196
	v_add_f32_e32 v197, v151, v197
	v_exp_f32_e32 v199, v142
	v_fma_f32 v142, v144, s88, -v196
	v_add_f32_e32 v197, v152, v197
	v_exp_f32_e32 v205, v142
	v_fma_f32 v142, v145, s88, -v196
	v_add_f32_e32 v197, v153, v197
	v_exp_f32_e32 v196, v142
	v_add_f32_e32 v142, v198, v197
	v_add_f32_e32 v142, v199, v142
	v_add_f32_e32 v142, v205, v142
	v_add_f32_e32 v142, v196, v142
	v_add_f32_e32 v225, v225, v142
	v_cvt_pk_bf16_f32 v142, v166, v167
	v_cvt_pk_bf16_f32 v143, v168, v169
	v_cvt_pk_bf16_f32 v144, v154, v155
	v_cvt_pk_bf16_f32 v145, v156, v157
	v_cvt_pk_bf16_f32 v170, v252, v231
	v_cvt_pk_bf16_f32 v171, v229, v230
	v_cvt_pk_bf16_f32 v229, v246, v247
	v_cvt_pk_bf16_f32 v230, v248, v249
	v_cvt_pk_bf16_f32 v231, v250, v251
	v_cvt_pk_bf16_f32 v246, v150, v151
	v_cvt_pk_bf16_f32 v247, v152, v153
	v_cvt_pk_bf16_f32 v248, v198, v199
	v_cvt_pk_bf16_f32 v249, v205, v196
	s_setprio 1
	v_add3_u32 v196, s71, v240, v239
	ds_read_b64_tr_b16 v[152:153], v196 offset:15872
	ds_read_b64_tr_b16 v[150:151], v196 offset:13312
	ds_read_b64_tr_b16 v[154:155], v196 offset:13344
	ds_read_b64_tr_b16 v[156:157], v196 offset:15904
	ds_read_b64_tr_b16 v[166:167], v196 offset:13376
	ds_read_b64_tr_b16 v[168:169], v196 offset:15936
	s_mov_b64 s[20:21], 0
	s_waitcnt lgkmcnt(4)
	v_mfma_f32_16x16x32_bf16 v[158:161], v[150:153], v[228:231], v[90:93]
	v_mfma_f32_16x16x32_bf16 v[150:153], v[150:153], v[142:145], v[82:85]
	s_waitcnt lgkmcnt(0)
	v_mfma_f32_16x16x32_bf16 v[182:185], v[166:169], v[228:231], v[74:77]
	s_nop 2
	ds_read_b64_tr_b16 v[146:147], v196 offset:13408
	ds_read_b64_tr_b16 v[148:149], v196 offset:15968
	v_mfma_f32_16x16x32_bf16 v[162:165], v[154:157], v[228:231], v[86:89]
	v_mfma_f32_16x16x32_bf16 v[154:157], v[154:157], v[142:145], v[78:81]
	v_mfma_f32_16x16x32_bf16 v[166:169], v[166:169], v[142:145], v[70:73]
	s_waitcnt lgkmcnt(0)
	v_mfma_f32_16x16x32_bf16 v[174:177], v[146:149], v[142:145], v[62:65]
	ds_read_b64_tr_b16 v[142:143], v196 offset:18432
	ds_read_b64_tr_b16 v[144:145], v196 offset:20992
	v_mfma_f32_16x16x32_bf16 v[178:181], v[146:149], v[228:231], v[66:69]
	s_waitcnt lgkmcnt(0)
	v_mfma_f32_16x16x32_bf16 v[90:93], v[142:145], v[170:173], v[158:161]
	v_mfma_f32_16x16x32_bf16 v[82:85], v[142:145], v[246:249], v[150:153]
	s_nop 2
	ds_read_b64_tr_b16 v[150:151], v196 offset:18464
	ds_read_b64_tr_b16 v[152:153], v196 offset:21024
	ds_read_b64_tr_b16 v[158:159], v196 offset:18496
	ds_read_b64_tr_b16 v[160:161], v196 offset:21056
	s_waitcnt lgkmcnt(2)
	v_mfma_f32_16x16x32_bf16 v[86:89], v[150:153], v[170:173], v[162:165]
	s_nop 2
	ds_read_b64_tr_b16 v[162:163], v196 offset:18528
	ds_read_b64_tr_b16 v[164:165], v196 offset:21088
	v_mfma_f32_16x16x32_bf16 v[78:81], v[150:153], v[246:249], v[154:157]
	s_waitcnt lgkmcnt(2)
	v_mfma_f32_16x16x32_bf16 v[74:77], v[158:161], v[170:173], v[182:185]
	v_mfma_f32_16x16x32_bf16 v[70:73], v[158:161], v[246:249], v[166:169]
	s_waitcnt lgkmcnt(0)
	v_mfma_f32_16x16x32_bf16 v[66:69], v[162:165], v[170:173], v[178:181]
	v_mfma_f32_16x16x32_bf16 v[62:65], v[162:165], v[246:249], v[174:177]
	s_setprio 0
	s_branch .Lmla_post_0

; __device__ __forceinline__ float ex2(float x) { return __builtin_amdgcn_exp2f(x); }
;   __device__ __forceinline__ bf16_t* W() const { return (bf16_t*)(ws + WS_W); }
; template <int MODE> __device__ __forceinline__ bool mask_ok(int tq, int kp, int W) {
;   if (MODE == MODE_CAUSAL) return kp <= tq;
;   if (MODE == MODE_WINDOW) return kp <= tq && kp > tq - W;
;   if (MODE == MODE_CMP) return 16 * kp + 31 <= tq;
;   return true;
; template <int NT, int NKK, int NDT, int MODE, bool MASK> ...
;     ...
;   for (int j = 0; j < NT; ++j) {
;     float mx = -INFINITY;
; #pragma unroll
;     for (int t = 0; t < 4; ++t)
; #pragma unroll
;       for (int i = 0; i < 4; ++i) {
;         if (MASK) { const int kp = kpos0 + 16 * t + 4 * lg + i; if (!mask_ok<MODE>(tq[j], kp, W)) s[j][t][i] = -INFINITY; }
;         mx = fmaxf(mx, s[j][t][i]);
;       }
;     mx = max_x16_x32(mx);
;     if (__any(mx > m[j] + 8.0f / c)) {
;       const float mnew = fmaxf(m[j], mx);
;       const float ms2 = (mnew == -INFINITY) ? 0.f : mnew;
;       const float alpha = ex2((m[j] - ms2) * c);
;       m[j] = mnew; l[j] *= alpha;
; #pragma unroll
;       for (int dt = 0; dt < NDT; ++dt) o[j][dt] *= alpha;
;     }
;     const float mc = ((m[j] == -INFINITY) ? 0.f : m[j]) * c;
;     float p[4][4], ps = 0.f;
; #pragma unroll
;     for (int t = 0; t < 4; ++t)
; #pragma unroll
;       for (int i = 0; i < 4; ++i) { p[t][i] = ex2(s[j][t][i] * c - mc); ps += p[t][i]; }
;     l[j] += ps;
;     pf[j][0] = pack8(p[0], p[1]); pf[j][1] = pack8(p[2], p[3]);
.LBB0_792:
	v_mul_f32_e32 v103, 0x3e16c740, v102
	v_cmp_neq_f32_e32 vcc, s81, v102
	v_cndmask_b32_e64 v1, v142, v130, s[22:23]
	v_cmp_lt_i32_e64 s[22:23], v104, v202
	v_cndmask_b32_e32 v142, 0, v103, vcc
	v_fma_f32 v1, v1, s88, -v142
	v_exp_f32_e32 v1, v1
	v_fma_f32 v102, v122, s88, -v142
	v_exp_f32_e32 v102, v102
	v_fma_f32 v103, v124, s88, -v142
	v_exp_f32_e32 v103, v103
	v_fma_f32 v122, v123, s88, -v142
	v_exp_f32_e32 v122, v122
	v_add_f32_e32 v123, v102, v1
	v_add_f32_e32 v123, v103, v123
	v_add_f32_e32 v143, v122, v123
	v_fma_f32 v123, v125, s88, -v142
	v_exp_f32_e32 v123, v123
	v_fma_f32 v124, v131, s88, -v142
	v_exp_f32_e32 v124, v124
	v_fma_f32 v125, v133, s88, -v142
	v_exp_f32_e32 v125, v125
	v_fma_f32 v130, v132, s88, -v142
	v_exp_f32_e32 v130, v130
	v_add_f32_e32 v131, v123, v143
	v_add_f32_e32 v131, v124, v131
	v_add_f32_e32 v131, v125, v131
	v_add_f32_e32 v143, v130, v131
	v_fma_f32 v131, v134, s88, -v142
	v_exp_f32_e32 v131, v131
	v_fma_f32 v132, v135, s88, -v142
	v_exp_f32_e32 v132, v132
	v_fma_f32 v133, v137, s88, -v142
	v_exp_f32_e32 v133, v133
	v_fma_f32 v134, v136, s88, -v142
	v_exp_f32_e32 v134, v134
	v_add_f32_e32 v135, v131, v143
	v_add_f32_e32 v135, v132, v135
	v_add_f32_e32 v135, v133, v135
	v_add_f32_e32 v136, v134, v135
	v_fma_f32 v135, v138, s88, -v142
	v_exp_f32_e32 v135, v135
	v_fma_f32 v137, v139, s88, -v142
	v_exp_f32_e32 v138, v137
	v_fma_f32 v137, v141, s88, -v142
	v_exp_f32_e32 v139, v137
	v_fma_f32 v137, v140, s88, -v142
	v_exp_f32_e32 v140, v137
	v_add_f32_e32 v136, v135, v136
	v_add_f32_e32 v136, v138, v136
	v_add_f32_e32 v136, v139, v136
	v_add_f32_e32 v136, v140, v136
	v_add_f32_e32 v218, v218, v136
	v_mov_b32_e32 v136, s81
	v_cmp_gt_i32_e32 vcc, v104, v202
	s_nop 1
	v_cndmask_b32_e32 v141, v126, v136, vcc
	v_cmp_le_i32_e32 vcc, v105, v202
	v_cndmask_b32_e64 v136, v200, v127, s[22:23]
	v_max3_f32 v104, v141, s81, v136
	v_cndmask_b32_e32 v137, v200, v128, vcc
	v_cmp_le_i32_e32 vcc, v106, v202
	s_nop 1
	v_cndmask_b32_e32 v128, v200, v129, vcc
	v_max3_f32 v105, v104, v137, v128
	v_mov_b32_e32 v104, s81
	v_cmp_le_i32_e32 vcc, v107, v202
	v_cndmask_b32_e64 v127, v114, v104, s[20:21]
	s_nop 0
	v_cndmask_b32_e32 v114, v200, v115, vcc
	v_cmp_le_i32_e32 vcc, v108, v202
	v_max3_f32 v104, v105, v127, v114
	s_nop 0
	v_cndmask_b32_e32 v115, v200, v116, vcc
	v_cmp_le_i32_e32 vcc, v110, v202
	s_nop 1
	v_cndmask_b32_e32 v108, v200, v117, vcc
	v_max3_f32 v106, v104, v115, v108
	v_mov_b32_e32 v104, s81
	v_cmp_gt_i32_e32 vcc, v109, v202
	s_nop 1
	v_cndmask_b32_e32 v107, v98, v104, vcc
	v_cmp_le_i32_e32 vcc, v111, v202
	s_nop 1
	v_cndmask_b32_e32 v105, v200, v99, vcc
	v_cmp_le_i32_e32 vcc, v112, v202
	v_max3_f32 v98, v106, v107, v105
	s_nop 0
	v_cndmask_b32_e32 v106, v200, v100, vcc
	v_cmp_le_i32_e32 vcc, v118, v202
	s_nop 1
	v_cndmask_b32_e32 v104, v200, v101, vcc
	v_max3_f32 v100, v98, v106, v104
	v_mov_b32_e32 v98, s81
	v_cmp_gt_i32_e32 vcc, v113, v202
	s_nop 1
	v_cndmask_b32_e32 v101, v94, v98, vcc
	v_cmp_le_i32_e32 vcc, v119, v202
	s_nop 1
	v_cndmask_b32_e32 v99, v200, v95, vcc
	v_cmp_le_i32_e32 vcc, v120, v202
	v_max3_f32 v94, v100, v101, v99
	s_nop 0
	v_cndmask_b32_e32 v100, v200, v96, vcc
	v_cmp_le_i32_e32 vcc, v121, v202
	s_nop 1
	v_cndmask_b32_e32 v98, v200, v97, vcc
	v_max3_f32 v94, v94, v100, v98
	v_mov_b32_e32 v95, v94
	s_nop 1
	v_permlane16_swap_b32_e32 v94, v95
	v_max_f32_e32 v94, v94, v95
	v_mov_b32_e32 v95, v94
	s_nop 1
	v_permlane32_swap_b32_e32 v94, v95
	v_max_f32_e32 v94, v94, v95
	v_add_f32_e32 v95, 0x4259535f, v221
	v_cmp_gt_f32_e32 vcc, v94, v95
	s_cbranch_vccz .LBB0_794
	v_max_f32_e32 v94, v94, v94
	v_max_f32_e32 v95, v221, v221
	v_max_f32_e32 v109, v95, v94
	v_cmp_neq_f32_e32 vcc, s81, v109
	s_nop 1
	v_cndmask_b32_e32 v94, 0, v109, vcc
	v_sub_f32_e32 v94, v221, v94
	v_mul_f32_e32 v94, 0x3e16c740, v94
	v_exp_f32_e32 v94, v94
	v_mov_b32_e32 v221, v109
	v_mul_f32_e32 v219, v219, v94
	v_pk_mul_f32 v[84:85], v[84:85], v[94:95] op_sel_hi:[1,0]
	v_pk_mul_f32 v[82:83], v[82:83], v[94:95] op_sel_hi:[1,0]
	v_pk_mul_f32 v[80:81], v[80:81], v[94:95] op_sel_hi:[1,0]
	v_pk_mul_f32 v[78:79], v[78:79], v[94:95] op_sel_hi:[1,0]
	v_pk_mul_f32 v[72:73], v[72:73], v[94:95] op_sel_hi:[1,0]
	v_pk_mul_f32 v[70:71], v[70:71], v[94:95] op_sel_hi:[1,0]
	v_pk_mul_f32 v[64:65], v[64:65], v[94:95] op_sel_hi:[1,0]
	v_pk_mul_f32 v[62:63], v[62:63], v[94:95] op_sel_hi:[1,0]
	s_branch .LBB0_795

; __device__ __forceinline__ float ex2(float x) { return __builtin_amdgcn_exp2f(x); }
; __device__ __forceinline__ f32x4 mfma16(bf16x8 a, bf16x8 b, f32x4 c) { return __builtin_amdgcn_mfma_f32_16x16x32_bf16(a, b, c, 0, 0, 0); }
; __device__ __forceinline__ s16x4 ds_tr(LAS const unsigned char* p) { return __builtin_bit_cast(s16x4, __builtin_amdgcn_ds_read_tr16_b64_v4i16((LAS v4i16_t*)p)); }
; template <int NT, int NKK, int NDT, int MODE, bool MASK> ...
;     ...
;     const float mc = ((m[j] == -INFINITY) ? 0.f : m[j]) * c;
;     float p[4][4], ps = 0.f;
; #pragma unroll
;     for (int t = 0; t < 4; ++t)
; #pragma unroll
;       for (int i = 0; i < 4; ++i) { p[t][i] = ex2(s[j][t][i] * c - mc); ps += p[t][i]; }
;     l[j] += ps;
;     pf[j][0] = pack8(p[0], p[1]); pf[j][1] = pack8(p[2], p[3]);
;   }
;   __builtin_amdgcn_s_setprio(1);
; #pragma unroll
;   for (int st = 0; st < 2; ++st)
; #pragma unroll
;     for (int dt = 0; dt < NDT; ++dt) {
;       const s16x4 v0 = ds_tr(Vl + (32 * st + 4 * lg + vq) * VSTR + (16 * dt + 4 * vp) * 2);
;       const s16x4 v1 = ds_tr(Vl + (32 * st + 16 + 4 * lg + vq) * VSTR + (16 * dt + 4 * vp) * 2);
;       const bf16x8 vf = (bf16x8){v0[0], v0[1], v0[2], v0[3], v1[0], v1[1], v1[2], v1[3]};
; #pragma unroll
;       for (int j = 0; j < NT; ++j) o[j][dt] = mfma16(vf, pf[j][st], o[j][dt]);
;     }
;   __builtin_amdgcn_s_setprio(0);
.LBB0_795:
	v_cvt_pk_bf16_f32 v110, v1, v102
	v_mul_f32_e32 v1, 0x3e16c740, v109
	v_cmp_neq_f32_e32 vcc, s81, v109
	v_cndmask_b32_e64 v116, v141, v126, s[22:23]
	v_cvt_pk_bf16_f32 v111, v103, v122
	v_cndmask_b32_e32 v1, 0, v1, vcc
	v_fma_f32 v102, v116, s88, -v1
	v_exp_f32_e32 v102, v102
	v_fma_f32 v103, v136, s88, -v1
	v_exp_f32_e32 v103, v103
	v_fma_f32 v109, v137, s88, -v1
	v_exp_f32_e32 v109, v109
	v_fma_f32 v116, v128, s88, -v1
	v_exp_f32_e32 v116, v116
	v_fma_f32 v118, v127, s88, -v1
	v_exp_f32_e32 v118, v118
	v_fma_f32 v114, v114, s88, -v1
	v_add_f32_e32 v117, v103, v102
	v_exp_f32_e32 v114, v114
	v_fma_f32 v115, v115, s88, -v1
	v_add_f32_e32 v117, v109, v117
	v_exp_f32_e32 v115, v115
	v_fma_f32 v108, v108, s88, -v1
	v_add_f32_e32 v117, v116, v117
	v_exp_f32_e32 v108, v108
	v_fma_f32 v107, v107, s88, -v1
	v_add_f32_e32 v117, v118, v117
	v_exp_f32_e32 v107, v107
	v_fma_f32 v105, v105, s88, -v1
	v_add_f32_e32 v117, v114, v117
	v_exp_f32_e32 v105, v105
	v_fma_f32 v106, v106, s88, -v1
	v_add_f32_e32 v117, v115, v117
	v_exp_f32_e32 v106, v106
	v_fma_f32 v104, v104, s88, -v1
	v_add_f32_e32 v117, v108, v117
	v_exp_f32_e32 v104, v104
	v_fma_f32 v101, v101, s88, -v1
	v_add_f32_e32 v117, v107, v117
	v_exp_f32_e32 v119, v101
	v_fma_f32 v99, v99, s88, -v1
	v_add_f32_e32 v117, v105, v117
	v_exp_f32_e32 v120, v99
	v_fma_f32 v99, v100, s88, -v1
	v_add_f32_e32 v117, v106, v117
	v_exp_f32_e32 v121, v99
	v_fma_f32 v1, v98, s88, -v1
	v_add_f32_e32 v117, v104, v117
	v_exp_f32_e32 v1, v1
	v_add_f32_e32 v98, v119, v117
	v_add_f32_e32 v98, v120, v98
	v_add_f32_e32 v98, v121, v98
	v_add_f32_e32 v98, v1, v98
	v_cvt_pk_bf16_f32 v94, v131, v132
	v_cvt_pk_bf16_f32 v95, v133, v134
	v_cvt_pk_bf16_f32 v96, v135, v138
	v_cvt_pk_bf16_f32 v97, v139, v140
	v_cvt_pk_bf16_f32 v112, v123, v124
	v_cvt_pk_bf16_f32 v113, v125, v130
	v_add_f32_e32 v219, v219, v98
	v_cvt_pk_bf16_f32 v98, v102, v103
	v_cvt_pk_bf16_f32 v99, v109, v116
	v_cvt_pk_bf16_f32 v100, v118, v114
	v_cvt_pk_bf16_f32 v101, v115, v108
	v_cvt_pk_bf16_f32 v102, v107, v105
	v_cvt_pk_bf16_f32 v103, v106, v104
	v_cvt_pk_bf16_f32 v104, v119, v120
	v_cvt_pk_bf16_f32 v105, v121, v1
	s_setprio 1
	v_add3_u32 v1, s71, v240, v239
	ds_read_b64_tr_b16 v[108:109], v1 offset:15872
	ds_read_b64_tr_b16 v[106:107], v1 offset:13312
	ds_read_b64_tr_b16 v[114:115], v1 offset:13344
	ds_read_b64_tr_b16 v[116:117], v1 offset:15904
	v_mov_b64_e32 v[224:225], v[218:219]
	v_mov_b64_e32 v[222:223], v[220:221]
	s_waitcnt lgkmcnt(2)
	v_mfma_f32_16x16x32_bf16 v[90:93], v[106:109], v[110:113], v[90:93]
	v_mfma_f32_16x16x32_bf16 v[82:85], v[106:109], v[98:101], v[82:85]
	ds_read_b64_tr_b16 v[106:107], v1 offset:13376
	ds_read_b64_tr_b16 v[108:109], v1 offset:15936
	s_waitcnt lgkmcnt(0)
	v_mfma_f32_16x16x32_bf16 v[74:77], v[106:109], v[110:113], v[74:77]
	v_mfma_f32_16x16x32_bf16 v[70:73], v[106:109], v[98:101], v[70:73]
	ds_read_b64_tr_b16 v[106:107], v1 offset:13408
	ds_read_b64_tr_b16 v[108:109], v1 offset:15968
	v_mfma_f32_16x16x32_bf16 v[78:81], v[114:117], v[98:101], v[78:81]
	s_waitcnt lgkmcnt(0)
	v_mfma_f32_16x16x32_bf16 v[62:65], v[106:109], v[98:101], v[62:65]
	ds_read_b64_tr_b16 v[98:99], v1 offset:18432
	ds_read_b64_tr_b16 v[100:101], v1 offset:20992
	s_waitcnt lgkmcnt(0)
	v_mfma_f32_16x16x32_bf16 v[142:145], v[98:101], v[102:105], v[82:85]
	s_nop 2
	ds_read_b64_tr_b16 v[82:83], v1 offset:18464
	ds_read_b64_tr_b16 v[84:85], v1 offset:21024
	s_waitcnt lgkmcnt(0)
	v_mfma_f32_16x16x32_bf16 v[150:153], v[82:85], v[102:105], v[78:81]
	s_nop 2
	ds_read_b64_tr_b16 v[78:79], v1 offset:18496
	ds_read_b64_tr_b16 v[80:81], v1 offset:21056
	s_waitcnt lgkmcnt(0)
	v_mfma_f32_16x16x32_bf16 v[158:161], v[78:81], v[102:105], v[70:73]
	s_nop 2
	ds_read_b64_tr_b16 v[70:71], v1 offset:18528
	ds_read_b64_tr_b16 v[72:73], v1 offset:21088
	v_mfma_f32_16x16x32_bf16 v[86:89], v[114:117], v[110:113], v[86:89]
	v_mfma_f32_16x16x32_bf16 v[66:69], v[106:109], v[110:113], v[66:69]
	v_mfma_f32_16x16x32_bf16 v[138:141], v[98:101], v[94:97], v[90:93]
	v_mfma_f32_16x16x32_bf16 v[146:149], v[82:85], v[94:97], v[86:89]
	v_mfma_f32_16x16x32_bf16 v[154:157], v[78:81], v[94:97], v[74:77]
	s_waitcnt lgkmcnt(0)
	v_mfma_f32_16x16x32_bf16 v[166:169], v[70:73], v[94:97], v[66:69]
	v_mfma_f32_16x16x32_bf16 v[162:165], v[70:73], v[102:105], v[62:65]

; __device__ __forceinline__ float ex2(float x) { return __builtin_amdgcn_exp2f(x); }
; __device__ __forceinline__ f32x4 mfma16(bf16x8 a, bf16x8 b, f32x4 c) { return __builtin_amdgcn_mfma_f32_16x16x32_bf16(a, b, c, 0, 0, 0); }
; __device__ __forceinline__ s16x4 ds_tr(LAS const unsigned char* p) { return __builtin_bit_cast(s16x4, __builtin_amdgcn_ds_read_tr16_b64_v4i16((LAS v4i16_t*)p)); }
; template <int NT, int NKK, int NDT, int MODE, bool MASK> ...
;     ...
;     const float mc = ((m[j] == -INFINITY) ? 0.f : m[j]) * c;
;     float p[4][4], ps = 0.f;
; #pragma unroll
;     for (int t = 0; t < 4; ++t)
; #pragma unroll
;       for (int i = 0; i < 4; ++i) { p[t][i] = ex2(s[j][t][i] * c - mc); ps += p[t][i]; }
;     l[j] += ps;
;     pf[j][0] = pack8(p[0], p[1]); pf[j][1] = pack8(p[2], p[3]);
;   }
;   __builtin_amdgcn_s_setprio(1);
; #pragma unroll
;   for (int st = 0; st < 2; ++st)
; #pragma unroll
;     for (int dt = 0; dt < NDT; ++dt) {
;       const s16x4 v0 = ds_tr(Vl + (32 * st + 4 * lg + vq) * VSTR + (16 * dt + 4 * vp) * 2);
;       const s16x4 v1 = ds_tr(Vl + (32 * st + 16 + 4 * lg + vq) * VSTR + (16 * dt + 4 * vp) * 2);
;       const bf16x8 vf = (bf16x8){v0[0], v0[1], v0[2], v0[3], v1[0], v1[1], v1[2], v1[3]};
; #pragma unroll
;       for (int j = 0; j < NT; ++j) o[j][dt] = mfma16(vf, pf[j][st], o[j][dt]);
;     }
;   __builtin_amdgcn_s_setprio(0);
.LBB0_827:
	v_cvt_pk_bf16_f32 v173, v196, v173
	v_mul_f32_e32 v196, 0x3e16c740, v197
	v_cmp_neq_f32_e32 vcc, s81, v197
	v_cvt_pk_bf16_f32 v172, v232, v228
	v_cvt_pk_bf16_f32 v228, v205, v207
	v_cndmask_b32_e32 v196, 0, v196, vcc
	v_fma_f32 v166, v166, s88, -v196
	v_exp_f32_e32 v166, v166
	v_fma_f32 v167, v167, s88, -v196
	v_exp_f32_e32 v167, v167
	v_fma_f32 v168, v168, s88, -v196
	v_exp_f32_e32 v168, v168
	v_fma_f32 v169, v169, s88, -v196
	v_exp_f32_e32 v169, v169
	v_fma_f32 v154, v154, s88, -v196
	v_exp_f32_e32 v154, v154
	v_fma_f32 v155, v155, s88, -v196
	v_add_f32_e32 v197, v167, v166
	v_exp_f32_e32 v155, v155
	v_fma_f32 v156, v156, s88, -v196
	v_add_f32_e32 v197, v168, v197
	v_exp_f32_e32 v156, v156
	v_fma_f32 v157, v157, s88, -v196
	v_add_f32_e32 v197, v169, v197
	v_exp_f32_e32 v157, v157
	v_fma_f32 v150, v150, s88, -v196
	v_add_f32_e32 v197, v154, v197
	v_exp_f32_e32 v150, v150
	v_fma_f32 v151, v151, s88, -v196
	v_add_f32_e32 v197, v155, v197
	v_exp_f32_e32 v151, v151
	v_fma_f32 v152, v152, s88, -v196
	v_add_f32_e32 v197, v156, v197
	v_exp_f32_e32 v152, v152
	v_fma_f32 v153, v153, s88, -v196
	v_add_f32_e32 v197, v157, v197
	v_exp_f32_e32 v153, v153
	v_fma_f32 v142, v142, s88, -v196
	v_add_f32_e32 v197, v150, v197
	v_exp_f32_e32 v198, v142
	v_fma_f32 v142, v143, s88, -v196
	v_add_f32_e32 v197, v151, v197
	v_exp_f32_e32 v199, v142
	v_fma_f32 v142, v144, s88, -v196
	v_add_f32_e32 v197, v152, v197
	v_exp_f32_e32 v205, v142
	v_fma_f32 v142, v145, s88, -v196
	v_add_f32_e32 v197, v153, v197
	v_exp_f32_e32 v196, v142
	v_add_f32_e32 v142, v198, v197
	v_add_f32_e32 v142, v199, v142
	v_add_f32_e32 v142, v205, v142
	v_add_f32_e32 v142, v196, v142
	v_add_f32_e32 v225, v225, v142
	v_cvt_pk_bf16_f32 v142, v166, v167
	v_cvt_pk_bf16_f32 v143, v168, v169
	v_cvt_pk_bf16_f32 v144, v154, v155
	v_cvt_pk_bf16_f32 v145, v156, v157
	v_cvt_pk_bf16_f32 v170, v252, v231
	v_cvt_pk_bf16_f32 v171, v229, v230
	v_cvt_pk_bf16_f32 v229, v246, v247
	v_cvt_pk_bf16_f32 v230, v248, v249
	v_cvt_pk_bf16_f32 v231, v250, v251
	v_cvt_pk_bf16_f32 v246, v150, v151
	v_cvt_pk_bf16_f32 v247, v152, v153
	v_cvt_pk_bf16_f32 v248, v198, v199
	v_cvt_pk_bf16_f32 v249, v205, v196
	s_setprio 1
	v_add3_u32 v196, s73, v240, v239
	ds_read_b64_tr_b16 v[152:153], v196 offset:15872
	ds_read_b64_tr_b16 v[150:151], v196 offset:13312
	ds_read_b64_tr_b16 v[154:155], v196 offset:13344
	ds_read_b64_tr_b16 v[156:157], v196 offset:15904
	ds_read_b64_tr_b16 v[166:167], v196 offset:13376
	ds_read_b64_tr_b16 v[168:169], v196 offset:15936
	s_mov_b64 s[20:21], 0
	s_waitcnt lgkmcnt(4)
	v_mfma_f32_16x16x32_bf16 v[158:161], v[150:153], v[228:231], v[90:93]
	v_mfma_f32_16x16x32_bf16 v[150:153], v[150:153], v[142:145], v[82:85]
	s_waitcnt lgkmcnt(0)
	v_mfma_f32_16x16x32_bf16 v[182:185], v[166:169], v[228:231], v[74:77]
	s_nop 2
	ds_read_b64_tr_b16 v[146:147], v196 offset:13408
	ds_read_b64_tr_b16 v[148:149], v196 offset:15968
	v_mfma_f32_16x16x32_bf16 v[162:165], v[154:157], v[228:231], v[86:89]
	v_mfma_f32_16x16x32_bf16 v[154:157], v[154:157], v[142:145], v[78:81]
	v_mfma_f32_16x16x32_bf16 v[166:169], v[166:169], v[142:145], v[70:73]
	s_waitcnt lgkmcnt(0)
	v_mfma_f32_16x16x32_bf16 v[174:177], v[146:149], v[142:145], v[62:65]
	ds_read_b64_tr_b16 v[142:143], v196 offset:18432
	ds_read_b64_tr_b16 v[144:145], v196 offset:20992
	v_mfma_f32_16x16x32_bf16 v[178:181], v[146:149], v[228:231], v[66:69]
	s_waitcnt lgkmcnt(0)
	v_mfma_f32_16x16x32_bf16 v[90:93], v[142:145], v[170:173], v[158:161]
	v_mfma_f32_16x16x32_bf16 v[82:85], v[142:145], v[246:249], v[150:153]
	s_nop 2
	ds_read_b64_tr_b16 v[150:151], v196 offset:18464
	ds_read_b64_tr_b16 v[152:153], v196 offset:21024
	ds_read_b64_tr_b16 v[158:159], v196 offset:18496
	ds_read_b64_tr_b16 v[160:161], v196 offset:21056
	s_waitcnt lgkmcnt(2)
	v_mfma_f32_16x16x32_bf16 v[86:89], v[150:153], v[170:173], v[162:165]
	s_nop 2
	ds_read_b64_tr_b16 v[162:163], v196 offset:18528
	ds_read_b64_tr_b16 v[164:165], v196 offset:21088
	v_mfma_f32_16x16x32_bf16 v[78:81], v[150:153], v[246:249], v[154:157]
	s_waitcnt lgkmcnt(2)
	v_mfma_f32_16x16x32_bf16 v[74:77], v[158:161], v[170:173], v[182:185]
	v_mfma_f32_16x16x32_bf16 v[70:73], v[158:161], v[246:249], v[166:169]
	s_waitcnt lgkmcnt(0)
	v_mfma_f32_16x16x32_bf16 v[66:69], v[162:165], v[170:173], v[178:181]
	v_mfma_f32_16x16x32_bf16 v[62:65], v[162:165], v[246:249], v[174:177]
	s_setprio 0
	s_branch .Lmla_post_1

; __device__ __forceinline__ float ex2(float x) { return __builtin_amdgcn_exp2f(x); }
; __device__ __forceinline__ f32x4 mfma16(bf16x8 a, bf16x8 b, f32x4 c) { return __builtin_amdgcn_mfma_f32_16x16x32_bf16(a, b, c, 0, 0, 0); }
; __device__ __forceinline__ s16x4 ds_tr(LAS const unsigned char* p) { return __builtin_bit_cast(s16x4, __builtin_amdgcn_ds_read_tr16_b64_v4i16((LAS v4i16_t*)p)); }
; template <int NT, int NKK, int NDT, int MODE, bool MASK> ...
;     ...
;     const float mc = ((m[j] == -INFINITY) ? 0.f : m[j]) * c;
;     float p[4][4], ps = 0.f;
; #pragma unroll
;     for (int t = 0; t < 4; ++t)
; #pragma unroll
;       for (int i = 0; i < 4; ++i) { p[t][i] = ex2(s[j][t][i] * c - mc); ps += p[t][i]; }
;     l[j] += ps;
;     pf[j][0] = pack8(p[0], p[1]); pf[j][1] = pack8(p[2], p[3]);
;   }
;   __builtin_amdgcn_s_setprio(1);
; #pragma unroll
;   for (int st = 0; st < 2; ++st)
; #pragma unroll
;     for (int dt = 0; dt < NDT; ++dt) {
;       const s16x4 v0 = ds_tr(Vl + (32 * st + 4 * lg + vq) * VSTR + (16 * dt + 4 * vp) * 2);
;       const s16x4 v1 = ds_tr(Vl + (32 * st + 16 + 4 * lg + vq) * VSTR + (16 * dt + 4 * vp) * 2);
;       const bf16x8 vf = (bf16x8){v0[0], v0[1], v0[2], v0[3], v1[0], v1[1], v1[2], v1[3]};
; #pragma unroll
;       for (int j = 0; j < NT; ++j) o[j][dt] = mfma16(vf, pf[j][st], o[j][dt]);
;     }
;   __builtin_amdgcn_s_setprio(0);
.LBB0_835:
	v_cvt_pk_bf16_f32 v110, v1, v102
	v_mul_f32_e32 v1, 0x3e16c740, v109
	v_cmp_neq_f32_e32 vcc, s81, v109
	v_cndmask_b32_e64 v116, v141, v126, s[22:23]
	v_cvt_pk_bf16_f32 v111, v103, v122
	v_cndmask_b32_e32 v1, 0, v1, vcc
	v_fma_f32 v102, v116, s88, -v1
	v_exp_f32_e32 v102, v102
	v_fma_f32 v103, v136, s88, -v1
	v_exp_f32_e32 v103, v103
	v_fma_f32 v109, v137, s88, -v1
	v_exp_f32_e32 v109, v109
	v_fma_f32 v116, v128, s88, -v1
	v_exp_f32_e32 v116, v116
	v_fma_f32 v118, v127, s88, -v1
	v_exp_f32_e32 v118, v118
	v_fma_f32 v114, v114, s88, -v1
	v_add_f32_e32 v117, v103, v102
	v_exp_f32_e32 v114, v114
	v_fma_f32 v115, v115, s88, -v1
	v_add_f32_e32 v117, v109, v117
	v_exp_f32_e32 v115, v115
	v_fma_f32 v108, v108, s88, -v1
	v_add_f32_e32 v117, v116, v117
	v_exp_f32_e32 v108, v108
	v_fma_f32 v107, v107, s88, -v1
	v_add_f32_e32 v117, v118, v117
	v_exp_f32_e32 v107, v107
	v_fma_f32 v105, v105, s88, -v1
	v_add_f32_e32 v117, v114, v117
	v_exp_f32_e32 v105, v105
	v_fma_f32 v106, v106, s88, -v1
	v_add_f32_e32 v117, v115, v117
	v_exp_f32_e32 v106, v106
	v_fma_f32 v104, v104, s88, -v1
	v_add_f32_e32 v117, v108, v117
	v_exp_f32_e32 v104, v104
	v_fma_f32 v101, v101, s88, -v1
	v_add_f32_e32 v117, v107, v117
	v_exp_f32_e32 v119, v101
	v_fma_f32 v99, v99, s88, -v1
	v_add_f32_e32 v117, v105, v117
	v_exp_f32_e32 v120, v99
	v_fma_f32 v99, v100, s88, -v1
	v_add_f32_e32 v117, v106, v117
	v_exp_f32_e32 v121, v99
	v_fma_f32 v1, v98, s88, -v1
	v_add_f32_e32 v117, v104, v117
	v_exp_f32_e32 v1, v1
	v_add_f32_e32 v98, v119, v117
	v_add_f32_e32 v98, v120, v98
	v_add_f32_e32 v98, v121, v98
	v_add_f32_e32 v98, v1, v98
	v_cvt_pk_bf16_f32 v94, v131, v132
	v_cvt_pk_bf16_f32 v95, v133, v134
	v_cvt_pk_bf16_f32 v96, v135, v138
	v_cvt_pk_bf16_f32 v97, v139, v140
	v_cvt_pk_bf16_f32 v112, v123, v124
	v_cvt_pk_bf16_f32 v113, v125, v130
	v_add_f32_e32 v219, v219, v98
	v_cvt_pk_bf16_f32 v98, v102, v103
	v_cvt_pk_bf16_f32 v99, v109, v116
	v_cvt_pk_bf16_f32 v100, v118, v114
	v_cvt_pk_bf16_f32 v101, v115, v108
	v_cvt_pk_bf16_f32 v102, v107, v105
	v_cvt_pk_bf16_f32 v103, v106, v104
	v_cvt_pk_bf16_f32 v104, v119, v120
	v_cvt_pk_bf16_f32 v105, v121, v1
	s_setprio 1
	v_add3_u32 v1, s73, v240, v239
	ds_read_b64_tr_b16 v[108:109], v1 offset:15872
	ds_read_b64_tr_b16 v[106:107], v1 offset:13312
	ds_read_b64_tr_b16 v[114:115], v1 offset:13344
	ds_read_b64_tr_b16 v[116:117], v1 offset:15904
	v_mov_b64_e32 v[224:225], v[218:219]
	v_mov_b64_e32 v[222:223], v[220:221]
	s_waitcnt lgkmcnt(2)
	v_mfma_f32_16x16x32_bf16 v[90:93], v[106:109], v[110:113], v[90:93]
	v_mfma_f32_16x16x32_bf16 v[82:85], v[106:109], v[98:101], v[82:85]
	ds_read_b64_tr_b16 v[106:107], v1 offset:13376
	ds_read_b64_tr_b16 v[108:109], v1 offset:15936
	s_waitcnt lgkmcnt(0)
	v_mfma_f32_16x16x32_bf16 v[74:77], v[106:109], v[110:113], v[74:77]
	v_mfma_f32_16x16x32_bf16 v[70:73], v[106:109], v[98:101], v[70:73]
	ds_read_b64_tr_b16 v[106:107], v1 offset:13408
	ds_read_b64_tr_b16 v[108:109], v1 offset:15968
	v_mfma_f32_16x16x32_bf16 v[78:81], v[114:117], v[98:101], v[78:81]
	s_waitcnt lgkmcnt(0)
	v_mfma_f32_16x16x32_bf16 v[62:65], v[106:109], v[98:101], v[62:65]
	ds_read_b64_tr_b16 v[98:99], v1 offset:18432
	ds_read_b64_tr_b16 v[100:101], v1 offset:20992
	s_waitcnt lgkmcnt(0)
	v_mfma_f32_16x16x32_bf16 v[142:145], v[98:101], v[102:105], v[82:85]
	s_nop 2
	ds_read_b64_tr_b16 v[82:83], v1 offset:18464
	ds_read_b64_tr_b16 v[84:85], v1 offset:21024
	s_waitcnt lgkmcnt(0)
	v_mfma_f32_16x16x32_bf16 v[150:153], v[82:85], v[102:105], v[78:81]
	s_nop 2
	ds_read_b64_tr_b16 v[78:79], v1 offset:18496
	ds_read_b64_tr_b16 v[80:81], v1 offset:21056
	s_waitcnt lgkmcnt(0)
	v_mfma_f32_16x16x32_bf16 v[158:161], v[78:81], v[102:105], v[70:73]
	s_nop 2
	ds_read_b64_tr_b16 v[70:71], v1 offset:18528
	ds_read_b64_tr_b16 v[72:73], v1 offset:21088
	v_mfma_f32_16x16x32_bf16 v[86:89], v[114:117], v[110:113], v[86:89]
	v_mfma_f32_16x16x32_bf16 v[66:69], v[106:109], v[110:113], v[66:69]
	v_mfma_f32_16x16x32_bf16 v[138:141], v[98:101], v[94:97], v[90:93]
	v_mfma_f32_16x16x32_bf16 v[146:149], v[82:85], v[94:97], v[86:89]
	v_mfma_f32_16x16x32_bf16 v[154:157], v[78:81], v[94:97], v[74:77]
	s_waitcnt lgkmcnt(0)
	v_mfma_f32_16x16x32_bf16 v[166:169], v[70:73], v[94:97], v[66:69]
	v_mfma_f32_16x16x32_bf16 v[162:165], v[70:73], v[102:105], v[62:65]

; __device__ __forceinline__ float ex2(float x) { return __builtin_amdgcn_exp2f(x); }
; __device__ __forceinline__ f32x4 mfma16(bf16x8 a, bf16x8 b, f32x4 c) { return __builtin_amdgcn_mfma_f32_16x16x32_bf16(a, b, c, 0, 0, 0); }
; __device__ __forceinline__ s16x4 ds_tr(LAS const unsigned char* p) { return __builtin_bit_cast(s16x4, __builtin_amdgcn_ds_read_tr16_b64_v4i16((LAS v4i16_t*)p)); }
; template <int NT, int NKK, int NDT, int MODE, bool MASK> ...
;     ...
;     const float mc = ((m[j] == -INFINITY) ? 0.f : m[j]) * c;
;     float p[4][4], ps = 0.f;
; #pragma unroll
;     for (int t = 0; t < 4; ++t)
; #pragma unroll
;       for (int i = 0; i < 4; ++i) { p[t][i] = ex2(s[j][t][i] * c - mc); ps += p[t][i]; }
;     l[j] += ps;
;     pf[j][0] = pack8(p[0], p[1]); pf[j][1] = pack8(p[2], p[3]);
;   }
;   __builtin_amdgcn_s_setprio(1);
; #pragma unroll
;   for (int st = 0; st < 2; ++st)
; #pragma unroll
;     for (int dt = 0; dt < NDT; ++dt) {
;       const s16x4 v0 = ds_tr(Vl + (32 * st + 4 * lg + vq) * VSTR + (16 * dt + 4 * vp) * 2);
;       const s16x4 v1 = ds_tr(Vl + (32 * st + 16 + 4 * lg + vq) * VSTR + (16 * dt + 4 * vp) * 2);
;       const bf16x8 vf = (bf16x8){v0[0], v0[1], v0[2], v0[3], v1[0], v1[1], v1[2], v1[3]};
; #pragma unroll
;       for (int j = 0; j < NT; ++j) o[j][dt] = mfma16(vf, pf[j][st], o[j][dt]);
;     }
;   __builtin_amdgcn_s_setprio(0);
.LBB0_960:
	v_cvt_pk_bf16_f32 v173, v196, v173
	v_mul_f32_e32 v196, 0x3e16c740, v197
	v_cmp_neq_f32_e32 vcc, s81, v197
	v_cvt_pk_bf16_f32 v172, v232, v228
	v_cvt_pk_bf16_f32 v228, v205, v207
	v_cndmask_b32_e32 v196, 0, v196, vcc
	v_fma_f32 v166, v166, s88, -v196
	v_exp_f32_e32 v166, v166
	v_fma_f32 v167, v167, s88, -v196
	v_exp_f32_e32 v167, v167
	v_fma_f32 v168, v168, s88, -v196
	v_exp_f32_e32 v168, v168
	v_fma_f32 v169, v169, s88, -v196
	v_exp_f32_e32 v169, v169
	v_fma_f32 v154, v154, s88, -v196
	v_exp_f32_e32 v154, v154
	v_fma_f32 v155, v155, s88, -v196
	v_add_f32_e32 v197, v167, v166
	v_exp_f32_e32 v155, v155
	v_fma_f32 v156, v156, s88, -v196
	v_add_f32_e32 v197, v168, v197
	v_exp_f32_e32 v156, v156
	v_fma_f32 v157, v157, s88, -v196
	v_add_f32_e32 v197, v169, v197
	v_exp_f32_e32 v157, v157
	v_fma_f32 v150, v150, s88, -v196
	v_add_f32_e32 v197, v154, v197
	v_exp_f32_e32 v150, v150
	v_fma_f32 v151, v151, s88, -v196
	v_add_f32_e32 v197, v155, v197
	v_exp_f32_e32 v151, v151
	v_fma_f32 v152, v152, s88, -v196
	v_add_f32_e32 v197, v156, v197
	v_exp_f32_e32 v152, v152
	v_fma_f32 v153, v153, s88, -v196
	v_add_f32_e32 v197, v157, v197
	v_exp_f32_e32 v153, v153
	v_fma_f32 v142, v142, s88, -v196
	v_add_f32_e32 v197, v150, v197
	v_exp_f32_e32 v198, v142
	v_fma_f32 v142, v143, s88, -v196
	v_add_f32_e32 v197, v151, v197
	v_exp_f32_e32 v199, v142
	v_fma_f32 v142, v144, s88, -v196
	v_add_f32_e32 v197, v152, v197
	v_exp_f32_e32 v205, v142
	v_fma_f32 v142, v145, s88, -v196
	v_add_f32_e32 v197, v153, v197
	v_exp_f32_e32 v196, v142
	v_add_f32_e32 v142, v198, v197
	v_add_f32_e32 v142, v199, v142
	v_add_f32_e32 v142, v205, v142
	v_add_f32_e32 v142, v196, v142
	v_add_f32_e32 v225, v225, v142
	v_cvt_pk_bf16_f32 v142, v166, v167
	v_cvt_pk_bf16_f32 v143, v168, v169
	v_cvt_pk_bf16_f32 v144, v154, v155
	v_cvt_pk_bf16_f32 v145, v156, v157
	v_cvt_pk_bf16_f32 v170, v252, v231
	v_cvt_pk_bf16_f32 v171, v229, v230
	v_cvt_pk_bf16_f32 v229, v246, v247
	v_cvt_pk_bf16_f32 v230, v248, v249
	v_cvt_pk_bf16_f32 v231, v250, v251
	v_cvt_pk_bf16_f32 v246, v150, v151
	v_cvt_pk_bf16_f32 v247, v152, v153
	v_cvt_pk_bf16_f32 v248, v198, v199
	v_cvt_pk_bf16_f32 v249, v205, v196
	s_setprio 1
	v_add3_u32 v196, s45, v240, v239
	ds_read_b64_tr_b16 v[152:153], v196 offset:15872
	ds_read_b64_tr_b16 v[150:151], v196 offset:13312
	ds_read_b64_tr_b16 v[154:155], v196 offset:13344
	ds_read_b64_tr_b16 v[156:157], v196 offset:15904
	ds_read_b64_tr_b16 v[166:167], v196 offset:13376
	ds_read_b64_tr_b16 v[168:169], v196 offset:15936
	s_mov_b64 s[20:21], 0
	s_waitcnt lgkmcnt(4)
	v_mfma_f32_16x16x32_bf16 v[158:161], v[150:153], v[228:231], v[90:93]
	v_mfma_f32_16x16x32_bf16 v[150:153], v[150:153], v[142:145], v[82:85]
	s_waitcnt lgkmcnt(0)
	v_mfma_f32_16x16x32_bf16 v[182:185], v[166:169], v[228:231], v[74:77]
	s_nop 2
	ds_read_b64_tr_b16 v[146:147], v196 offset:13408
	ds_read_b64_tr_b16 v[148:149], v196 offset:15968
	v_mfma_f32_16x16x32_bf16 v[162:165], v[154:157], v[228:231], v[86:89]
	v_mfma_f32_16x16x32_bf16 v[154:157], v[154:157], v[142:145], v[78:81]
	v_mfma_f32_16x16x32_bf16 v[166:169], v[166:169], v[142:145], v[70:73]
	s_waitcnt lgkmcnt(0)
	v_mfma_f32_16x16x32_bf16 v[174:177], v[146:149], v[142:145], v[62:65]
	ds_read_b64_tr_b16 v[142:143], v196 offset:18432
	ds_read_b64_tr_b16 v[144:145], v196 offset:20992
	v_mfma_f32_16x16x32_bf16 v[178:181], v[146:149], v[228:231], v[66:69]
	s_waitcnt lgkmcnt(0)
	v_mfma_f32_16x16x32_bf16 v[90:93], v[142:145], v[170:173], v[158:161]
	v_mfma_f32_16x16x32_bf16 v[82:85], v[142:145], v[246:249], v[150:153]
	s_nop 2
	ds_read_b64_tr_b16 v[150:151], v196 offset:18464
	ds_read_b64_tr_b16 v[152:153], v196 offset:21024
	ds_read_b64_tr_b16 v[158:159], v196 offset:18496
	ds_read_b64_tr_b16 v[160:161], v196 offset:21056
	s_waitcnt lgkmcnt(2)
	v_mfma_f32_16x16x32_bf16 v[86:89], v[150:153], v[170:173], v[162:165]
	s_nop 2
	ds_read_b64_tr_b16 v[162:163], v196 offset:18528
	ds_read_b64_tr_b16 v[164:165], v196 offset:21088
	v_mfma_f32_16x16x32_bf16 v[78:81], v[150:153], v[246:249], v[154:157]
	s_waitcnt lgkmcnt(2)
	v_mfma_f32_16x16x32_bf16 v[74:77], v[158:161], v[170:173], v[182:185]
	v_mfma_f32_16x16x32_bf16 v[70:73], v[158:161], v[246:249], v[166:169]
	s_waitcnt lgkmcnt(0)
	v_mfma_f32_16x16x32_bf16 v[66:69], v[162:165], v[170:173], v[178:181]
	v_mfma_f32_16x16x32_bf16 v[62:65], v[162:165], v[246:249], v[174:177]
	s_setprio 0
	s_branch .Lmla_post_3

; __device__ __forceinline__ float ex2(float x) { return __builtin_amdgcn_exp2f(x); }
; __device__ __forceinline__ f32x4 mfma16(bf16x8 a, bf16x8 b, f32x4 c) { return __builtin_amdgcn_mfma_f32_16x16x32_bf16(a, b, c, 0, 0, 0); }
; __device__ __forceinline__ s16x4 ds_tr(LAS const unsigned char* p) { return __builtin_bit_cast(s16x4, __builtin_amdgcn_ds_read_tr16_b64_v4i16((LAS v4i16_t*)p)); }
; template <int NT, int NKK, int NDT, int MODE, bool MASK> ...
;     ...
;     const float mc = ((m[j] == -INFINITY) ? 0.f : m[j]) * c;
;     float p[4][4], ps = 0.f;
; #pragma unroll
;     for (int t = 0; t < 4; ++t)
; #pragma unroll
;       for (int i = 0; i < 4; ++i) { p[t][i] = ex2(s[j][t][i] * c - mc); ps += p[t][i]; }
;     l[j] += ps;
;     pf[j][0] = pack8(p[0], p[1]); pf[j][1] = pack8(p[2], p[3]);
;   }
;   __builtin_amdgcn_s_setprio(1);
; #pragma unroll
;   for (int st = 0; st < 2; ++st)
; #pragma unroll
;     for (int dt = 0; dt < NDT; ++dt) {
;       const s16x4 v0 = ds_tr(Vl + (32 * st + 4 * lg + vq) * VSTR + (16 * dt + 4 * vp) * 2);
;       const s16x4 v1 = ds_tr(Vl + (32 * st + 16 + 4 * lg + vq) * VSTR + (16 * dt + 4 * vp) * 2);
;       const bf16x8 vf = (bf16x8){v0[0], v0[1], v0[2], v0[3], v1[0], v1[1], v1[2], v1[3]};
; #pragma unroll
;       for (int j = 0; j < NT; ++j) o[j][dt] = mfma16(vf, pf[j][st], o[j][dt]);
;     }
;   __builtin_amdgcn_s_setprio(0);
.LBB0_968:
	v_cvt_pk_bf16_f32 v110, v1, v102
	v_mul_f32_e32 v1, 0x3e16c740, v109
	v_cmp_neq_f32_e32 vcc, s81, v109
	v_cndmask_b32_e64 v116, v141, v126, s[22:23]
	v_cvt_pk_bf16_f32 v111, v103, v122
	v_cndmask_b32_e32 v1, 0, v1, vcc
	v_fma_f32 v102, v116, s88, -v1
	v_exp_f32_e32 v102, v102
	v_fma_f32 v103, v136, s88, -v1
	v_exp_f32_e32 v103, v103
	v_fma_f32 v109, v137, s88, -v1
	v_exp_f32_e32 v109, v109
	v_fma_f32 v116, v128, s88, -v1
	v_exp_f32_e32 v116, v116
	v_fma_f32 v118, v127, s88, -v1
	v_exp_f32_e32 v118, v118
	v_fma_f32 v114, v114, s88, -v1
	v_add_f32_e32 v117, v103, v102
	v_exp_f32_e32 v114, v114
	v_fma_f32 v115, v115, s88, -v1
	v_add_f32_e32 v117, v109, v117
	v_exp_f32_e32 v115, v115
	v_fma_f32 v108, v108, s88, -v1
	v_add_f32_e32 v117, v116, v117
	v_exp_f32_e32 v108, v108
	v_fma_f32 v107, v107, s88, -v1
	v_add_f32_e32 v117, v118, v117
	v_exp_f32_e32 v107, v107
	v_fma_f32 v105, v105, s88, -v1
	v_add_f32_e32 v117, v114, v117
	v_exp_f32_e32 v105, v105
	v_fma_f32 v106, v106, s88, -v1
	v_add_f32_e32 v117, v115, v117
	v_exp_f32_e32 v106, v106
	v_fma_f32 v104, v104, s88, -v1
	v_add_f32_e32 v117, v108, v117
	v_exp_f32_e32 v104, v104
	v_fma_f32 v101, v101, s88, -v1
	v_add_f32_e32 v117, v107, v117
	v_exp_f32_e32 v119, v101
	v_fma_f32 v99, v99, s88, -v1
	v_add_f32_e32 v117, v105, v117
	v_exp_f32_e32 v120, v99
	v_fma_f32 v99, v100, s88, -v1
	v_add_f32_e32 v117, v106, v117
	v_exp_f32_e32 v121, v99
	v_fma_f32 v1, v98, s88, -v1
	v_add_f32_e32 v117, v104, v117
	v_exp_f32_e32 v1, v1
	v_add_f32_e32 v98, v119, v117
	v_add_f32_e32 v98, v120, v98
	v_add_f32_e32 v98, v121, v98
	v_add_f32_e32 v98, v1, v98
	v_cvt_pk_bf16_f32 v94, v131, v132
	v_cvt_pk_bf16_f32 v95, v133, v134
	v_cvt_pk_bf16_f32 v96, v135, v138
	v_cvt_pk_bf16_f32 v97, v139, v140
	v_cvt_pk_bf16_f32 v112, v123, v124
	v_cvt_pk_bf16_f32 v113, v125, v130
	v_add_f32_e32 v219, v219, v98
	v_cvt_pk_bf16_f32 v98, v102, v103
	v_cvt_pk_bf16_f32 v99, v109, v116
	v_cvt_pk_bf16_f32 v100, v118, v114
	v_cvt_pk_bf16_f32 v101, v115, v108
	v_cvt_pk_bf16_f32 v102, v107, v105
	v_cvt_pk_bf16_f32 v103, v106, v104
	v_cvt_pk_bf16_f32 v104, v119, v120
	v_cvt_pk_bf16_f32 v105, v121, v1
	s_setprio 1
	v_add3_u32 v1, s45, v240, v239
	ds_read_b64_tr_b16 v[108:109], v1 offset:15872
	ds_read_b64_tr_b16 v[106:107], v1 offset:13312
	ds_read_b64_tr_b16 v[114:115], v1 offset:13344
	ds_read_b64_tr_b16 v[116:117], v1 offset:15904
	v_mov_b64_e32 v[224:225], v[218:219]
	v_mov_b64_e32 v[222:223], v[220:221]
	s_waitcnt lgkmcnt(2)
	v_mfma_f32_16x16x32_bf16 v[90:93], v[106:109], v[110:113], v[90:93]
	v_mfma_f32_16x16x32_bf16 v[82:85], v[106:109], v[98:101], v[82:85]
	ds_read_b64_tr_b16 v[106:107], v1 offset:13376
	ds_read_b64_tr_b16 v[108:109], v1 offset:15936
	s_waitcnt lgkmcnt(0)
	v_mfma_f32_16x16x32_bf16 v[74:77], v[106:109], v[110:113], v[74:77]
	v_mfma_f32_16x16x32_bf16 v[70:73], v[106:109], v[98:101], v[70:73]
	ds_read_b64_tr_b16 v[106:107], v1 offset:13408
	ds_read_b64_tr_b16 v[108:109], v1 offset:15968
	v_mfma_f32_16x16x32_bf16 v[78:81], v[114:117], v[98:101], v[78:81]
	s_waitcnt lgkmcnt(0)
	v_mfma_f32_16x16x32_bf16 v[62:65], v[106:109], v[98:101], v[62:65]
	ds_read_b64_tr_b16 v[98:99], v1 offset:18432
	ds_read_b64_tr_b16 v[100:101], v1 offset:20992
	s_waitcnt lgkmcnt(0)
	v_mfma_f32_16x16x32_bf16 v[142:145], v[98:101], v[102:105], v[82:85]
	s_nop 2
	ds_read_b64_tr_b16 v[82:83], v1 offset:18464
	ds_read_b64_tr_b16 v[84:85], v1 offset:21024
	s_waitcnt lgkmcnt(0)
	v_mfma_f32_16x16x32_bf16 v[150:153], v[82:85], v[102:105], v[78:81]
	s_nop 2
	ds_read_b64_tr_b16 v[78:79], v1 offset:18496
	ds_read_b64_tr_b16 v[80:81], v1 offset:21056
	s_waitcnt lgkmcnt(0)
	v_mfma_f32_16x16x32_bf16 v[158:161], v[78:81], v[102:105], v[70:73]
	s_nop 2
	ds_read_b64_tr_b16 v[70:71], v1 offset:18528
	ds_read_b64_tr_b16 v[72:73], v1 offset:21088
	v_mfma_f32_16x16x32_bf16 v[86:89], v[114:117], v[110:113], v[86:89]
	v_mfma_f32_16x16x32_bf16 v[66:69], v[106:109], v[110:113], v[66:69]
	v_mfma_f32_16x16x32_bf16 v[138:141], v[98:101], v[94:97], v[90:93]
	v_mfma_f32_16x16x32_bf16 v[146:149], v[82:85], v[94:97], v[86:89]
	v_mfma_f32_16x16x32_bf16 v[154:157], v[78:81], v[94:97], v[74:77]
	s_waitcnt lgkmcnt(0)
	v_mfma_f32_16x16x32_bf16 v[166:169], v[70:73], v[94:97], v[66:69]
	v_mfma_f32_16x16x32_bf16 v[162:165], v[70:73], v[102:105], v[62:65]

; __device__ __forceinline__ float ex2(float x) { return __builtin_amdgcn_exp2f(x); }
; __device__ __forceinline__ f32x4 mfma16(bf16x8 a, bf16x8 b, f32x4 c) { return __builtin_amdgcn_mfma_f32_16x16x32_bf16(a, b, c, 0, 0, 0); }
; __device__ __forceinline__ s16x4 ds_tr(LAS const unsigned char* p) { return __builtin_bit_cast(s16x4, __builtin_amdgcn_ds_read_tr16_b64_v4i16((LAS v4i16_t*)p)); }
; template <int NT, int NKK, int NDT, int MODE, bool MASK> ...
;     ...
;     const float mc = ((m[j] == -INFINITY) ? 0.f : m[j]) * c;
;     float p[4][4], ps = 0.f;
; #pragma unroll
;     for (int t = 0; t < 4; ++t)
; #pragma unroll
;       for (int i = 0; i < 4; ++i) { p[t][i] = ex2(s[j][t][i] * c - mc); ps += p[t][i]; }
;     l[j] += ps;
;     pf[j][0] = pack8(p[0], p[1]); pf[j][1] = pack8(p[2], p[3]);
;   }
;   __builtin_amdgcn_s_setprio(1);
; #pragma unroll
;   for (int st = 0; st < 2; ++st)
; #pragma unroll
;     for (int dt = 0; dt < NDT; ++dt) {
;       const s16x4 v0 = ds_tr(Vl + (32 * st + 4 * lg + vq) * VSTR + (16 * dt + 4 * vp) * 2);
;       const s16x4 v1 = ds_tr(Vl + (32 * st + 16 + 4 * lg + vq) * VSTR + (16 * dt + 4 * vp) * 2);
;       const bf16x8 vf = (bf16x8){v0[0], v0[1], v0[2], v0[3], v1[0], v1[1], v1[2], v1[3]};
; #pragma unroll
;       for (int j = 0; j < NT; ++j) o[j][dt] = mfma16(vf, pf[j][st], o[j][dt]);
;     }
;   __builtin_amdgcn_s_setprio(0);
.LBB0_1000:
	v_cvt_pk_bf16_f32 v173, v196, v173
	v_mul_f32_e32 v196, 0x3e16c740, v197
	v_cmp_neq_f32_e32 vcc, s81, v197
	v_cvt_pk_bf16_f32 v172, v232, v228
	v_cvt_pk_bf16_f32 v228, v205, v207
	v_cndmask_b32_e32 v196, 0, v196, vcc
	v_fma_f32 v166, v166, s88, -v196
	v_exp_f32_e32 v166, v166
	v_fma_f32 v167, v167, s88, -v196
	v_exp_f32_e32 v167, v167
	v_fma_f32 v168, v168, s88, -v196
	v_exp_f32_e32 v168, v168
	v_fma_f32 v169, v169, s88, -v196
	v_exp_f32_e32 v169, v169
	v_fma_f32 v154, v154, s88, -v196
	v_exp_f32_e32 v154, v154
	v_fma_f32 v155, v155, s88, -v196
	v_add_f32_e32 v197, v167, v166
	v_exp_f32_e32 v155, v155
	v_fma_f32 v156, v156, s88, -v196
	v_add_f32_e32 v197, v168, v197
	v_exp_f32_e32 v156, v156
	v_fma_f32 v157, v157, s88, -v196
	v_add_f32_e32 v197, v169, v197
	v_exp_f32_e32 v157, v157
	v_fma_f32 v150, v150, s88, -v196
	v_add_f32_e32 v197, v154, v197
	v_exp_f32_e32 v150, v150
	v_fma_f32 v151, v151, s88, -v196
	v_add_f32_e32 v197, v155, v197
	v_exp_f32_e32 v151, v151
	v_fma_f32 v152, v152, s88, -v196
	v_add_f32_e32 v197, v156, v197
	v_exp_f32_e32 v152, v152
	v_fma_f32 v153, v153, s88, -v196
	v_add_f32_e32 v197, v157, v197
	v_exp_f32_e32 v153, v153
	v_fma_f32 v142, v142, s88, -v196
	v_add_f32_e32 v197, v150, v197
	v_exp_f32_e32 v198, v142
	v_fma_f32 v142, v143, s88, -v196
	v_add_f32_e32 v197, v151, v197
	v_exp_f32_e32 v199, v142
	v_fma_f32 v142, v144, s88, -v196
	v_add_f32_e32 v197, v152, v197
	v_exp_f32_e32 v205, v142
	v_fma_f32 v142, v145, s88, -v196
	v_add_f32_e32 v197, v153, v197
	v_exp_f32_e32 v196, v142
	v_add_f32_e32 v142, v198, v197
	v_add_f32_e32 v142, v199, v142
	v_add_f32_e32 v142, v205, v142
	v_add_f32_e32 v142, v196, v142
	v_add_f32_e32 v225, v225, v142
	v_cvt_pk_bf16_f32 v142, v166, v167
	v_cvt_pk_bf16_f32 v143, v168, v169
	v_cvt_pk_bf16_f32 v144, v154, v155
	v_cvt_pk_bf16_f32 v145, v156, v157
	v_cvt_pk_bf16_f32 v170, v252, v231
	v_cvt_pk_bf16_f32 v171, v229, v230
	v_cvt_pk_bf16_f32 v229, v246, v247
	v_cvt_pk_bf16_f32 v230, v248, v249
	v_cvt_pk_bf16_f32 v231, v250, v251
	v_cvt_pk_bf16_f32 v246, v150, v151
	v_cvt_pk_bf16_f32 v247, v152, v153
	v_cvt_pk_bf16_f32 v248, v198, v199
	v_cvt_pk_bf16_f32 v249, v205, v196
	s_setprio 1
	v_add3_u32 v196, s59, v240, v239
	ds_read_b64_tr_b16 v[152:153], v196 offset:15872
	ds_read_b64_tr_b16 v[150:151], v196 offset:13312
	ds_read_b64_tr_b16 v[154:155], v196 offset:13344
	ds_read_b64_tr_b16 v[156:157], v196 offset:15904
	ds_read_b64_tr_b16 v[166:167], v196 offset:13376
	ds_read_b64_tr_b16 v[168:169], v196 offset:15936
	s_mov_b64 s[20:21], 0
	s_waitcnt lgkmcnt(4)
	v_mfma_f32_16x16x32_bf16 v[158:161], v[150:153], v[228:231], v[90:93]
	v_mfma_f32_16x16x32_bf16 v[150:153], v[150:153], v[142:145], v[82:85]
	s_waitcnt lgkmcnt(0)
	v_mfma_f32_16x16x32_bf16 v[182:185], v[166:169], v[228:231], v[74:77]
	s_nop 2
	ds_read_b64_tr_b16 v[146:147], v196 offset:13408
	ds_read_b64_tr_b16 v[148:149], v196 offset:15968
	v_mfma_f32_16x16x32_bf16 v[162:165], v[154:157], v[228:231], v[86:89]
	v_mfma_f32_16x16x32_bf16 v[154:157], v[154:157], v[142:145], v[78:81]
	v_mfma_f32_16x16x32_bf16 v[166:169], v[166:169], v[142:145], v[70:73]
	s_waitcnt lgkmcnt(0)
	v_mfma_f32_16x16x32_bf16 v[174:177], v[146:149], v[142:145], v[62:65]
	ds_read_b64_tr_b16 v[142:143], v196 offset:18432
	ds_read_b64_tr_b16 v[144:145], v196 offset:20992
	v_mfma_f32_16x16x32_bf16 v[178:181], v[146:149], v[228:231], v[66:69]
	s_waitcnt lgkmcnt(0)
	v_mfma_f32_16x16x32_bf16 v[90:93], v[142:145], v[170:173], v[158:161]
	v_mfma_f32_16x16x32_bf16 v[82:85], v[142:145], v[246:249], v[150:153]
	s_nop 2
	ds_read_b64_tr_b16 v[150:151], v196 offset:18464
	ds_read_b64_tr_b16 v[152:153], v196 offset:21024
	ds_read_b64_tr_b16 v[158:159], v196 offset:18496
	ds_read_b64_tr_b16 v[160:161], v196 offset:21056
	s_waitcnt lgkmcnt(2)
	v_mfma_f32_16x16x32_bf16 v[86:89], v[150:153], v[170:173], v[162:165]
	s_nop 2
	ds_read_b64_tr_b16 v[162:163], v196 offset:18528
	ds_read_b64_tr_b16 v[164:165], v196 offset:21088
	v_mfma_f32_16x16x32_bf16 v[78:81], v[150:153], v[246:249], v[154:157]
	s_waitcnt lgkmcnt(2)
	v_mfma_f32_16x16x32_bf16 v[74:77], v[158:161], v[170:173], v[182:185]
	v_mfma_f32_16x16x32_bf16 v[70:73], v[158:161], v[246:249], v[166:169]
	s_waitcnt lgkmcnt(0)
	v_mfma_f32_16x16x32_bf16 v[66:69], v[162:165], v[170:173], v[178:181]
	v_mfma_f32_16x16x32_bf16 v[62:65], v[162:165], v[246:249], v[174:177]
	s_setprio 0
	s_branch .Lmla_post_4

; __device__ __forceinline__ float ex2(float x) { return __builtin_amdgcn_exp2f(x); }
; __device__ __forceinline__ f32x4 mfma16(bf16x8 a, bf16x8 b, f32x4 c) { return __builtin_amdgcn_mfma_f32_16x16x32_bf16(a, b, c, 0, 0, 0); }
; __device__ __forceinline__ s16x4 ds_tr(LAS const unsigned char* p) { return __builtin_bit_cast(s16x4, __builtin_amdgcn_ds_read_tr16_b64_v4i16((LAS v4i16_t*)p)); }
; template <int NT, int NKK, int NDT, int MODE, bool MASK> ...
;     ...
;     const float mc = ((m[j] == -INFINITY) ? 0.f : m[j]) * c;
;     float p[4][4], ps = 0.f;
; #pragma unroll
;     for (int t = 0; t < 4; ++t)
; #pragma unroll
;       for (int i = 0; i < 4; ++i) { p[t][i] = ex2(s[j][t][i] * c - mc); ps += p[t][i]; }
;     l[j] += ps;
;     pf[j][0] = pack8(p[0], p[1]); pf[j][1] = pack8(p[2], p[3]);
;   }
;   __builtin_amdgcn_s_setprio(1);
; #pragma unroll
;   for (int st = 0; st < 2; ++st)
; #pragma unroll
;     for (int dt = 0; dt < NDT; ++dt) {
;       const s16x4 v0 = ds_tr(Vl + (32 * st + 4 * lg + vq) * VSTR + (16 * dt + 4 * vp) * 2);
;       const s16x4 v1 = ds_tr(Vl + (32 * st + 16 + 4 * lg + vq) * VSTR + (16 * dt + 4 * vp) * 2);
;       const bf16x8 vf = (bf16x8){v0[0], v0[1], v0[2], v0[3], v1[0], v1[1], v1[2], v1[3]};
; #pragma unroll
;       for (int j = 0; j < NT; ++j) o[j][dt] = mfma16(vf, pf[j][st], o[j][dt]);
;     }
;   __builtin_amdgcn_s_setprio(0);
.LBB0_1008:
	v_cvt_pk_bf16_f32 v110, v1, v102
	v_mul_f32_e32 v1, 0x3e16c740, v109
	v_cmp_neq_f32_e32 vcc, s81, v109
	v_cndmask_b32_e64 v116, v141, v126, s[22:23]
	v_cvt_pk_bf16_f32 v111, v103, v122
	v_cndmask_b32_e32 v1, 0, v1, vcc
	v_fma_f32 v102, v116, s88, -v1
	v_exp_f32_e32 v102, v102
	v_fma_f32 v103, v136, s88, -v1
	v_exp_f32_e32 v103, v103
	v_fma_f32 v109, v137, s88, -v1
	v_exp_f32_e32 v109, v109
	v_fma_f32 v116, v128, s88, -v1
	v_exp_f32_e32 v116, v116
	v_fma_f32 v118, v127, s88, -v1
	v_exp_f32_e32 v118, v118
	v_fma_f32 v114, v114, s88, -v1
	v_add_f32_e32 v117, v103, v102
	v_exp_f32_e32 v114, v114
	v_fma_f32 v115, v115, s88, -v1
	v_add_f32_e32 v117, v109, v117
	v_exp_f32_e32 v115, v115
	v_fma_f32 v108, v108, s88, -v1
	v_add_f32_e32 v117, v116, v117
	v_exp_f32_e32 v108, v108
	v_fma_f32 v107, v107, s88, -v1
	v_add_f32_e32 v117, v118, v117
	v_exp_f32_e32 v107, v107
	v_fma_f32 v105, v105, s88, -v1
	v_add_f32_e32 v117, v114, v117
	v_exp_f32_e32 v105, v105
	v_fma_f32 v106, v106, s88, -v1
	v_add_f32_e32 v117, v115, v117
	v_exp_f32_e32 v106, v106
	v_fma_f32 v104, v104, s88, -v1
	v_add_f32_e32 v117, v108, v117
	v_exp_f32_e32 v104, v104
	v_fma_f32 v101, v101, s88, -v1
	v_add_f32_e32 v117, v107, v117
	v_exp_f32_e32 v119, v101
	v_fma_f32 v99, v99, s88, -v1
	v_add_f32_e32 v117, v105, v117
	v_exp_f32_e32 v120, v99
	v_fma_f32 v99, v100, s88, -v1
	v_add_f32_e32 v117, v106, v117
	v_exp_f32_e32 v121, v99
	v_fma_f32 v1, v98, s88, -v1
	v_add_f32_e32 v117, v104, v117
	v_exp_f32_e32 v1, v1
	v_add_f32_e32 v98, v119, v117
	v_add_f32_e32 v98, v120, v98
	v_add_f32_e32 v98, v121, v98
	v_add_f32_e32 v98, v1, v98
	v_cvt_pk_bf16_f32 v94, v131, v132
	v_cvt_pk_bf16_f32 v95, v133, v134
	v_cvt_pk_bf16_f32 v96, v135, v138
	v_cvt_pk_bf16_f32 v97, v139, v140
	v_cvt_pk_bf16_f32 v112, v123, v124
	v_cvt_pk_bf16_f32 v113, v125, v130
	v_add_f32_e32 v219, v219, v98
	v_cvt_pk_bf16_f32 v98, v102, v103
	v_cvt_pk_bf16_f32 v99, v109, v116
	v_cvt_pk_bf16_f32 v100, v118, v114
	v_cvt_pk_bf16_f32 v101, v115, v108
	v_cvt_pk_bf16_f32 v102, v107, v105
	v_cvt_pk_bf16_f32 v103, v106, v104
	v_cvt_pk_bf16_f32 v104, v119, v120
	v_cvt_pk_bf16_f32 v105, v121, v1
	s_setprio 1
	v_add3_u32 v1, s59, v240, v239
	ds_read_b64_tr_b16 v[108:109], v1 offset:15872
	ds_read_b64_tr_b16 v[106:107], v1 offset:13312
	ds_read_b64_tr_b16 v[114:115], v1 offset:13344
	ds_read_b64_tr_b16 v[116:117], v1 offset:15904
	v_mov_b64_e32 v[224:225], v[218:219]
	v_mov_b64_e32 v[222:223], v[220:221]
	s_waitcnt lgkmcnt(2)
	v_mfma_f32_16x16x32_bf16 v[90:93], v[106:109], v[110:113], v[90:93]
	v_mfma_f32_16x16x32_bf16 v[82:85], v[106:109], v[98:101], v[82:85]
	ds_read_b64_tr_b16 v[106:107], v1 offset:13376
	ds_read_b64_tr_b16 v[108:109], v1 offset:15936
	s_waitcnt lgkmcnt(0)
	v_mfma_f32_16x16x32_bf16 v[74:77], v[106:109], v[110:113], v[74:77]
	v_mfma_f32_16x16x32_bf16 v[70:73], v[106:109], v[98:101], v[70:73]
	ds_read_b64_tr_b16 v[106:107], v1 offset:13408
	ds_read_b64_tr_b16 v[108:109], v1 offset:15968
	v_mfma_f32_16x16x32_bf16 v[78:81], v[114:117], v[98:101], v[78:81]
	s_waitcnt lgkmcnt(0)
	v_mfma_f32_16x16x32_bf16 v[62:65], v[106:109], v[98:101], v[62:65]
	ds_read_b64_tr_b16 v[98:99], v1 offset:18432
	ds_read_b64_tr_b16 v[100:101], v1 offset:20992
	s_waitcnt lgkmcnt(0)
	v_mfma_f32_16x16x32_bf16 v[142:145], v[98:101], v[102:105], v[82:85]
	s_nop 2
	ds_read_b64_tr_b16 v[82:83], v1 offset:18464
	ds_read_b64_tr_b16 v[84:85], v1 offset:21024
	s_waitcnt lgkmcnt(0)
	v_mfma_f32_16x16x32_bf16 v[150:153], v[82:85], v[102:105], v[78:81]
	s_nop 2
	ds_read_b64_tr_b16 v[78:79], v1 offset:18496
	ds_read_b64_tr_b16 v[80:81], v1 offset:21056
	s_waitcnt lgkmcnt(0)
	v_mfma_f32_16x16x32_bf16 v[158:161], v[78:81], v[102:105], v[70:73]
	s_nop 2
	ds_read_b64_tr_b16 v[70:71], v1 offset:18528
	ds_read_b64_tr_b16 v[72:73], v1 offset:21088
	v_mfma_f32_16x16x32_bf16 v[86:89], v[114:117], v[110:113], v[86:89]
	v_mfma_f32_16x16x32_bf16 v[66:69], v[106:109], v[110:113], v[66:69]
	v_mfma_f32_16x16x32_bf16 v[138:141], v[98:101], v[94:97], v[90:93]
	v_mfma_f32_16x16x32_bf16 v[146:149], v[82:85], v[94:97], v[86:89]
	v_mfma_f32_16x16x32_bf16 v[154:157], v[78:81], v[94:97], v[74:77]
	s_waitcnt lgkmcnt(0)
	v_mfma_f32_16x16x32_bf16 v[166:169], v[70:73], v[94:97], v[66:69]
	v_mfma_f32_16x16x32_bf16 v[162:165], v[70:73], v[102:105], v[62:65]

; template <int NT, int NKK, int NDT, int MODE, bool MASK> ...
;     ...
;     for (int jh = 0; jh < NT / JB; ++jh) {
;       int oz = 0; if (NT > JB) asm volatile("" : "+v"(oz));
;       f32x4 s[JB][2];
;       __builtin_amdgcn_s_setprio(1);
; #pragma unroll
;       for (int t = 0; t < 2; ++t)
; #pragma unroll
;         for (int kk = 0; kk < NKK; ++kk) {
;           const bf16x8 kf = *(LAS const bf16x8*)(Kl + oz + (32 * st + 16 * t + r) * KSTR + (32 * kk + 8 * lg) * 2);
; #pragma unroll
;           for (int jj = 0; jj < JB; ++jj) s[jj][t] = mfma16(kf, qf[jh * JB + jj][kk], kk == 0 ? (f32x4){0.f, 0.f, 0.f, 0.f} : s[jj][t]);
;         }
;       __builtin_amdgcn_s_setprio(0);
;       bf16x8 pf[JB];
;       if (NT > JB) __builtin_amdgcn_sched_barrier(0);
; #pragma unroll
;       for (int jj = 0; jj < JB; ++jj) {
;         const int j = jh * JB + jj;
;         float mx = -INFINITY;
; #pragma unroll
;         for (int t = 0; t < 2; ++t)
; #pragma unroll
;           for (int i = 0; i < 4; ++i) {
;             if (MASK) { const int kp = kpos0 + 32 * st + 16 * t + 4 * lg + i; if (!mask_ok<MODE>(tq[j], kp, W)) s[jj][t][i] = -INFINITY; }
;             mx = fmaxf(mx, s[jj][t][i]);
;           }
;         mx = max_x16_x32(mx);
;         if (NT > 2 || __any(mx > m[j] + 8.0f / c)) {
;           const float mnew = fmaxf(m[j], mx);
;           const float ms2 = (mnew == -INFINITY) ? 0.f : mnew;
;           const float alpha = ex2((m[j] - ms2) * c);
;           m[j] = mnew; l[j] *= alpha;
; #pragma unroll
;           for (int dt = 0; dt < NDT; ++dt) o[j][dt] *= alpha;
;         }
;         const float mc = ((m[j] == -INFINITY) ? 0.f : m[j]) * c;
;         float p0[4], p1[4], ps = 0.f;
; #pragma unroll
;         for (int i = 0; i < 4; ++i) { p0[i] = ex2(s[jj][0][i] * c - mc); p1[i] = ex2(s[jj][1][i] * c - mc); ps += p0[i] + p1[i]; }
;         l[j] += ps;
;         pf[jj] = pack8(p0, p1);
;       }
;       if (NT > JB) __builtin_amdgcn_sched_barrier(0);
;       __builtin_amdgcn_s_setprio(1);
; #pragma unroll
;       for (int dt = 0; dt < NDT; ++dt) {
;         const s16x4 v0 = ds_tr(Vl + oz + (32 * st + 4 * lg + vq) * VSTR + (16 * dt + 4 * vp) * 2);
;         const s16x4 v1 = ds_tr(Vl + oz + (32 * st + 16 + 4 * lg + vq) * VSTR + (16 * dt + 4 * vp) * 2);
;         const bf16x8 vf = (bf16x8){v0[0], v0[1], v0[2], v0[3], v1[0], v1[1], v1[2], v1[3]};
; #pragma unroll
.LBB0_1126:
	v_mov_b32_e32 v196, v206
	v_mov_b32_e32 v232, v209
	v_or_b32_e32 v199, s8, v203
	v_mov_b32_e32 v206, s45
	v_mov_b32_e32 v209, 0
	v_mov_b32_e32 v197, v207
	v_mov_b32_e32 v235, v210
	v_or_b32_e32 v198, s8, v201
	v_mad_u32_u24 v208, v199, s80, v206
	s_setprio 1
	v_mul_u32_u24_e32 v244, 0x90, v198
	v_add3_u32 v198, v1, v209, v244
	ds_read_b128 v[210:213], v198
	ds_read_b128 v[214:217], v198 offset:64
	s_waitcnt lgkmcnt(1)
	v_mfma_f32_16x16x32_bf16 v[218:221], v[210:213], v[2:5], 0
	v_mfma_f32_16x16x32_bf16 v[210:213], v[210:213], v[10:13], 0
	s_waitcnt lgkmcnt(0)
	v_mfma_f32_16x16x32_bf16 v[218:221], v[214:217], v[6:9], v[218:221]
	v_mfma_f32_16x16x32_bf16 v[210:213], v[214:217], v[14:17], v[210:213]
	ds_read_b128 v[214:217], v198 offset:2304
	ds_read_b128 v[222:225], v198 offset:2368
	s_waitcnt lgkmcnt(1)
	v_mfma_f32_16x16x32_bf16 v[228:231], v[214:217], v[2:5], 0
	v_mfma_f32_16x16x32_bf16 v[214:217], v[214:217], v[10:13], 0
	s_waitcnt lgkmcnt(0)
	v_mfma_f32_16x16x32_bf16 v[228:231], v[222:225], v[6:9], v[228:231]
	v_mfma_f32_16x16x32_bf16 v[214:217], v[222:225], v[14:17], v[214:217]
	s_setprio 0
	v_max3_f32 v198, v218, s81, v219
	v_max3_f32 v198, v198, v220, v221
	s_nop 3
	v_max3_f32 v198, v198, v228, v229
	v_max3_f32 v198, v198, v230, v231
	v_mov_b32_e32 v199, v198
	s_nop 1
	v_permlane16_swap_b32_e32 v198, v199
	v_max_f32_e32 v198, v198, v199
	v_mov_b32_e32 v199, v198
	s_nop 1
	v_permlane32_swap_b32_e32 v198, v199
	v_max3_f32 v206, v196, v198, v199
	v_cmp_eq_f32_e32 vcc, s81, v206
	s_nop 1
	v_cndmask_b32_e64 v198, v206, 0, vcc
	v_sub_f32_e32 v196, v196, v198
	v_mul_f32_e32 v198, 0x3e38aa3b, v206
	v_cndmask_b32_e64 v198, v198, 0, vcc
	v_fma_f32 v207, v228, s42, -v198
	v_exp_f32_e32 v223, v207
	v_fma_f32 v207, v219, s42, -v198
	v_exp_f32_e32 v225, v207
	v_fma_f32 v207, v229, s42, -v198
	v_exp_f32_e32 v229, v207
	v_fma_f32 v207, v220, s42, -v198
	v_exp_f32_e32 v237, v207
	v_fma_f32 v207, v230, s42, -v198
	v_fma_f32 v199, v218, s42, -v198
	v_exp_f32_e32 v239, v207
	v_fma_f32 v207, v221, s42, -v198
	v_fma_f32 v198, v231, s42, -v198
	v_exp_f32_e32 v231, v198
	v_max3_f32 v198, v210, s81, v211
	v_max3_f32 v198, v198, v212, v213
	v_max3_f32 v198, v198, v214, v215
	v_max3_f32 v198, v198, v216, v217
	v_exp_f32_e32 v241, v207
	v_mov_b32_e32 v207, v198
	s_nop 1
	v_permlane16_swap_b32_e32 v198, v207
	v_max_f32_e32 v198, v198, v207
	v_mul_f32_e32 v196, 0x3e38aa3b, v196
	v_mov_b32_e32 v207, v198
	v_exp_f32_e32 v196, v196
	s_nop 0
	v_permlane32_swap_b32_e32 v198, v207
	v_max3_f32 v207, v197, v198, v207
	v_cmp_eq_f32_e32 vcc, s81, v207
	v_pk_mul_f32 v[140:141], v[140:141], v[196:197] op_sel_hi:[1,0]
	v_pk_mul_f32 v[138:139], v[138:139], v[196:197] op_sel_hi:[1,0]
	v_cndmask_b32_e64 v198, v207, 0, vcc
	v_pk_mul_f32 v[136:137], v[136:137], v[196:197] op_sel_hi:[1,0]
	v_pk_mul_f32 v[134:135], v[134:135], v[196:197] op_sel_hi:[1,0]
	v_pk_mul_f32 v[156:157], v[156:157], v[196:197] op_sel_hi:[1,0]
	v_pk_mul_f32 v[154:155], v[154:155], v[196:197] op_sel_hi:[1,0]
	v_pk_mul_f32 v[164:165], v[164:165], v[196:197] op_sel_hi:[1,0]
	v_pk_mul_f32 v[162:163], v[162:163], v[196:197] op_sel_hi:[1,0]
	v_sub_f32_e32 v197, v197, v198
	v_mul_f32_e32 v197, 0x3e38aa3b, v197
	v_exp_f32_e32 v242, v197
	v_mul_f32_e32 v197, 0x3e38aa3b, v207
	v_cndmask_b32_e64 v197, v197, 0, vcc
	v_fma_f32 v198, v210, s42, -v197
	v_fma_f32 v210, v214, s42, -v197
	v_exp_f32_e32 v222, v210
	v_fma_f32 v210, v211, s42, -v197
	v_exp_f32_e32 v224, v210
	v_fma_f32 v210, v215, s42, -v197
	v_exp_f32_e32 v199, v199
	v_exp_f32_e32 v198, v198
	v_exp_f32_e32 v228, v210
	v_fma_f32 v210, v212, s42, -v197
	v_exp_f32_e32 v236, v210
	v_fma_f32 v210, v216, s42, -v197
	v_exp_f32_e32 v238, v210
	v_fma_f32 v210, v213, s42, -v197
	v_fma_f32 v197, v217, s42, -v197
	v_exp_f32_e32 v240, v210
	v_exp_f32_e32 v230, v197
	v_pk_mul_f32 v[112:113], v[112:113], v[242:243] op_sel_hi:[1,0]
	v_pk_mul_f32 v[110:111], v[110:111], v[242:243] op_sel_hi:[1,0]
	v_pk_mul_f32 v[108:109], v[108:109], v[242:243] op_sel_hi:[1,0]
	v_pk_mul_f32 v[106:107], v[106:107], v[242:243] op_sel_hi:[1,0]
	v_pk_mul_f32 v[124:125], v[124:125], v[242:243] op_sel_hi:[1,0]
	v_pk_mul_f32 v[122:123], v[122:123], v[242:243] op_sel_hi:[1,0]
	v_pk_mul_f32 v[132:133], v[132:133], v[242:243] op_sel_hi:[1,0]
	v_pk_mul_f32 v[130:131], v[130:131], v[242:243] op_sel_hi:[1,0]
	v_mov_b32_e32 v243, v196
	v_pk_add_f32 v[196:197], v[198:199], v[222:223]
	v_pk_add_f32 v[210:211], v[224:225], v[228:229]
	v_cvt_pk_bf16_f32 v218, v199, v225
	v_pk_add_f32 v[196:197], v[210:211], v[196:197]
	v_pk_add_f32 v[210:211], v[236:237], v[238:239]
	v_cvt_pk_bf16_f32 v219, v237, v241
	v_pk_add_f32 v[196:197], v[210:211], v[196:197]
	v_pk_add_f32 v[210:211], v[240:241], v[230:231]
	v_cvt_pk_bf16_f32 v220, v223, v229
	v_pk_add_f32 v[196:197], v[210:211], v[196:197]
	v_cvt_pk_bf16_f32 v210, v198, v224
	v_pk_fma_f32 v[180:181], v[180:181], v[242:243], v[196:197]
	v_cvt_pk_bf16_f32 v221, v239, v231
	v_cvt_pk_bf16_f32 v211, v236, v240
	v_cvt_pk_bf16_f32 v212, v222, v228
	v_cvt_pk_bf16_f32 v213, v238, v230
	s_setprio 1
	v_add3_u32 v196, v208, v209, v204
	ds_read_b64_tr_b16 v[216:217], v196 offset:11776
	ds_read_b64_tr_b16 v[214:215], v196 offset:9216
	ds_read_b64_tr_b16 v[222:223], v196 offset:9248
	ds_read_b64_tr_b16 v[224:225], v196 offset:11808
	s_waitcnt lgkmcnt(2)
	v_mfma_f32_16x16x32_bf16 v[138:141], v[214:217], v[218:221], v[138:141]
	v_mfma_f32_16x16x32_bf16 v[110:113], v[214:217], v[210:213], v[110:113]
	ds_read_b64_tr_b16 v[214:215], v196 offset:9280
	ds_read_b64_tr_b16 v[216:217], v196 offset:11840
	s_waitcnt lgkmcnt(0)
; template <int NT, int NKK, int NDT, int MODE, bool MASK> ...
;     ...
;     for (int jh = 0; jh < NT / JB; ++jh) {
;       int oz = 0; if (NT > JB) asm volatile("" : "+v"(oz));
;       f32x4 s[JB][2];
;       __builtin_amdgcn_s_setprio(1);
; #pragma unroll
;       for (int t = 0; t < 2; ++t)
; #pragma unroll
;         for (int kk = 0; kk < NKK; ++kk) {
;           const bf16x8 kf = *(LAS const bf16x8*)(Kl + oz + (32 * st + 16 * t + r) * KSTR + (32 * kk + 8 * lg) * 2);
; #pragma unroll
;           for (int jj = 0; jj < JB; ++jj) s[jj][t] = mfma16(kf, qf[jh * JB + jj][kk], kk == 0 ? (f32x4){0.f, 0.f, 0.f, 0.f} : s[jj][t]);
;         }
;       __builtin_amdgcn_s_setprio(0);
;       bf16x8 pf[JB];
;       if (NT > JB) __builtin_amdgcn_sched_barrier(0);
; #pragma unroll
;       for (int jj = 0; jj < JB; ++jj) {
;         const int j = jh * JB + jj;
;         float mx = -INFINITY;
; #pragma unroll
;         for (int t = 0; t < 2; ++t)
; #pragma unroll
;           for (int i = 0; i < 4; ++i) {
;             if (MASK) { const int kp = kpos0 + 32 * st + 16 * t + 4 * lg + i; if (!mask_ok<MODE>(tq[j], kp, W)) s[jj][t][i] = -INFINITY; }
;             mx = fmaxf(mx, s[jj][t][i]);
;           }
;         mx = max_x16_x32(mx);
;         if (NT > 2 || __any(mx > m[j] + 8.0f / c)) {
;           const float mnew = fmaxf(m[j], mx);
;           const float ms2 = (mnew == -INFINITY) ? 0.f : mnew;
;           const float alpha = ex2((m[j] - ms2) * c);
;           m[j] = mnew; l[j] *= alpha;
; #pragma unroll
;           for (int dt = 0; dt < NDT; ++dt) o[j][dt] *= alpha;
;         }
;         const float mc = ((m[j] == -INFINITY) ? 0.f : m[j]) * c;
;         float p0[4], p1[4], ps = 0.f;
; #pragma unroll
;         for (int i = 0; i < 4; ++i) { p0[i] = ex2(s[jj][0][i] * c - mc); p1[i] = ex2(s[jj][1][i] * c - mc); ps += p0[i] + p1[i]; }
;         l[j] += ps;
;         pf[jj] = pack8(p0, p1);
;       }
;       if (NT > JB) __builtin_amdgcn_sched_barrier(0);
;       __builtin_amdgcn_s_setprio(1);
; #pragma unroll
;       for (int dt = 0; dt < NDT; ++dt) {
;         const s16x4 v0 = ds_tr(Vl + oz + (32 * st + 4 * lg + vq) * VSTR + (16 * dt + 4 * vp) * 2);
;         const s16x4 v1 = ds_tr(Vl + oz + (32 * st + 16 + 4 * lg + vq) * VSTR + (16 * dt + 4 * vp) * 2);
;         const bf16x8 vf = (bf16x8){v0[0], v0[1], v0[2], v0[3], v1[0], v1[1], v1[2], v1[3]};
; #pragma unroll
	v_mfma_f32_16x16x32_bf16 v[154:157], v[214:217], v[218:221], v[154:157]
	v_mfma_f32_16x16x32_bf16 v[122:125], v[214:217], v[210:213], v[122:125]
	ds_read_b64_tr_b16 v[214:215], v196 offset:9312
	ds_read_b64_tr_b16 v[216:217], v196 offset:11872
	v_mfma_f32_16x16x32_bf16 v[134:137], v[222:225], v[218:221], v[134:137]
	v_mfma_f32_16x16x32_bf16 v[106:109], v[222:225], v[210:213], v[106:109]
	s_waitcnt lgkmcnt(0)
	v_mfma_f32_16x16x32_bf16 v[162:165], v[214:217], v[218:221], v[162:165]
	v_mfma_f32_16x16x32_bf16 v[130:133], v[214:217], v[210:213], v[130:133]
	s_setprio 0
	v_mov_b32_e32 v246, 0
	s_setprio 1
	v_add3_u32 v196, v1, v246, v244
	ds_read_b128 v[210:213], v196
	ds_read_b128 v[214:217], v196 offset:64
	ds_read_b128 v[222:225], v196 offset:2304
	ds_read_b128 v[228:231], v196 offset:2368
	s_waitcnt lgkmcnt(3)
	v_mfma_f32_16x16x32_bf16 v[218:221], v[210:213], v[18:21], 0
	v_mfma_f32_16x16x32_bf16 v[210:213], v[210:213], v[26:29], 0
	s_waitcnt lgkmcnt(1)
	v_mfma_f32_16x16x32_bf16 v[236:239], v[222:225], v[18:21], 0
	v_mfma_f32_16x16x32_bf16 v[222:225], v[222:225], v[26:29], 0
	v_mfma_f32_16x16x32_bf16 v[218:221], v[214:217], v[22:25], v[218:221]
	v_mfma_f32_16x16x32_bf16 v[212:215], v[214:217], v[30:33], v[210:213]
	s_waitcnt lgkmcnt(0)
	v_mfma_f32_16x16x32_bf16 v[236:239], v[228:231], v[22:25], v[236:239]
	v_mfma_f32_16x16x32_bf16 v[222:225], v[228:231], v[30:33], v[222:225]
	s_setprio 0
	s_nop 1
	v_max3_f32 v196, v218, s81, v219
	v_max3_f32 v196, v196, v220, v221
	s_nop 1
	v_max3_f32 v196, v196, v236, v237
	v_max3_f32 v196, v196, v238, v239
	v_mov_b32_e32 v197, v196
	s_nop 1
	v_permlane16_swap_b32_e32 v196, v197
	v_max_f32_e32 v196, v196, v197
	v_mov_b32_e32 v197, v196
	s_nop 1
	v_permlane32_swap_b32_e32 v196, v197
	v_max3_f32 v209, v232, v196, v197
	v_cmp_eq_f32_e32 vcc, s81, v209
	s_nop 1
	v_cndmask_b32_e64 v196, v209, 0, vcc
	v_sub_f32_e32 v196, v232, v196
	v_mul_f32_e32 v196, 0x3e38aa3b, v196
	v_exp_f32_e32 v196, v196
	s_nop 0
	v_pk_mul_f32 v[152:153], v[152:153], v[196:197] op_sel_hi:[1,0]
	v_pk_mul_f32 v[150:151], v[150:151], v[196:197] op_sel_hi:[1,0]
	v_pk_mul_f32 v[148:149], v[148:149], v[196:197] op_sel_hi:[1,0]
	v_pk_mul_f32 v[146:147], v[146:147], v[196:197] op_sel_hi:[1,0]
	v_pk_mul_f32 v[160:161], v[160:161], v[196:197] op_sel_hi:[1,0]
	v_pk_mul_f32 v[158:159], v[158:159], v[196:197] op_sel_hi:[1,0]
	v_pk_mul_f32 v[168:169], v[168:169], v[196:197] op_sel_hi:[1,0]
	v_pk_mul_f32 v[166:167], v[166:167], v[196:197] op_sel_hi:[1,0]
	v_mul_f32_e32 v197, 0x3e38aa3b, v209
	v_cndmask_b32_e64 v197, v197, 0, vcc
	v_fma_f32 v198, v218, s42, -v197
	v_exp_f32_e32 v199, v198
	v_fma_f32 v198, v236, s42, -v197
	v_exp_f32_e32 v229, v198
	v_fma_f32 v198, v219, s42, -v197
	v_exp_f32_e32 v231, v198
	v_fma_f32 v198, v237, s42, -v197
	v_exp_f32_e32 v237, v198
	v_fma_f32 v198, v220, s42, -v197
	v_exp_f32_e32 v241, v198
	v_fma_f32 v198, v238, s42, -v197
	v_exp_f32_e32 v243, v198
	v_fma_f32 v198, v221, s42, -v197
	v_fma_f32 v197, v239, s42, -v197
	v_exp_f32_e32 v239, v197
	v_max3_f32 v197, v212, s81, v213
	v_max3_f32 v197, v197, v214, v215
	v_max3_f32 v197, v197, v222, v223
	v_max3_f32 v197, v197, v224, v225
	v_exp_f32_e32 v221, v198
	v_mov_b32_e32 v198, v197
	s_nop 1
	v_permlane16_swap_b32_e32 v197, v198
	v_max_f32_e32 v197, v197, v198
	v_mov_b32_e32 v198, v197
	s_nop 1
	v_permlane32_swap_b32_e32 v197, v198
	v_max3_f32 v210, v235, v197, v198
	v_cmp_eq_f32_e32 vcc, s81, v210
	v_cvt_pk_bf16_f32 v216, v199, v231
	v_cvt_pk_bf16_f32 v217, v241, v221
	v_cndmask_b32_e64 v197, v210, 0, vcc
	v_sub_f32_e32 v197, v235, v197
	v_mul_f32_e32 v197, 0x3e38aa3b, v197
	v_exp_f32_e32 v244, v197
	v_mul_f32_e32 v197, 0x3e38aa3b, v210
	v_cndmask_b32_e64 v197, v197, 0, vcc
	v_fma_f32 v211, v222, s42, -v197
	v_exp_f32_e32 v228, v211
	v_fma_f32 v211, v213, s42, -v197
	v_fma_f32 v198, v212, s42, -v197
	v_exp_f32_e32 v230, v211
	v_fma_f32 v211, v223, s42, -v197
	v_exp_f32_e32 v198, v198
	v_exp_f32_e32 v236, v211
	v_fma_f32 v211, v214, s42, -v197
	v_exp_f32_e32 v240, v211
	v_fma_f32 v211, v224, s42, -v197
	v_exp_f32_e32 v242, v211
	v_fma_f32 v211, v215, s42, -v197
	v_fma_f32 v197, v225, s42, -v197
	v_exp_f32_e32 v220, v211
	v_exp_f32_e32 v238, v197
	v_pk_mul_f32 v[120:121], v[120:121], v[244:245] op_sel_hi:[1,0]
	v_pk_mul_f32 v[118:119], v[118:119], v[244:245] op_sel_hi:[1,0]
	v_pk_mul_f32 v[116:117], v[116:117], v[244:245] op_sel_hi:[1,0]
	v_pk_mul_f32 v[114:115], v[114:115], v[244:245] op_sel_hi:[1,0]
	v_pk_mul_f32 v[128:129], v[128:129], v[244:245] op_sel_hi:[1,0]
	v_pk_mul_f32 v[126:127], v[126:127], v[244:245] op_sel_hi:[1,0]
	v_pk_mul_f32 v[144:145], v[144:145], v[244:245] op_sel_hi:[1,0]
	v_pk_mul_f32 v[142:143], v[142:143], v[244:245] op_sel_hi:[1,0]
	v_mov_b32_e32 v245, v196
	v_pk_add_f32 v[196:197], v[198:199], v[228:229]
	v_pk_add_f32 v[212:213], v[230:231], v[236:237]
	v_cvt_pk_bf16_f32 v218, v229, v237
	v_pk_add_f32 v[196:197], v[212:213], v[196:197]
	v_pk_add_f32 v[212:213], v[240:241], v[242:243]
	v_cvt_pk_bf16_f32 v219, v243, v239
	v_pk_add_f32 v[196:197], v[212:213], v[196:197]
	v_pk_add_f32 v[212:213], v[220:221], v[238:239]
	v_cvt_pk_bf16_f32 v214, v228, v236
	v_pk_add_f32 v[196:197], v[212:213], v[196:197]
	v_cvt_pk_bf16_f32 v212, v198, v230
	v_pk_fma_f32 v[182:183], v[182:183], v[244:245], v[196:197]
	v_cvt_pk_bf16_f32 v213, v240, v220
	v_cvt_pk_bf16_f32 v215, v242, v238
	s_setprio 1
	v_add3_u32 v196, v208, v246, v204
	ds_read_b64_tr_b16 v[222:223], v196 offset:11776
	ds_read_b64_tr_b16 v[220:221], v196 offset:9216
	ds_read_b64_tr_b16 v[228:229], v196 offset:9248
	ds_read_b64_tr_b16 v[230:231], v196 offset:11808
	s_waitcnt lgkmcnt(2)
	v_mfma_f32_16x16x32_bf16 v[150:153], v[220:223], v[216:219], v[150:153]
	v_mfma_f32_16x16x32_bf16 v[118:121], v[220:223], v[212:215], v[118:121]
	ds_read_b64_tr_b16 v[220:221], v196 offset:9280
	ds_read_b64_tr_b16 v[222:223], v196 offset:11840
	s_waitcnt lgkmcnt(0)
	v_mfma_f32_16x16x32_bf16 v[158:161], v[220:223], v[216:219], v[158:161]
	v_mfma_f32_16x16x32_bf16 v[126:129], v[220:223], v[212:215], v[126:129]
	ds_read_b64_tr_b16 v[220:221], v196 offset:9312
	ds_read_b64_tr_b16 v[222:223], v196 offset:11872
	v_mfma_f32_16x16x32_bf16 v[146:149], v[228:231], v[216:219], v[146:149]
	v_mfma_f32_16x16x32_bf16 v[114:117], v[228:231], v[212:215], v[114:117]
	s_waitcnt lgkmcnt(0)
	v_mfma_f32_16x16x32_bf16 v[166:169], v[220:223], v[216:219], v[166:169]
	v_mfma_f32_16x16x32_bf16 v[142:145], v[220:223], v[212:215], v[142:145]
	s_setprio 0
	s_mov_b32 s8, 32
	s_andn2_b64 vcc, exec, s[26:27]
	s_mov_b64 s[26:27], 0
	s_cbranch_vccz .LBB0_1126

; template <int NT, int NKK, int NDT, int MODE, bool MASK> ...
;     ...
;     for (int jh = 0; jh < NT / JB; ++jh) {
;       int oz = 0; if (NT > JB) asm volatile("" : "+v"(oz));
;       f32x4 s[JB][2];
;       __builtin_amdgcn_s_setprio(1);
; #pragma unroll
;       for (int t = 0; t < 2; ++t)
; #pragma unroll
;         for (int kk = 0; kk < NKK; ++kk) {
;           const bf16x8 kf = *(LAS const bf16x8*)(Kl + oz + (32 * st + 16 * t + r) * KSTR + (32 * kk + 8 * lg) * 2);
; #pragma unroll
;           for (int jj = 0; jj < JB; ++jj) s[jj][t] = mfma16(kf, qf[jh * JB + jj][kk], kk == 0 ? (f32x4){0.f, 0.f, 0.f, 0.f} : s[jj][t]);
;         }
;       __builtin_amdgcn_s_setprio(0);
;       bf16x8 pf[JB];
;       if (NT > JB) __builtin_amdgcn_sched_barrier(0);
; #pragma unroll
;       for (int jj = 0; jj < JB; ++jj) {
;         const int j = jh * JB + jj;
;         float mx = -INFINITY;
; #pragma unroll
;         for (int t = 0; t < 2; ++t)
; #pragma unroll
;           for (int i = 0; i < 4; ++i) {
;             if (MASK) { const int kp = kpos0 + 32 * st + 16 * t + 4 * lg + i; if (!mask_ok<MODE>(tq[j], kp, W)) s[jj][t][i] = -INFINITY; }
;             mx = fmaxf(mx, s[jj][t][i]);
;           }
;         mx = max_x16_x32(mx);
;         if (NT > 2 || __any(mx > m[j] + 8.0f / c)) {
;           const float mnew = fmaxf(m[j], mx);
;           const float ms2 = (mnew == -INFINITY) ? 0.f : mnew;
;           const float alpha = ex2((m[j] - ms2) * c);
;           m[j] = mnew; l[j] *= alpha;
; #pragma unroll
;           for (int dt = 0; dt < NDT; ++dt) o[j][dt] *= alpha;
;         }
;         const float mc = ((m[j] == -INFINITY) ? 0.f : m[j]) * c;
;         float p0[4], p1[4], ps = 0.f;
; #pragma unroll
;         for (int i = 0; i < 4; ++i) { p0[i] = ex2(s[jj][0][i] * c - mc); p1[i] = ex2(s[jj][1][i] * c - mc); ps += p0[i] + p1[i]; }
;         l[j] += ps;
;         pf[jj] = pack8(p0, p1);
;       }
;       if (NT > JB) __builtin_amdgcn_sched_barrier(0);
;       __builtin_amdgcn_s_setprio(1);
; #pragma unroll
;       for (int dt = 0; dt < NDT; ++dt) {
;         const s16x4 v0 = ds_tr(Vl + oz + (32 * st + 4 * lg + vq) * VSTR + (16 * dt + 4 * vp) * 2);
;         const s16x4 v1 = ds_tr(Vl + oz + (32 * st + 16 + 4 * lg + vq) * VSTR + (16 * dt + 4 * vp) * 2);
;         const bf16x8 vf = (bf16x8){v0[0], v0[1], v0[2], v0[3], v1[0], v1[1], v1[2], v1[3]};
; #pragma unroll
.LBB0_1129:
	v_or_b32_e32 v107, s8, v203
	v_mov_b32_e32 v111, s45
	v_mov_b32_e32 v141, 0
	v_mov_b32_e32 v109, v175
	v_mov_b32_e32 v130, v190
	v_mov_b32_e32 v140, v191
	v_mov_b32_e32 v108, v192
	v_or_b32_e32 v110, s8, v201
	v_or_b32_e32 v131, s8, v106
	v_mad_u32_u24 v107, v107, s80, v111
	s_setprio 1
	v_mul_u32_u24_e32 v142, 0x90, v110
	v_add3_u32 v122, v1, v141, v142
	ds_read_b128 v[110:113], v122
	ds_read_b128 v[114:117], v122 offset:64
	s_waitcnt lgkmcnt(1)
	v_mfma_f32_16x16x32_bf16 v[118:121], v[110:113], v[2:5], 0
	v_mfma_f32_16x16x32_bf16 v[110:113], v[110:113], v[10:13], 0
	s_waitcnt lgkmcnt(0)
	v_mfma_f32_16x16x32_bf16 v[118:121], v[114:117], v[6:9], v[118:121]
	v_mfma_f32_16x16x32_bf16 v[110:113], v[114:117], v[14:17], v[110:113]
	ds_read_b128 v[114:117], v122 offset:2304
	ds_read_b128 v[122:125], v122 offset:2368
	s_waitcnt lgkmcnt(1)
	v_mfma_f32_16x16x32_bf16 v[126:129], v[114:117], v[2:5], 0
	v_mfma_f32_16x16x32_bf16 v[114:117], v[114:117], v[10:13], 0
	s_waitcnt lgkmcnt(0)
	v_mfma_f32_16x16x32_bf16 v[126:129], v[122:125], v[6:9], v[126:129]
	v_mfma_f32_16x16x32_bf16 v[114:117], v[122:125], v[14:17], v[114:117]
	s_setprio 0
	v_lshlrev_b32_e32 v123, 4, v131
	v_or_b32_e32 v143, 31, v123
	v_mov_b32_e32 v122, s81
	v_cmp_gt_i32_e32 vcc, v143, v184
	v_or_b32_e32 v144, 47, v123
	v_or_b32_e32 v145, 63, v123
	v_cndmask_b32_e32 v124, v118, v122, vcc
	v_cmp_le_i32_e32 vcc, v144, v184
	v_add_u32_e32 v146, 0x4f, v123
	v_or_b32_e32 v147, 0x11f, v123
	v_cndmask_b32_e32 v119, v200, v119, vcc
	v_cmp_le_i32_e32 vcc, v145, v184
	v_max3_f32 v118, v124, s81, v119
	v_or_b32_e32 v148, 0x12f, v123
	v_cndmask_b32_e32 v120, v200, v120, vcc
	v_cmp_le_i32_e32 vcc, v146, v184
	v_or_b32_e32 v149, 0x13f, v123
	v_add_u32_e32 v150, 0x14f, v123
	v_cndmask_b32_e32 v121, v200, v121, vcc
	v_max3_f32 v122, v118, v120, v121
	v_mov_b32_e32 v118, s81
	v_cmp_gt_i32_e32 vcc, v147, v184
	s_nop 1
	v_cndmask_b32_e32 v118, v126, v118, vcc
	v_cmp_le_i32_e32 vcc, v148, v184
	s_nop 1
	v_cndmask_b32_e32 v126, v200, v127, vcc
	v_cmp_le_i32_e32 vcc, v149, v184
	v_max3_f32 v122, v122, v118, v126
	s_nop 0
	v_cndmask_b32_e32 v128, v200, v128, vcc
	v_cmp_le_i32_e32 vcc, v150, v184
	s_nop 1
	v_cndmask_b32_e32 v123, v200, v129, vcc
	v_max3_f32 v122, v122, v128, v123
	v_mov_b32_e32 v125, v122
	s_nop 1
	v_permlane16_swap_b32_e32 v122, v125
	v_max_f32_e32 v122, v122, v125
	v_mov_b32_e32 v125, v122
	s_nop 1
	v_permlane32_swap_b32_e32 v122, v125
	v_max3_f32 v175, v109, v122, v125
	v_cmp_eq_f32_e32 vcc, s81, v175
	s_nop 1
	v_cndmask_b32_e64 v122, v175, 0, vcc
	v_sub_f32_e32 v109, v109, v122
	v_mul_f32_e32 v109, 0x3e38aa3b, v109
	v_exp_f32_e32 v122, v109
	v_mul_f32_e32 v109, 0x3e38aa3b, v175
	v_cndmask_b32_e64 v109, v109, 0, vcc
	v_fma_f32 v118, v118, s42, -v109
	v_exp_f32_e32 v127, v118
	v_fma_f32 v118, v119, s42, -v109
	v_exp_f32_e32 v129, v118
	v_fma_f32 v118, v126, s42, -v109
	v_exp_f32_e32 v131, v118
	v_fma_f32 v118, v120, s42, -v109
	v_exp_f32_e32 v133, v118
	v_fma_f32 v118, v128, s42, -v109
	v_fma_f32 v124, v124, s42, -v109
	v_exp_f32_e32 v135, v118
	v_fma_f32 v118, v121, s42, -v109
	v_fma_f32 v109, v123, s42, -v109
	v_mov_b32_e32 v120, s81
	v_cmp_gt_i32_e32 vcc, v143, v185
	v_exp_f32_e32 v139, v109
	v_pk_mul_f32 v[92:93], v[92:93], v[122:123] op_sel_hi:[1,0]
	v_cndmask_b32_e32 v109, v110, v120, vcc
	v_cmp_le_i32_e32 vcc, v144, v185
	v_pk_mul_f32 v[90:91], v[90:91], v[122:123] op_sel_hi:[1,0]
	v_pk_mul_f32 v[88:89], v[88:89], v[122:123] op_sel_hi:[1,0]
	v_cndmask_b32_e32 v111, v200, v111, vcc
	v_cmp_le_i32_e32 vcc, v145, v185
	v_max3_f32 v110, v109, s81, v111
	v_pk_mul_f32 v[86:87], v[86:87], v[122:123] op_sel_hi:[1,0]
	v_cndmask_b32_e32 v112, v200, v112, vcc
	v_cmp_le_i32_e32 vcc, v146, v185
	v_pk_mul_f32 v[96:97], v[96:97], v[122:123] op_sel_hi:[1,0]
	v_pk_mul_f32 v[94:95], v[94:95], v[122:123] op_sel_hi:[1,0]
	v_cndmask_b32_e32 v113, v200, v113, vcc
	v_max3_f32 v119, v110, v112, v113
	v_mov_b32_e32 v110, s81
	v_cmp_gt_i32_e32 vcc, v147, v185
	v_pk_mul_f32 v[84:85], v[84:85], v[122:123] op_sel_hi:[1,0]
	v_pk_mul_f32 v[82:83], v[82:83], v[122:123] op_sel_hi:[1,0]
	v_cndmask_b32_e32 v114, v114, v110, vcc
	v_cmp_le_i32_e32 vcc, v148, v185
	v_exp_f32_e32 v125, v124
	v_exp_f32_e32 v137, v118
	v_cndmask_b32_e32 v115, v200, v115, vcc
	v_cmp_le_i32_e32 vcc, v149, v185
	v_max3_f32 v110, v119, v114, v115
	v_cvt_pk_bf16_f32 v118, v125, v129
	v_cndmask_b32_e32 v116, v200, v116, vcc
	v_cmp_le_i32_e32 vcc, v150, v185
	v_cvt_pk_bf16_f32 v120, v127, v131
	v_cvt_pk_bf16_f32 v121, v135, v139
	v_cndmask_b32_e32 v117, v200, v117, vcc
	v_max3_f32 v110, v110, v116, v117
	v_mov_b32_e32 v119, v110
	s_nop 1
	v_permlane16_swap_b32_e32 v110, v119
	v_max_f32_e32 v110, v110, v119
	v_mov_b32_e32 v119, v110
	s_nop 1
	v_permlane32_swap_b32_e32 v110, v119
	v_max3_f32 v190, v130, v110, v119
	v_cmp_eq_f32_e32 vcc, s81, v190
	v_mul_f32_e32 v123, 0x3e38aa3b, v190
	v_cvt_pk_bf16_f32 v119, v133, v137
	v_cndmask_b32_e64 v123, v123, 0, vcc
	v_fma_f32 v109, v109, s42, -v123
	v_exp_f32_e32 v124, v109
	v_fma_f32 v109, v114, s42, -v123
	v_exp_f32_e32 v126, v109
	v_fma_f32 v109, v111, s42, -v123
	v_cndmask_b32_e64 v110, v190, 0, vcc
	v_exp_f32_e32 v128, v109
	v_fma_f32 v109, v115, s42, -v123
	v_sub_f32_e32 v110, v130, v110
	v_exp_f32_e32 v130, v109
	v_fma_f32 v109, v112, s42, -v123
	v_exp_f32_e32 v132, v109
	v_fma_f32 v109, v116, s42, -v123
	v_exp_f32_e32 v134, v109
	v_fma_f32 v109, v113, s42, -v123
	v_exp_f32_e32 v136, v109
	v_fma_f32 v109, v117, s42, -v123
	v_mul_f32_e32 v110, 0x3e38aa3b, v110
	v_exp_f32_e32 v138, v109
	v_exp_f32_e32 v110, v110
	v_pk_add_f32 v[112:113], v[124:125], v[126:127]
	v_pk_add_f32 v[114:115], v[128:129], v[130:131]
	v_pk_mul_f32 v[80:81], v[80:81], v[110:111] op_sel_hi:[1,0]
	v_pk_add_f32 v[112:113], v[114:115], v[112:113]
	v_pk_add_f32 v[114:115], v[132:133], v[134:135]
	v_pk_mul_f32 v[78:79], v[78:79], v[110:111] op_sel_hi:[1,0]
	v_pk_add_f32 v[112:113], v[114:115], v[112:113]
	v_pk_add_f32 v[114:115], v[136:137], v[138:139]
	v_pk_mul_f32 v[76:77], v[76:77], v[110:111] op_sel_hi:[1,0]
	v_pk_mul_f32 v[74:75], v[74:75], v[110:111] op_sel_hi:[1,0]
	v_pk_mul_f32 v[72:73], v[72:73], v[110:111] op_sel_hi:[1,0]
	v_pk_mul_f32 v[70:71], v[70:71], v[110:111] op_sel_hi:[1,0]
	v_pk_mul_f32 v[68:69], v[68:69], v[110:111] op_sel_hi:[1,0]
	v_pk_mul_f32 v[66:67], v[66:67], v[110:111] op_sel_hi:[1,0]
	v_mov_b32_e32 v111, v122
	v_pk_add_f32 v[112:113], v[114:115], v[112:113]
	s_nop 0
	v_pk_fma_f32 v[172:173], v[172:173], v[110:111], v[112:113]
	v_cvt_pk_bf16_f32 v110, v124, v128
	v_cvt_pk_bf16_f32 v111, v132, v136
	v_cvt_pk_bf16_f32 v112, v126, v130
	v_cvt_pk_bf16_f32 v113, v134, v138
	s_setprio 1
	v_add3_u32 v109, v107, v141, v204
	ds_read_b64_tr_b16 v[116:117], v109 offset:11776
	ds_read_b64_tr_b16 v[114:115], v109 offset:9216
	ds_read_b64_tr_b16 v[122:123], v109 offset:9248
	ds_read_b64_tr_b16 v[124:125], v109 offset:11808
	s_waitcnt lgkmcnt(2)
; template <int NT, int NKK, int NDT, int MODE, bool MASK> ...
;     ...
;     for (int jh = 0; jh < NT / JB; ++jh) {
;       int oz = 0; if (NT > JB) asm volatile("" : "+v"(oz));
;       f32x4 s[JB][2];
;       __builtin_amdgcn_s_setprio(1);
; #pragma unroll
;       for (int t = 0; t < 2; ++t)
; #pragma unroll
;         for (int kk = 0; kk < NKK; ++kk) {
;           const bf16x8 kf = *(LAS const bf16x8*)(Kl + oz + (32 * st + 16 * t + r) * KSTR + (32 * kk + 8 * lg) * 2);
; #pragma unroll
;           for (int jj = 0; jj < JB; ++jj) s[jj][t] = mfma16(kf, qf[jh * JB + jj][kk], kk == 0 ? (f32x4){0.f, 0.f, 0.f, 0.f} : s[jj][t]);
;         }
;       __builtin_amdgcn_s_setprio(0);
;       bf16x8 pf[JB];
;       if (NT > JB) __builtin_amdgcn_sched_barrier(0);
; #pragma unroll
;       for (int jj = 0; jj < JB; ++jj) {
;         const int j = jh * JB + jj;
;         float mx = -INFINITY;
; #pragma unroll
;         for (int t = 0; t < 2; ++t)
; #pragma unroll
;           for (int i = 0; i < 4; ++i) {
;             if (MASK) { const int kp = kpos0 + 32 * st + 16 * t + 4 * lg + i; if (!mask_ok<MODE>(tq[j], kp, W)) s[jj][t][i] = -INFINITY; }
;             mx = fmaxf(mx, s[jj][t][i]);
;           }
;         mx = max_x16_x32(mx);
;         if (NT > 2 || __any(mx > m[j] + 8.0f / c)) {
;           const float mnew = fmaxf(m[j], mx);
;           const float ms2 = (mnew == -INFINITY) ? 0.f : mnew;
;           const float alpha = ex2((m[j] - ms2) * c);
;           m[j] = mnew; l[j] *= alpha;
; #pragma unroll
;           for (int dt = 0; dt < NDT; ++dt) o[j][dt] *= alpha;
;         }
;         const float mc = ((m[j] == -INFINITY) ? 0.f : m[j]) * c;
;         float p0[4], p1[4], ps = 0.f;
; #pragma unroll
;         for (int i = 0; i < 4; ++i) { p0[i] = ex2(s[jj][0][i] * c - mc); p1[i] = ex2(s[jj][1][i] * c - mc); ps += p0[i] + p1[i]; }
;         l[j] += ps;
;         pf[jj] = pack8(p0, p1);
;       }
;       if (NT > JB) __builtin_amdgcn_sched_barrier(0);
;       __builtin_amdgcn_s_setprio(1);
; #pragma unroll
;       for (int dt = 0; dt < NDT; ++dt) {
;         const s16x4 v0 = ds_tr(Vl + oz + (32 * st + 4 * lg + vq) * VSTR + (16 * dt + 4 * vp) * 2);
;         const s16x4 v1 = ds_tr(Vl + oz + (32 * st + 16 + 4 * lg + vq) * VSTR + (16 * dt + 4 * vp) * 2);
;         const bf16x8 vf = (bf16x8){v0[0], v0[1], v0[2], v0[3], v1[0], v1[1], v1[2], v1[3]};
; #pragma unroll
	v_mfma_f32_16x16x32_bf16 v[90:93], v[114:117], v[118:121], v[90:93]
	v_mfma_f32_16x16x32_bf16 v[78:81], v[114:117], v[110:113], v[78:81]
	ds_read_b64_tr_b16 v[114:115], v109 offset:9280
	ds_read_b64_tr_b16 v[116:117], v109 offset:11840
	s_waitcnt lgkmcnt(0)
	v_mfma_f32_16x16x32_bf16 v[94:97], v[114:117], v[118:121], v[94:97]
	v_mfma_f32_16x16x32_bf16 v[70:73], v[114:117], v[110:113], v[70:73]
	ds_read_b64_tr_b16 v[114:115], v109 offset:9312
	ds_read_b64_tr_b16 v[116:117], v109 offset:11872
	v_mfma_f32_16x16x32_bf16 v[86:89], v[122:125], v[118:121], v[86:89]
	v_mfma_f32_16x16x32_bf16 v[74:77], v[122:125], v[110:113], v[74:77]
	s_waitcnt lgkmcnt(0)
	v_mfma_f32_16x16x32_bf16 v[82:85], v[114:117], v[118:121], v[82:85]
	v_mfma_f32_16x16x32_bf16 v[66:69], v[114:117], v[110:113], v[66:69]
	s_setprio 0
	v_mov_b32_e32 v138, 0
	s_setprio 1
	v_add3_u32 v109, v1, v138, v142
	ds_read_b128 v[110:113], v109
	ds_read_b128 v[114:117], v109 offset:64
	s_waitcnt lgkmcnt(1)
	v_mfma_f32_16x16x32_bf16 v[118:121], v[110:113], v[18:21], 0
	v_mfma_f32_16x16x32_bf16 v[110:113], v[110:113], v[26:29], 0
	s_waitcnt lgkmcnt(0)
	v_mfma_f32_16x16x32_bf16 v[118:121], v[114:117], v[22:25], v[118:121]
	v_mfma_f32_16x16x32_bf16 v[110:113], v[114:117], v[30:33], v[110:113]
	ds_read_b128 v[114:117], v109 offset:2304
	ds_read_b128 v[122:125], v109 offset:2368
	s_waitcnt lgkmcnt(1)
	v_mfma_f32_16x16x32_bf16 v[126:129], v[114:117], v[18:21], 0
	v_mfma_f32_16x16x32_bf16 v[114:117], v[114:117], v[26:29], 0
	s_waitcnt lgkmcnt(0)
	v_mfma_f32_16x16x32_bf16 v[126:129], v[122:125], v[22:25], v[126:129]
	v_mfma_f32_16x16x32_bf16 v[114:117], v[122:125], v[30:33], v[114:117]
	s_setprio 0
	v_mov_b32_e32 v122, s81
	v_cmp_gt_i32_e32 vcc, v143, v186
	s_nop 1
	v_cndmask_b32_e32 v109, v118, v122, vcc
	v_cmp_le_i32_e32 vcc, v144, v186
	s_nop 1
	v_cndmask_b32_e32 v119, v200, v119, vcc
	v_cmp_le_i32_e32 vcc, v145, v186
	v_max3_f32 v118, v109, s81, v119
	s_nop 0
	v_cndmask_b32_e32 v120, v200, v120, vcc
	v_cmp_le_i32_e32 vcc, v146, v186
	s_nop 1
	v_cndmask_b32_e32 v121, v200, v121, vcc
	v_max3_f32 v122, v118, v120, v121
	v_mov_b32_e32 v118, s81
	v_cmp_gt_i32_e32 vcc, v147, v186
	s_nop 1
	v_cndmask_b32_e32 v118, v126, v118, vcc
	v_cmp_le_i32_e32 vcc, v148, v186
	s_nop 1
	v_cndmask_b32_e32 v123, v200, v127, vcc
	v_cmp_le_i32_e32 vcc, v149, v186
	v_max3_f32 v122, v122, v118, v123
	s_nop 0
	v_cndmask_b32_e32 v124, v200, v128, vcc
	v_cmp_le_i32_e32 vcc, v150, v186
	s_nop 1
	v_cndmask_b32_e32 v126, v200, v129, vcc
	v_max3_f32 v122, v122, v124, v126
	v_mov_b32_e32 v125, v122
	s_nop 1
	v_permlane16_swap_b32_e32 v122, v125
	v_max_f32_e32 v122, v122, v125
	v_mov_b32_e32 v125, v122
	s_nop 1
	v_permlane32_swap_b32_e32 v122, v125
	v_max3_f32 v191, v140, v122, v125
	v_cmp_eq_f32_e32 vcc, s81, v191
	v_mul_f32_e32 v125, 0x3e38aa3b, v191
	s_nop 0
	v_cndmask_b32_e64 v122, v191, 0, vcc
	v_sub_f32_e32 v122, v140, v122
	v_mul_f32_e32 v122, 0x3e38aa3b, v122
	v_cndmask_b32_e64 v128, v125, 0, vcc
	v_exp_f32_e32 v122, v122
	v_fma_f32 v118, v118, s42, -v128
	v_exp_f32_e32 v125, v118
	v_fma_f32 v118, v119, s42, -v128
	v_exp_f32_e32 v127, v118
	v_fma_f32 v118, v123, s42, -v128
	v_exp_f32_e32 v129, v118
	v_fma_f32 v118, v120, s42, -v128
	v_mov_b32_e32 v120, s81
	v_cmp_gt_i32_e32 vcc, v143, v187
	v_pk_mul_f32 v[64:65], v[64:65], v[122:123] op_sel_hi:[1,0]
	v_pk_mul_f32 v[62:63], v[62:63], v[122:123] op_sel_hi:[1,0]
	v_pk_mul_f32 v[60:61], v[60:61], v[122:123] op_sel_hi:[1,0]
	v_pk_mul_f32 v[58:59], v[58:59], v[122:123] op_sel_hi:[1,0]
	v_pk_mul_f32 v[52:53], v[52:53], v[122:123] op_sel_hi:[1,0]
	v_pk_mul_f32 v[50:51], v[50:51], v[122:123] op_sel_hi:[1,0]
	v_pk_mul_f32 v[56:57], v[56:57], v[122:123] op_sel_hi:[1,0]
	v_pk_mul_f32 v[54:55], v[54:55], v[122:123] op_sel_hi:[1,0]
	v_cndmask_b32_e32 v123, v110, v120, vcc
	v_cmp_le_i32_e32 vcc, v144, v187
	v_exp_f32_e32 v131, v118
	v_fma_f32 v118, v124, s42, -v128
	v_cndmask_b32_e32 v111, v200, v111, vcc
	v_cmp_le_i32_e32 vcc, v145, v187
	v_max3_f32 v110, v123, s81, v111
	v_exp_f32_e32 v133, v118
	v_cndmask_b32_e32 v112, v200, v112, vcc
	v_cmp_le_i32_e32 vcc, v146, v187
	v_fma_f32 v118, v121, s42, -v128
	v_exp_f32_e32 v135, v118
	v_cndmask_b32_e32 v113, v200, v113, vcc
	v_max3_f32 v119, v110, v112, v113
	v_mov_b32_e32 v110, s81
	v_cmp_gt_i32_e32 vcc, v147, v187
	v_fma_f32 v118, v126, s42, -v128
	v_fma_f32 v109, v109, s42, -v128
	v_cndmask_b32_e32 v114, v114, v110, vcc
	v_cmp_le_i32_e32 vcc, v148, v187
	v_exp_f32_e32 v109, v109
	v_exp_f32_e32 v137, v118
	v_cndmask_b32_e32 v115, v200, v115, vcc
	v_cmp_le_i32_e32 vcc, v149, v187
	v_max3_f32 v110, v119, v114, v115
	v_cvt_pk_bf16_f32 v118, v109, v127
	v_cndmask_b32_e32 v116, v200, v116, vcc
	v_cmp_le_i32_e32 vcc, v150, v187
; __device__ __forceinline__ float ex2(float x) { return __builtin_amdgcn_exp2f(x); }
; __device__ __forceinline__ f32x4 mfma16(bf16x8 a, bf16x8 b, f32x4 c) { return __builtin_amdgcn_mfma_f32_16x16x32_bf16(a, b, c, 0, 0, 0); }
; __device__ __forceinline__ s16x4 ds_tr(LAS const unsigned char* p) { return __builtin_bit_cast(s16x4, __builtin_amdgcn_ds_read_tr16_b64_v4i16((LAS v4i16_t*)p)); }
;   __device__ __forceinline__ bf16_t* W() const { return (bf16_t*)(ws + WS_W); }
; template <int NT, int NKK, int NDT, int MODE, bool MASK> ...
;     ...
;       for (int jj = 0; jj < JB; ++jj) {
;         const int j = jh * JB + jj;
;         float mx = -INFINITY;
; #pragma unroll
;         for (int t = 0; t < 2; ++t)
; #pragma unroll
;           for (int i = 0; i < 4; ++i) {
;             if (MASK) { const int kp = kpos0 + 32 * st + 16 * t + 4 * lg + i; if (!mask_ok<MODE>(tq[j], kp, W)) s[jj][t][i] = -INFINITY; }
;             mx = fmaxf(mx, s[jj][t][i]);
;           }
;         mx = max_x16_x32(mx);
;         if (NT > 2 || __any(mx > m[j] + 8.0f / c)) {
;           const float mnew = fmaxf(m[j], mx);
;           const float ms2 = (mnew == -INFINITY) ? 0.f : mnew;
;           const float alpha = ex2((m[j] - ms2) * c);
;           m[j] = mnew; l[j] *= alpha;
; #pragma unroll
;           for (int dt = 0; dt < NDT; ++dt) o[j][dt] *= alpha;
;         }
;         const float mc = ((m[j] == -INFINITY) ? 0.f : m[j]) * c;
;         float p0[4], p1[4], ps = 0.f;
; #pragma unroll
;         for (int i = 0; i < 4; ++i) { p0[i] = ex2(s[jj][0][i] * c - mc); p1[i] = ex2(s[jj][1][i] * c - mc); ps += p0[i] + p1[i]; }
;         l[j] += ps;
;         pf[jj] = pack8(p0, p1);
;       }
;       if (NT > JB) __builtin_amdgcn_sched_barrier(0);
;       __builtin_amdgcn_s_setprio(1);
; #pragma unroll
;       for (int dt = 0; dt < NDT; ++dt) {
;         const s16x4 v0 = ds_tr(Vl + oz + (32 * st + 4 * lg + vq) * VSTR + (16 * dt + 4 * vp) * 2);
;         const s16x4 v1 = ds_tr(Vl + oz + (32 * st + 16 + 4 * lg + vq) * VSTR + (16 * dt + 4 * vp) * 2);
;         const bf16x8 vf = (bf16x8){v0[0], v0[1], v0[2], v0[3], v1[0], v1[1], v1[2], v1[3]};
; #pragma unroll
;         for (int jj = 0; jj < JB; ++jj) o[jh * JB + jj][dt] = mfma16(vf, pf[jj], o[jh * JB + jj][dt]);
;       }
;       __builtin_amdgcn_s_setprio(0);
;       if (NT > JB) __builtin_amdgcn_sched_barrier(0);
	v_cvt_pk_bf16_f32 v120, v125, v129
	v_cvt_pk_bf16_f32 v121, v133, v137
	v_cndmask_b32_e32 v117, v200, v117, vcc
	v_max3_f32 v110, v110, v116, v117
	v_mov_b32_e32 v119, v110
	s_nop 1
	v_permlane16_swap_b32_e32 v110, v119
	v_max_f32_e32 v110, v110, v119
	v_mov_b32_e32 v119, v110
	s_nop 1
	v_permlane32_swap_b32_e32 v110, v119
	v_max3_f32 v192, v108, v110, v119
	v_cmp_eq_f32_e32 vcc, s81, v192
	v_cvt_pk_bf16_f32 v119, v131, v135
	s_nop 0
	v_cndmask_b32_e64 v110, v192, 0, vcc
	v_sub_f32_e32 v108, v108, v110
	v_mul_f32_e32 v108, 0x3e38aa3b, v108
	v_exp_f32_e32 v110, v108
	v_mul_f32_e32 v108, 0x3e38aa3b, v192
	v_cndmask_b32_e64 v136, v108, 0, vcc
	v_fma_f32 v108, v123, s42, -v136
	v_pk_mul_f32 v[48:49], v[48:49], v[110:111] op_sel_hi:[1,0]
	v_pk_mul_f32 v[46:47], v[46:47], v[110:111] op_sel_hi:[1,0]
	v_pk_mul_f32 v[44:45], v[44:45], v[110:111] op_sel_hi:[1,0]
	v_pk_mul_f32 v[42:43], v[42:43], v[110:111] op_sel_hi:[1,0]
	v_pk_mul_f32 v[36:37], v[36:37], v[110:111] op_sel_hi:[1,0]
	v_pk_mul_f32 v[34:35], v[34:35], v[110:111] op_sel_hi:[1,0]
	v_pk_mul_f32 v[40:41], v[40:41], v[110:111] op_sel_hi:[1,0]
	v_pk_mul_f32 v[38:39], v[38:39], v[110:111] op_sel_hi:[1,0]
	v_fma_f32 v111, v111, s42, -v136
	v_exp_f32_e32 v126, v111
	v_fma_f32 v111, v115, s42, -v136
	v_fma_f32 v114, v114, s42, -v136
	v_exp_f32_e32 v128, v111
	v_fma_f32 v111, v112, s42, -v136
	v_exp_f32_e32 v108, v108
	v_exp_f32_e32 v124, v114
	v_exp_f32_e32 v130, v111
	v_fma_f32 v111, v116, s42, -v136
	v_exp_f32_e32 v132, v111
	v_fma_f32 v111, v113, s42, -v136
	v_exp_f32_e32 v134, v111
	v_fma_f32 v111, v117, s42, -v136
	v_exp_f32_e32 v136, v111
	v_pk_add_f32 v[112:113], v[108:109], v[124:125]
	v_pk_add_f32 v[114:115], v[126:127], v[128:129]
	v_mov_b32_e32 v111, v122
	v_pk_add_f32 v[112:113], v[114:115], v[112:113]
	v_pk_add_f32 v[114:115], v[130:131], v[132:133]
	v_cvt_pk_bf16_f32 v108, v108, v126
	v_pk_add_f32 v[112:113], v[114:115], v[112:113]
	v_pk_add_f32 v[114:115], v[134:135], v[136:137]
	v_cvt_pk_bf16_f32 v109, v130, v134
	v_pk_add_f32 v[112:113], v[114:115], v[112:113]
	s_nop 0
	v_pk_fma_f32 v[170:171], v[170:171], v[110:111], v[112:113]
	v_cvt_pk_bf16_f32 v110, v124, v128
	v_cvt_pk_bf16_f32 v111, v132, v136
	s_setprio 1
	v_add3_u32 v107, v107, v138, v204
	ds_read_b64_tr_b16 v[114:115], v107 offset:11776
	ds_read_b64_tr_b16 v[112:113], v107 offset:9216
	ds_read_b64_tr_b16 v[122:123], v107 offset:9248
	ds_read_b64_tr_b16 v[124:125], v107 offset:11808
	s_waitcnt lgkmcnt(2)
	v_mfma_f32_16x16x32_bf16 v[62:65], v[112:115], v[118:121], v[62:65]
	v_mfma_f32_16x16x32_bf16 v[46:49], v[112:115], v[108:111], v[46:49]
	ds_read_b64_tr_b16 v[112:113], v107 offset:9280
	ds_read_b64_tr_b16 v[114:115], v107 offset:11840
	s_waitcnt lgkmcnt(0)
	v_mfma_f32_16x16x32_bf16 v[50:53], v[112:115], v[118:121], v[50:53]
	v_mfma_f32_16x16x32_bf16 v[34:37], v[112:115], v[108:111], v[34:37]
	ds_read_b64_tr_b16 v[112:113], v107 offset:9312
	ds_read_b64_tr_b16 v[114:115], v107 offset:11872
	v_mfma_f32_16x16x32_bf16 v[58:61], v[122:125], v[118:121], v[58:61]
	v_mfma_f32_16x16x32_bf16 v[42:45], v[122:125], v[108:111], v[42:45]
	s_waitcnt lgkmcnt(0)
	v_mfma_f32_16x16x32_bf16 v[54:57], v[112:115], v[118:121], v[54:57]
	v_mfma_f32_16x16x32_bf16 v[38:41], v[112:115], v[108:111], v[38:41]
	s_setprio 0
	s_mov_b32 s8, 32
	s_andn2_b64 vcc, exec, s[26:27]
	s_mov_b64 s[26:27], 0
	s_cbranch_vccz .LBB0_1129
	s_branch .Lrt_skip_0
	v_mov_b64_e32 v[140:141], v[92:93]
	v_mov_b64_e32 v[136:137], v[88:89]
	v_mov_b64_e32 v[156:157], v[96:97]
	v_mov_b64_e32 v[164:165], v[84:85]
	v_mov_b64_e32 v[112:113], v[80:81]
	v_mov_b64_e32 v[108:109], v[76:77]
	v_mov_b64_e32 v[124:125], v[72:73]
	v_mov_b64_e32 v[132:133], v[68:69]
	v_mov_b64_e32 v[152:153], v[64:65]
	v_mov_b64_e32 v[148:149], v[60:61]
	v_mov_b64_e32 v[160:161], v[52:53]
	v_mov_b64_e32 v[168:169], v[56:57]
	v_mov_b64_e32 v[120:121], v[48:49]
	v_mov_b64_e32 v[116:117], v[44:45]
	v_mov_b64_e32 v[128:129], v[36:37]
	v_mov_b64_e32 v[144:145], v[40:41]
	v_mov_b64_e32 v[180:181], v[172:173]
	v_mov_b64_e32 v[182:183], v[170:171]
	v_mov_b32_e32 v206, v175
	v_mov_b64_e32 v[138:139], v[90:91]
	v_mov_b64_e32 v[134:135], v[86:87]
	v_mov_b64_e32 v[154:155], v[94:95]
	v_mov_b64_e32 v[162:163], v[82:83]
	v_mov_b32_e32 v207, v190
	v_mov_b64_e32 v[110:111], v[78:79]
	v_mov_b64_e32 v[106:107], v[74:75]
	v_mov_b64_e32 v[122:123], v[70:71]
	v_mov_b64_e32 v[130:131], v[66:67]
	v_mov_b32_e32 v209, v191
	v_mov_b64_e32 v[150:151], v[62:63]
	v_mov_b64_e32 v[146:147], v[58:59]
	v_mov_b64_e32 v[158:159], v[50:51]
	v_mov_b64_e32 v[166:167], v[54:55]
	v_mov_b32_e32 v210, v192
	v_mov_b64_e32 v[118:119], v[46:47]
	v_mov_b64_e32 v[114:115], v[42:43]
	v_mov_b64_e32 v[126:127], v[34:35]
	v_mov_b64_e32 v[142:143], v[38:39]

; #define LAS __attribute__((address_space(3)))
; __device__ __forceinline__ float ex2(float x) { return __builtin_amdgcn_exp2f(x); }
; __device__ __forceinline__ f32x4 mfma16(bf16x8 a, bf16x8 b, f32x4 c) { return __builtin_amdgcn_mfma_f32_16x16x32_bf16(a, b, c, 0, 0, 0); }
;   __device__ __forceinline__ bf16_t* W() const { return (bf16_t*)(ws + WS_W); }
; template <int NT, int NKK, int NDT, int MODE, bool MASK> ...
;     ...
;   for (int st = 0; st < 2; ++st) {
; #pragma unroll
;     for (int jh = 0; jh < NT / JB; ++jh) {
;       int oz = 0; if (NT > JB) asm volatile("" : "+v"(oz));
;       f32x4 s[JB][2];
;       __builtin_amdgcn_s_setprio(1);
; #pragma unroll
;       for (int t = 0; t < 2; ++t)
; #pragma unroll
;         for (int kk = 0; kk < NKK; ++kk) {
;           const bf16x8 kf = *(LAS const bf16x8*)(Kl + oz + (32 * st + 16 * t + r) * KSTR + (32 * kk + 8 * lg) * 2);
; #pragma unroll
;           for (int jj = 0; jj < JB; ++jj) s[jj][t] = mfma16(kf, qf[jh * JB + jj][kk], kk == 0 ? (f32x4){0.f, 0.f, 0.f, 0.f} : s[jj][t]);
;         }
;       __builtin_amdgcn_s_setprio(0);
;       bf16x8 pf[JB];
;       if (NT > JB) __builtin_amdgcn_sched_barrier(0);
; #pragma unroll
;       for (int jj = 0; jj < JB; ++jj) {
;         const int j = jh * JB + jj;
;         float mx = -INFINITY;
; #pragma unroll
;         for (int t = 0; t < 2; ++t)
; #pragma unroll
;           for (int i = 0; i < 4; ++i) {
;             if (MASK) { const int kp = kpos0 + 32 * st + 16 * t + 4 * lg + i; if (!mask_ok<MODE>(tq[j], kp, W)) s[jj][t][i] = -INFINITY; }
;             mx = fmaxf(mx, s[jj][t][i]);
;           }
;         mx = max_x16_x32(mx);
;         if (NT > 2 || __any(mx > m[j] + 8.0f / c)) {
;           const float mnew = fmaxf(m[j], mx);
;           const float ms2 = (mnew == -INFINITY) ? 0.f : mnew;
;           const float alpha = ex2((m[j] - ms2) * c);
;           m[j] = mnew; l[j] *= alpha;
; #pragma unroll
;           for (int dt = 0; dt < NDT; ++dt) o[j][dt] *= alpha;
;         }
.LBB0_1199:
	v_mov_b32_e32 v197, v207
	v_mov_b32_e32 v232, v213
	v_mov_b32_e32 v211, v212
	v_or_b32_e32 v212, s8, v208
	v_or_b32_e32 v198, s8, v191
	v_mov_b32_e32 v207, s75
	v_mov_b32_e32 v213, 0
	v_mov_b32_e32 v199, v209
	v_or_b32_e32 v196, s8, v189
	v_mad_u32_u24 v210, v198, s80, v207
	s_setprio 1
	v_mul_u32_u24_e32 v235, 0x90, v196
	v_add3_u32 v196, v1, v213, v235
	ds_read_b128 v[214:217], v196
	ds_read_b128 v[218:221], v196 offset:64
	s_waitcnt lgkmcnt(1)
	v_mfma_f32_16x16x32_bf16 v[222:225], v[214:217], v[54:57], 0
	v_mfma_f32_16x16x32_bf16 v[214:217], v[214:217], v[62:65], 0
	s_waitcnt lgkmcnt(0)
	v_mfma_f32_16x16x32_bf16 v[222:225], v[218:221], v[58:61], v[222:225]
	v_mfma_f32_16x16x32_bf16 v[214:217], v[218:221], v[66:69], v[214:217]
	ds_read_b128 v[218:221], v196 offset:2304
	ds_read_b128 v[228:231], v196 offset:2368
	s_waitcnt lgkmcnt(1)
	v_mfma_f32_16x16x32_bf16 v[236:239], v[218:221], v[54:57], 0
	v_mfma_f32_16x16x32_bf16 v[218:221], v[218:221], v[62:65], 0
	s_waitcnt lgkmcnt(0)
	v_mfma_f32_16x16x32_bf16 v[236:239], v[228:231], v[58:61], v[236:239]
	v_mfma_f32_16x16x32_bf16 v[218:221], v[228:231], v[66:69], v[218:221]
	s_setprio 0
	v_cmp_le_i32_e32 vcc, v212, v184
	v_cmp_gt_i32_e64 s[12:13], v212, v194
	v_mov_b32_e32 v196, s81
	s_and_b64 vcc, vcc, s[12:13]
	v_cndmask_b32_e32 v209, v196, v222, vcc
	v_cmp_lt_i32_e32 vcc, v212, v184
	v_cmp_ge_i32_e64 s[12:13], v212, v194
	s_and_b64 vcc, vcc, s[12:13]
	v_or_b32_e32 v246, 2, v212
	v_cndmask_b32_e32 v222, v200, v223, vcc
	v_cmp_le_i32_e32 vcc, v246, v184
	v_cmp_gt_i32_e64 s[12:13], v246, v194
	s_and_b64 vcc, vcc, s[12:13]
	v_or_b32_e32 v247, 3, v212
	v_cndmask_b32_e32 v223, v200, v224, vcc
	v_cmp_le_i32_e32 vcc, v247, v184
	v_cmp_gt_i32_e64 s[12:13], v247, v194
	s_and_b64 vcc, vcc, s[12:13]
	v_or_b32_e32 v248, 16, v212
	v_max3_f32 v196, v209, s81, v222
	v_cndmask_b32_e32 v224, v200, v225, vcc
	v_cmp_le_i32_e32 vcc, v248, v184
	v_cmp_gt_i32_e64 s[12:13], v248, v194
	v_max3_f32 v198, v196, v223, v224
	v_mov_b32_e32 v196, s81
	s_and_b64 vcc, vcc, s[12:13]
	v_or_b32_e32 v249, 17, v212
	v_cndmask_b32_e32 v196, v196, v236, vcc
	v_cmp_le_i32_e32 vcc, v249, v184
	v_cmp_gt_i32_e64 s[12:13], v249, v194
	s_and_b64 vcc, vcc, s[12:13]
	v_or_b32_e32 v250, 18, v212
	v_cndmask_b32_e32 v225, v200, v237, vcc
	v_cmp_le_i32_e32 vcc, v250, v184
	v_cmp_gt_i32_e64 s[12:13], v250, v194
	s_and_b64 vcc, vcc, s[12:13]
	v_or_b32_e32 v251, 19, v212
	v_cndmask_b32_e32 v228, v200, v238, vcc
	v_cmp_le_i32_e32 vcc, v251, v184
	v_cmp_gt_i32_e64 s[12:13], v251, v194
	s_and_b64 vcc, vcc, s[12:13]
	v_max3_f32 v198, v198, v196, v225
	v_cndmask_b32_e32 v230, v200, v239, vcc
	v_max3_f32 v198, v198, v228, v230
	v_mov_b32_e32 v207, v198
	s_nop 1
	v_permlane16_swap_b32_e32 v198, v207
	v_max_f32_e32 v198, v198, v207
	v_mov_b32_e32 v207, v198
	s_nop 1
	v_permlane32_swap_b32_e32 v198, v207
	v_max3_f32 v207, v197, v198, v207
	v_cmp_eq_f32_e32 vcc, s81, v207
	v_cmp_gt_i32_e64 s[12:13], v212, v195
	s_nop 0
	v_cndmask_b32_e64 v198, v207, 0, vcc
	v_sub_f32_e32 v197, v197, v198
	v_mul_f32_e32 v197, 0x3e38aa3b, v197
	v_exp_f32_e32 v198, v197
	v_mul_f32_e32 v197, 0x3e38aa3b, v207
	v_cndmask_b32_e64 v236, v197, 0, vcc
	v_fma_f32 v196, v196, s42, -v236
	v_exp_f32_e32 v229, v196
	v_fma_f32 v196, v222, s42, -v236
	v_exp_f32_e32 v231, v196
	v_fma_f32 v196, v225, s42, -v236
	v_exp_f32_e32 v237, v196
	v_fma_f32 v196, v223, s42, -v236
	v_exp_f32_e32 v239, v196
	v_fma_f32 v196, v228, s42, -v236
	v_exp_f32_e32 v241, v196
	v_fma_f32 v196, v224, s42, -v236
	v_exp_f32_e32 v243, v196
	v_fma_f32 v196, v230, s42, -v236
	v_cmp_le_i32_e32 vcc, v212, v185
	v_exp_f32_e32 v245, v196
	v_mov_b32_e32 v196, s81
	s_and_b64 vcc, vcc, s[12:13]
	v_cndmask_b32_e32 v228, v196, v214, vcc
	v_cmp_lt_i32_e32 vcc, v212, v185
	v_cmp_ge_i32_e64 s[12:13], v212, v195
	s_and_b64 vcc, vcc, s[12:13]
	v_cndmask_b32_e32 v215, v200, v215, vcc
	v_cmp_le_i32_e32 vcc, v246, v185
	v_cmp_gt_i32_e64 s[12:13], v246, v195
	s_and_b64 vcc, vcc, s[12:13]
	v_cndmask_b32_e32 v216, v200, v216, vcc
	v_cmp_le_i32_e32 vcc, v247, v185
	v_cmp_gt_i32_e64 s[12:13], v247, v195
	s_and_b64 vcc, vcc, s[12:13]
	v_max3_f32 v196, v228, s81, v215
	v_cndmask_b32_e32 v217, v200, v217, vcc
	v_cmp_le_i32_e32 vcc, v248, v185
	v_cmp_gt_i32_e64 s[12:13], v248, v195
	v_fma_f32 v197, v209, s42, -v236
	v_max3_f32 v209, v196, v216, v217
	v_mov_b32_e32 v196, s81
	s_and_b64 vcc, vcc, s[12:13]
	v_cndmask_b32_e32 v218, v196, v218, vcc
	v_cmp_le_i32_e32 vcc, v249, v185
	v_cmp_gt_i32_e64 s[12:13], v249, v195
	s_and_b64 vcc, vcc, s[12:13]
	v_cndmask_b32_e32 v219, v200, v219, vcc
	v_cmp_le_i32_e32 vcc, v250, v185
	v_cmp_gt_i32_e64 s[12:13], v250, v195
	s_and_b64 vcc, vcc, s[12:13]
	v_cndmask_b32_e32 v220, v200, v220, vcc
	v_cmp_le_i32_e32 vcc, v251, v185
	v_cmp_gt_i32_e64 s[12:13], v251, v195
	s_and_b64 vcc, vcc, s[12:13]
	v_max3_f32 v196, v209, v218, v219
	v_cndmask_b32_e32 v221, v200, v221, vcc
	v_max3_f32 v196, v196, v220, v221
	v_mov_b32_e32 v209, v196
	s_nop 1
	v_permlane16_swap_b32_e32 v196, v209
	v_max_f32_e32 v196, v196, v209
	v_mov_b32_e32 v209, v196
	s_nop 1
	v_permlane32_swap_b32_e32 v196, v209
	v_max3_f32 v209, v199, v196, v209
	v_cmp_eq_f32_e32 vcc, s81, v209
	v_pk_mul_f32 v[144:145], v[144:145], v[198:199] op_sel_hi:[1,0]
	v_pk_mul_f32 v[142:143], v[142:143], v[198:199] op_sel_hi:[1,0]
	v_cndmask_b32_e64 v196, v209, 0, vcc
	v_sub_f32_e32 v196, v199, v196
	v_mul_f32_e32 v196, 0x3e38aa3b, v196
	v_exp_f32_e32 v214, v196
	v_mul_f32_e32 v196, 0x3e38aa3b, v209
	v_pk_mul_f32 v[140:141], v[140:141], v[198:199] op_sel_hi:[1,0]
	v_pk_mul_f32 v[138:139], v[138:139], v[198:199] op_sel_hi:[1,0]
; #define LAS __attribute__((address_space(3)))
; template <int NT, int NKK, int NDT, int MODE, bool MASK> ...
;     ...
;       __builtin_amdgcn_s_setprio(1);
; #pragma unroll
;       for (int t = 0; t < 2; ++t)
; #pragma unroll
;         for (int kk = 0; kk < NKK; ++kk) {
;           const bf16x8 kf = *(LAS const bf16x8*)(Kl + oz + (32 * st + 16 * t + r) * KSTR + (32 * kk + 8 * lg) * 2);
; #pragma unroll
;           for (int jj = 0; jj < JB; ++jj) s[jj][t] = mfma16(kf, qf[jh * JB + jj][kk], kk == 0 ? (f32x4){0.f, 0.f, 0.f, 0.f} : s[jj][t]);
;         }
;       __builtin_amdgcn_s_setprio(0);
;       bf16x8 pf[JB];
;       if (NT > JB) __builtin_amdgcn_sched_barrier(0);
; #pragma unroll
;       for (int jj = 0; jj < JB; ++jj) {
;         const int j = jh * JB + jj;
;         float mx = -INFINITY;
; #pragma unroll
;         for (int t = 0; t < 2; ++t)
; #pragma unroll
;           for (int i = 0; i < 4; ++i) {
;             if (MASK) { const int kp = kpos0 + 32 * st + 16 * t + 4 * lg + i; if (!mask_ok<MODE>(tq[j], kp, W)) s[jj][t][i] = -INFINITY; }
;             mx = fmaxf(mx, s[jj][t][i]);
;           }
;         mx = max_x16_x32(mx);
;         if (NT > 2 || __any(mx > m[j] + 8.0f / c)) {
;           const float mnew = fmaxf(m[j], mx);
;           const float ms2 = (mnew == -INFINITY) ? 0.f : mnew;
;           const float alpha = ex2((m[j] - ms2) * c);
;           m[j] = mnew; l[j] *= alpha;
; #pragma unroll
;           for (int dt = 0; dt < NDT; ++dt) o[j][dt] *= alpha;
;         }
;         const float mc = ((m[j] == -INFINITY) ? 0.f : m[j]) * c;
;         float p0[4], p1[4], ps = 0.f;
; #pragma unroll
;         for (int i = 0; i < 4; ++i) { p0[i] = ex2(s[jj][0][i] * c - mc); p1[i] = ex2(s[jj][1][i] * c - mc); ps += p0[i] + p1[i]; }
;         l[j] += ps;
;         pf[jj] = pack8(p0, p1);
;       }
;       if (NT > JB) __builtin_amdgcn_sched_barrier(0);
;       __builtin_amdgcn_s_setprio(1);
; #pragma unroll
;       for (int dt = 0; dt < NDT; ++dt) {
;         const s16x4 v0 = ds_tr(Vl + oz + (32 * st + 4 * lg + vq) * VSTR + (16 * dt + 4 * vp) * 2);
;         const s16x4 v1 = ds_tr(Vl + oz + (32 * st + 16 + 4 * lg + vq) * VSTR + (16 * dt + 4 * vp) * 2);
;         const bf16x8 vf = (bf16x8){v0[0], v0[1], v0[2], v0[3], v1[0], v1[1], v1[2], v1[3]};
; #pragma unroll
;         for (int jj = 0; jj < JB; ++jj) o[jh * JB + jj][dt] = mfma16(vf, pf[jj], o[jh * JB + jj][dt]);
	v_pk_mul_f32 v[156:157], v[156:157], v[198:199] op_sel_hi:[1,0]
	v_pk_mul_f32 v[154:155], v[154:155], v[198:199] op_sel_hi:[1,0]
	v_pk_mul_f32 v[164:165], v[164:165], v[198:199] op_sel_hi:[1,0]
	v_pk_mul_f32 v[162:163], v[162:163], v[198:199] op_sel_hi:[1,0]
	v_cndmask_b32_e64 v199, v196, 0, vcc
	v_pk_mul_f32 v[112:113], v[112:113], v[214:215] op_sel_hi:[1,0]
	v_pk_mul_f32 v[110:111], v[110:111], v[214:215] op_sel_hi:[1,0]
	v_pk_mul_f32 v[108:109], v[108:109], v[214:215] op_sel_hi:[1,0]
	v_pk_mul_f32 v[106:107], v[106:107], v[214:215] op_sel_hi:[1,0]
	v_pk_mul_f32 v[124:125], v[124:125], v[214:215] op_sel_hi:[1,0]
	v_pk_mul_f32 v[122:123], v[122:123], v[214:215] op_sel_hi:[1,0]
	v_pk_mul_f32 v[132:133], v[132:133], v[214:215] op_sel_hi:[1,0]
	v_pk_mul_f32 v[130:131], v[130:131], v[214:215] op_sel_hi:[1,0]
	v_fma_f32 v215, v215, s42, -v199
	v_fma_f32 v196, v228, s42, -v199
	v_fma_f32 v218, v218, s42, -v199
	v_exp_f32_e32 v230, v215
	v_fma_f32 v215, v219, s42, -v199
	v_exp_f32_e32 v197, v197
	v_exp_f32_e32 v196, v196
	v_exp_f32_e32 v228, v218
	v_exp_f32_e32 v236, v215
	v_fma_f32 v215, v216, s42, -v199
	v_exp_f32_e32 v238, v215
	v_fma_f32 v215, v220, s42, -v199
	v_exp_f32_e32 v240, v215
	v_fma_f32 v215, v217, s42, -v199
	v_fma_f32 v199, v221, s42, -v199
	v_exp_f32_e32 v242, v215
	v_exp_f32_e32 v244, v199
	v_mov_b32_e32 v215, v198
	v_pk_add_f32 v[198:199], v[196:197], v[228:229]
	v_pk_add_f32 v[216:217], v[230:231], v[236:237]
	v_cvt_pk_bf16_f32 v222, v197, v231
	v_pk_add_f32 v[198:199], v[216:217], v[198:199]
	v_pk_add_f32 v[216:217], v[238:239], v[240:241]
	v_cvt_pk_bf16_f32 v223, v239, v243
	v_pk_add_f32 v[198:199], v[216:217], v[198:199]
	v_pk_add_f32 v[216:217], v[242:243], v[244:245]
	v_cvt_pk_bf16_f32 v224, v229, v237
	v_pk_add_f32 v[198:199], v[216:217], v[198:199]
	v_cvt_pk_bf16_f32 v225, v241, v245
	v_pk_fma_f32 v[178:179], v[178:179], v[214:215], v[198:199]
	v_cvt_pk_bf16_f32 v214, v196, v230
	v_cvt_pk_bf16_f32 v215, v238, v242
	v_cvt_pk_bf16_f32 v216, v228, v236
	v_cvt_pk_bf16_f32 v217, v240, v244
	s_setprio 1
	v_add3_u32 v196, v210, v213, v193
	ds_read_b64_tr_b16 v[220:221], v196 offset:11776
	ds_read_b64_tr_b16 v[218:219], v196 offset:9216
	ds_read_b64_tr_b16 v[228:229], v196 offset:9248
	ds_read_b64_tr_b16 v[230:231], v196 offset:11808
	s_waitcnt lgkmcnt(2)
	v_mfma_f32_16x16x32_bf16 v[142:145], v[218:221], v[222:225], v[142:145]
	v_mfma_f32_16x16x32_bf16 v[110:113], v[218:221], v[214:217], v[110:113]
	ds_read_b64_tr_b16 v[218:219], v196 offset:9280
	ds_read_b64_tr_b16 v[220:221], v196 offset:11840
	s_waitcnt lgkmcnt(0)
	v_mfma_f32_16x16x32_bf16 v[154:157], v[218:221], v[222:225], v[154:157]
	v_mfma_f32_16x16x32_bf16 v[122:125], v[218:221], v[214:217], v[122:125]
	ds_read_b64_tr_b16 v[218:219], v196 offset:9312
	ds_read_b64_tr_b16 v[220:221], v196 offset:11872
	v_mfma_f32_16x16x32_bf16 v[138:141], v[228:231], v[222:225], v[138:141]
	v_mfma_f32_16x16x32_bf16 v[106:109], v[228:231], v[214:217], v[106:109]
	s_waitcnt lgkmcnt(0)
	v_mfma_f32_16x16x32_bf16 v[162:165], v[218:221], v[222:225], v[162:165]
	v_mfma_f32_16x16x32_bf16 v[130:133], v[218:221], v[214:217], v[130:133]
	s_setprio 0
	v_mov_b32_e32 v252, 0
	s_setprio 1
	v_add3_u32 v196, v1, v252, v235
	ds_read_b128 v[214:217], v196
	ds_read_b128 v[218:221], v196 offset:64
	s_waitcnt lgkmcnt(1)
	v_mfma_f32_16x16x32_bf16 v[222:225], v[214:217], v[74:77], 0
	v_mfma_f32_16x16x32_bf16 v[214:217], v[214:217], v[82:85], 0
	s_waitcnt lgkmcnt(0)
	v_mfma_f32_16x16x32_bf16 v[222:225], v[218:221], v[78:81], v[222:225]
	v_mfma_f32_16x16x32_bf16 v[214:217], v[218:221], v[86:89], v[214:217]
	ds_read_b128 v[218:221], v196 offset:2304
	ds_read_b128 v[228:231], v196 offset:2368
	s_waitcnt lgkmcnt(1)
	v_mfma_f32_16x16x32_bf16 v[236:239], v[218:221], v[74:77], 0
	v_mfma_f32_16x16x32_bf16 v[218:221], v[218:221], v[82:85], 0
	s_waitcnt lgkmcnt(0)
	v_mfma_f32_16x16x32_bf16 v[236:239], v[228:231], v[78:81], v[236:239]
	v_mfma_f32_16x16x32_bf16 v[218:221], v[228:231], v[86:89], v[218:221]
	s_setprio 0
	v_cmp_le_i32_e32 vcc, v212, v186
	v_cmp_gt_i32_e64 s[12:13], v212, v201
	v_mov_b32_e32 v196, s81
	s_and_b64 vcc, vcc, s[12:13]
	v_cndmask_b32_e32 v197, v196, v222, vcc
	v_cmp_lt_i32_e32 vcc, v212, v186
	v_cmp_ge_i32_e64 s[12:13], v212, v201
	s_and_b64 vcc, vcc, s[12:13]
	v_cndmask_b32_e32 v199, v200, v223, vcc
	v_cmp_le_i32_e32 vcc, v246, v186
	v_cmp_gt_i32_e64 s[12:13], v246, v201
	s_and_b64 vcc, vcc, s[12:13]
	v_cndmask_b32_e32 v222, v200, v224, vcc
	v_cmp_le_i32_e32 vcc, v247, v186
	v_cmp_gt_i32_e64 s[12:13], v247, v201
	s_and_b64 vcc, vcc, s[12:13]
	v_max3_f32 v196, v197, s81, v199
	v_cndmask_b32_e32 v223, v200, v225, vcc
	v_cmp_le_i32_e32 vcc, v248, v186
	v_cmp_gt_i32_e64 s[12:13], v248, v201
	v_max3_f32 v198, v196, v222, v223
	v_mov_b32_e32 v196, s81
	s_and_b64 vcc, vcc, s[12:13]
	v_cndmask_b32_e32 v196, v196, v236, vcc
	v_cmp_le_i32_e32 vcc, v249, v186
	v_cmp_gt_i32_e64 s[12:13], v249, v201
	s_and_b64 vcc, vcc, s[12:13]
	v_cndmask_b32_e32 v224, v200, v237, vcc
	v_cmp_le_i32_e32 vcc, v250, v186
	v_cmp_gt_i32_e64 s[12:13], v250, v201
	s_and_b64 vcc, vcc, s[12:13]
	v_cndmask_b32_e32 v225, v200, v238, vcc
	v_cmp_le_i32_e32 vcc, v251, v186
	v_cmp_gt_i32_e64 s[12:13], v251, v201
	s_and_b64 vcc, vcc, s[12:13]
	v_max3_f32 v198, v198, v196, v224
	v_cndmask_b32_e32 v228, v200, v239, vcc
	v_max3_f32 v198, v198, v225, v228
	v_mov_b32_e32 v213, v198
	s_nop 1
	v_permlane16_swap_b32_e32 v198, v213
	v_max_f32_e32 v198, v198, v213
	v_mov_b32_e32 v213, v198
	s_nop 1
	v_permlane32_swap_b32_e32 v198, v213
	v_max3_f32 v213, v232, v198, v213
	v_cmp_eq_f32_e32 vcc, s81, v213
	v_mul_f32_e32 v229, 0x3e38aa3b, v213
; __device__ __forceinline__ float ex2(float x) { return __builtin_amdgcn_exp2f(x); }
; __device__ __forceinline__ f32x4 mfma16(bf16x8 a, bf16x8 b, f32x4 c) { return __builtin_amdgcn_mfma_f32_16x16x32_bf16(a, b, c, 0, 0, 0); }
; __device__ __forceinline__ s16x4 ds_tr(LAS const unsigned char* p) { return __builtin_bit_cast(s16x4, __builtin_amdgcn_ds_read_tr16_b64_v4i16((LAS v4i16_t*)p)); }
;   __device__ __forceinline__ bf16_t* W() const { return (bf16_t*)(ws + WS_W); }
; template <int NT, int NKK, int NDT, int MODE, bool MASK> ...
;     ...
;       for (int jj = 0; jj < JB; ++jj) {
;         const int j = jh * JB + jj;
;         float mx = -INFINITY;
; #pragma unroll
;         for (int t = 0; t < 2; ++t)
; #pragma unroll
;           for (int i = 0; i < 4; ++i) {
;             if (MASK) { const int kp = kpos0 + 32 * st + 16 * t + 4 * lg + i; if (!mask_ok<MODE>(tq[j], kp, W)) s[jj][t][i] = -INFINITY; }
;             mx = fmaxf(mx, s[jj][t][i]);
;           }
;         mx = max_x16_x32(mx);
;         if (NT > 2 || __any(mx > m[j] + 8.0f / c)) {
;           const float mnew = fmaxf(m[j], mx);
;           const float ms2 = (mnew == -INFINITY) ? 0.f : mnew;
;           const float alpha = ex2((m[j] - ms2) * c);
;           m[j] = mnew; l[j] *= alpha;
; #pragma unroll
;           for (int dt = 0; dt < NDT; ++dt) o[j][dt] *= alpha;
;         }
;         const float mc = ((m[j] == -INFINITY) ? 0.f : m[j]) * c;
;         float p0[4], p1[4], ps = 0.f;
; #pragma unroll
;         for (int i = 0; i < 4; ++i) { p0[i] = ex2(s[jj][0][i] * c - mc); p1[i] = ex2(s[jj][1][i] * c - mc); ps += p0[i] + p1[i]; }
;         l[j] += ps;
;         pf[jj] = pack8(p0, p1);
;       }
;       if (NT > JB) __builtin_amdgcn_sched_barrier(0);
;       __builtin_amdgcn_s_setprio(1);
; #pragma unroll
;       for (int dt = 0; dt < NDT; ++dt) {
;         const s16x4 v0 = ds_tr(Vl + oz + (32 * st + 4 * lg + vq) * VSTR + (16 * dt + 4 * vp) * 2);
;         const s16x4 v1 = ds_tr(Vl + oz + (32 * st + 16 + 4 * lg + vq) * VSTR + (16 * dt + 4 * vp) * 2);
;         const bf16x8 vf = (bf16x8){v0[0], v0[1], v0[2], v0[3], v1[0], v1[1], v1[2], v1[3]};
; #pragma unroll
;         for (int jj = 0; jj < JB; ++jj) o[jh * JB + jj][dt] = mfma16(vf, pf[jj], o[jh * JB + jj][dt]);
;       }
;       __builtin_amdgcn_s_setprio(0);
;       if (NT > JB) __builtin_amdgcn_sched_barrier(0);
	v_cmp_gt_i32_e64 s[12:13], v212, v202
	v_cndmask_b32_e64 v230, v229, 0, vcc
	v_fma_f32 v196, v196, s42, -v230
	v_cndmask_b32_e64 v198, v213, 0, vcc
	v_exp_f32_e32 v229, v196
	v_fma_f32 v196, v199, s42, -v230
	v_sub_f32_e32 v198, v232, v198
	v_exp_f32_e32 v231, v196
	v_fma_f32 v196, v224, s42, -v230
	v_mul_f32_e32 v198, 0x3e38aa3b, v198
	v_exp_f32_e32 v237, v196
	v_fma_f32 v196, v222, s42, -v230
	v_exp_f32_e32 v198, v198
	v_exp_f32_e32 v239, v196
	v_fma_f32 v196, v225, s42, -v230
	v_exp_f32_e32 v241, v196
	v_fma_f32 v196, v223, s42, -v230
	v_exp_f32_e32 v243, v196
	v_fma_f32 v196, v228, s42, -v230
	v_cmp_le_i32_e32 vcc, v212, v187
	v_exp_f32_e32 v245, v196
	v_mov_b32_e32 v196, s81
	s_and_b64 vcc, vcc, s[12:13]
	v_pk_mul_f32 v[152:153], v[152:153], v[198:199] op_sel_hi:[1,0]
	v_pk_mul_f32 v[150:151], v[150:151], v[198:199] op_sel_hi:[1,0]
	v_pk_mul_f32 v[148:149], v[148:149], v[198:199] op_sel_hi:[1,0]
	v_pk_mul_f32 v[146:147], v[146:147], v[198:199] op_sel_hi:[1,0]
	v_pk_mul_f32 v[160:161], v[160:161], v[198:199] op_sel_hi:[1,0]
	v_pk_mul_f32 v[158:159], v[158:159], v[198:199] op_sel_hi:[1,0]
	v_pk_mul_f32 v[168:169], v[168:169], v[198:199] op_sel_hi:[1,0]
	v_pk_mul_f32 v[166:167], v[166:167], v[198:199] op_sel_hi:[1,0]
	v_cndmask_b32_e32 v199, v196, v214, vcc
	v_cmp_lt_i32_e32 vcc, v212, v187
	v_cmp_ge_i32_e64 s[12:13], v212, v202
	s_and_b64 vcc, vcc, s[12:13]
	v_cndmask_b32_e32 v215, v200, v215, vcc
	v_cmp_le_i32_e32 vcc, v246, v187
	v_cmp_gt_i32_e64 s[12:13], v246, v202
	s_and_b64 vcc, vcc, s[12:13]
	v_cndmask_b32_e32 v216, v200, v216, vcc
	v_cmp_le_i32_e32 vcc, v247, v187
	v_cmp_gt_i32_e64 s[12:13], v247, v202
	s_and_b64 vcc, vcc, s[12:13]
	v_max3_f32 v196, v199, s81, v215
	v_cndmask_b32_e32 v217, v200, v217, vcc
	v_cmp_le_i32_e32 vcc, v248, v187
	v_cmp_gt_i32_e64 s[12:13], v248, v202
	v_max3_f32 v212, v196, v216, v217
	v_mov_b32_e32 v196, s81
	s_and_b64 vcc, vcc, s[12:13]
	v_cndmask_b32_e32 v218, v196, v218, vcc
	v_cmp_le_i32_e32 vcc, v249, v187
	v_cmp_gt_i32_e64 s[12:13], v249, v202
	s_and_b64 vcc, vcc, s[12:13]
	v_cndmask_b32_e32 v219, v200, v219, vcc
	v_cmp_le_i32_e32 vcc, v250, v187
	v_cmp_gt_i32_e64 s[12:13], v250, v202
	s_and_b64 vcc, vcc, s[12:13]
	v_cndmask_b32_e32 v220, v200, v220, vcc
	v_cmp_le_i32_e32 vcc, v251, v187
	v_cmp_gt_i32_e64 s[12:13], v251, v202
	s_and_b64 vcc, vcc, s[12:13]
	v_max3_f32 v196, v212, v218, v219
	v_cndmask_b32_e32 v221, v200, v221, vcc
	v_max3_f32 v196, v196, v220, v221
	v_mov_b32_e32 v212, v196
	s_nop 1
	v_permlane16_swap_b32_e32 v196, v212
	v_max_f32_e32 v196, v196, v212
	v_mov_b32_e32 v212, v196
	s_nop 1
	v_permlane32_swap_b32_e32 v196, v212
	v_max3_f32 v212, v211, v196, v212
	v_cmp_eq_f32_e32 vcc, s81, v212
	v_fma_f32 v197, v197, s42, -v230
	v_exp_f32_e32 v197, v197
	v_cndmask_b32_e64 v196, v212, 0, vcc
	v_sub_f32_e32 v196, v211, v196
	v_mul_f32_e32 v196, 0x3e38aa3b, v196
	v_exp_f32_e32 v214, v196
	v_mul_f32_e32 v196, 0x3e38aa3b, v212
	v_cndmask_b32_e64 v211, v196, 0, vcc
	v_fma_f32 v196, v199, s42, -v211
	v_fma_f32 v199, v218, s42, -v211
	v_exp_f32_e32 v228, v199
	v_fma_f32 v199, v215, s42, -v211
	v_exp_f32_e32 v230, v199
	v_fma_f32 v199, v219, s42, -v211
	v_exp_f32_e32 v236, v199
	v_fma_f32 v199, v216, s42, -v211
	v_exp_f32_e32 v196, v196
	v_exp_f32_e32 v238, v199
	v_fma_f32 v199, v220, s42, -v211
	v_exp_f32_e32 v240, v199
	v_fma_f32 v199, v217, s42, -v211
	v_exp_f32_e32 v242, v199
	v_fma_f32 v199, v221, s42, -v211
	v_exp_f32_e32 v244, v199
	v_pk_mul_f32 v[120:121], v[120:121], v[214:215] op_sel_hi:[1,0]
	v_pk_mul_f32 v[118:119], v[118:119], v[214:215] op_sel_hi:[1,0]
	v_pk_mul_f32 v[116:117], v[116:117], v[214:215] op_sel_hi:[1,0]
	v_pk_mul_f32 v[114:115], v[114:115], v[214:215] op_sel_hi:[1,0]
	v_pk_mul_f32 v[128:129], v[128:129], v[214:215] op_sel_hi:[1,0]
	v_pk_mul_f32 v[126:127], v[126:127], v[214:215] op_sel_hi:[1,0]
	v_pk_mul_f32 v[136:137], v[136:137], v[214:215] op_sel_hi:[1,0]
	v_pk_mul_f32 v[134:135], v[134:135], v[214:215] op_sel_hi:[1,0]
	v_mov_b32_e32 v215, v198
	v_pk_add_f32 v[198:199], v[196:197], v[228:229]
	v_pk_add_f32 v[216:217], v[230:231], v[236:237]
	v_cvt_pk_bf16_f32 v222, v197, v231
	v_pk_add_f32 v[198:199], v[216:217], v[198:199]
	v_pk_add_f32 v[216:217], v[238:239], v[240:241]
	v_cvt_pk_bf16_f32 v223, v239, v243
	v_pk_add_f32 v[198:199], v[216:217], v[198:199]
	v_pk_add_f32 v[216:217], v[242:243], v[244:245]
	v_cvt_pk_bf16_f32 v224, v229, v237
	v_pk_add_f32 v[198:199], v[216:217], v[198:199]
	v_cvt_pk_bf16_f32 v225, v241, v245
	v_pk_fma_f32 v[180:181], v[180:181], v[214:215], v[198:199]
	v_cvt_pk_bf16_f32 v214, v196, v230
	v_cvt_pk_bf16_f32 v215, v238, v242
	v_cvt_pk_bf16_f32 v216, v228, v236
	v_cvt_pk_bf16_f32 v217, v240, v244
	s_setprio 1
	v_add3_u32 v196, v210, v252, v193
	ds_read_b64_tr_b16 v[220:221], v196 offset:11776
	ds_read_b64_tr_b16 v[218:219], v196 offset:9216
	ds_read_b64_tr_b16 v[228:229], v196 offset:9248
	ds_read_b64_tr_b16 v[230:231], v196 offset:11808
	s_waitcnt lgkmcnt(2)
	v_mfma_f32_16x16x32_bf16 v[150:153], v[218:221], v[222:225], v[150:153]
	v_mfma_f32_16x16x32_bf16 v[118:121], v[218:221], v[214:217], v[118:121]
	ds_read_b64_tr_b16 v[218:219], v196 offset:9280
	ds_read_b64_tr_b16 v[220:221], v196 offset:11840
	s_waitcnt lgkmcnt(0)
	v_mfma_f32_16x16x32_bf16 v[158:161], v[218:221], v[222:225], v[158:161]
	v_mfma_f32_16x16x32_bf16 v[126:129], v[218:221], v[214:217], v[126:129]
	ds_read_b64_tr_b16 v[218:219], v196 offset:9312
	ds_read_b64_tr_b16 v[220:221], v196 offset:11872
	v_mfma_f32_16x16x32_bf16 v[146:149], v[228:231], v[222:225], v[146:149]
	v_mfma_f32_16x16x32_bf16 v[114:117], v[228:231], v[214:217], v[114:117]
	s_waitcnt lgkmcnt(0)
	v_mfma_f32_16x16x32_bf16 v[166:169], v[218:221], v[222:225], v[166:169]
	v_mfma_f32_16x16x32_bf16 v[134:137], v[218:221], v[214:217], v[134:137]
	s_setprio 0
	s_mov_b32 s8, 32
	s_and_b64 vcc, exec, s[52:53]
	s_mov_b64 s[52:53], 0
	s_cbranch_vccnz .LBB0_1199
	s_mov_b64 s[12:13], 0

; #define LAS __attribute__((address_space(3)))
; template <int NT, int NKK, int NDT, int MODE, bool MASK> ...
;     ...
;       __builtin_amdgcn_s_setprio(1);
; #pragma unroll
;       for (int t = 0; t < 2; ++t)
; #pragma unroll
;         for (int kk = 0; kk < NKK; ++kk) {
;           const bf16x8 kf = *(LAS const bf16x8*)(Kl + oz + (32 * st + 16 * t + r) * KSTR + (32 * kk + 8 * lg) * 2);
; #pragma unroll
;           for (int jj = 0; jj < JB; ++jj) s[jj][t] = mfma16(kf, qf[jh * JB + jj][kk], kk == 0 ? (f32x4){0.f, 0.f, 0.f, 0.f} : s[jj][t]);
;         }
;       __builtin_amdgcn_s_setprio(0);
;       bf16x8 pf[JB];
;       if (NT > JB) __builtin_amdgcn_sched_barrier(0);
; #pragma unroll
;       for (int jj = 0; jj < JB; ++jj) {
;         const int j = jh * JB + jj;
;         float mx = -INFINITY;
; #pragma unroll
;         for (int t = 0; t < 2; ++t)
; #pragma unroll
;           for (int i = 0; i < 4; ++i) {
;             if (MASK) { const int kp = kpos0 + 32 * st + 16 * t + 4 * lg + i; if (!mask_ok<MODE>(tq[j], kp, W)) s[jj][t][i] = -INFINITY; }
;             mx = fmaxf(mx, s[jj][t][i]);
;           }
;         mx = max_x16_x32(mx);
;         if (NT > 2 || __any(mx > m[j] + 8.0f / c)) {
;           const float mnew = fmaxf(m[j], mx);
;           const float ms2 = (mnew == -INFINITY) ? 0.f : mnew;
;           const float alpha = ex2((m[j] - ms2) * c);
;           m[j] = mnew; l[j] *= alpha;
; #pragma unroll
;           for (int dt = 0; dt < NDT; ++dt) o[j][dt] *= alpha;
;         }
;         const float mc = ((m[j] == -INFINITY) ? 0.f : m[j]) * c;
;         float p0[4], p1[4], ps = 0.f;
; #pragma unroll
;         for (int i = 0; i < 4; ++i) { p0[i] = ex2(s[jj][0][i] * c - mc); p1[i] = ex2(s[jj][1][i] * c - mc); ps += p0[i] + p1[i]; }
;         l[j] += ps;
;         pf[jj] = pack8(p0, p1);
;       }
;       if (NT > JB) __builtin_amdgcn_sched_barrier(0);
;       __builtin_amdgcn_s_setprio(1);
; #pragma unroll
;       for (int dt = 0; dt < NDT; ++dt) {
;         const s16x4 v0 = ds_tr(Vl + oz + (32 * st + 4 * lg + vq) * VSTR + (16 * dt + 4 * vp) * 2);
;         const s16x4 v1 = ds_tr(Vl + oz + (32 * st + 16 + 4 * lg + vq) * VSTR + (16 * dt + 4 * vp) * 2);
;         const bf16x8 vf = (bf16x8){v0[0], v0[1], v0[2], v0[3], v1[0], v1[1], v1[2], v1[3]};
; #pragma unroll
;         for (int jj = 0; jj < JB; ++jj) o[jh * JB + jj][dt] = mfma16(vf, pf[jj], o[jh * JB + jj][dt]);
.LBB0_1203:
	v_or_b32_e32 v106, s8, v191
	v_mov_b32_e32 v109, s75
	v_mov_b32_e32 v142, 0
	v_mov_b32_e32 v107, v203
	v_mov_b32_e32 v128, v204
	v_mov_b32_e32 v140, v205
	v_mov_b32_e32 v141, v206
	v_or_b32_e32 v108, s8, v189
	v_mad_u32_u24 v106, v106, s80, v109
	s_setprio 1
	v_mul_u32_u24_e32 v143, 0x90, v108
	v_add3_u32 v120, v1, v142, v143
	ds_read_b128 v[108:111], v120
	ds_read_b128 v[112:115], v120 offset:64
	s_waitcnt lgkmcnt(1)
	v_mfma_f32_16x16x32_bf16 v[116:119], v[108:111], v[54:57], 0
	v_mfma_f32_16x16x32_bf16 v[108:111], v[108:111], v[62:65], 0
	s_waitcnt lgkmcnt(0)
	v_mfma_f32_16x16x32_bf16 v[116:119], v[112:115], v[58:61], v[116:119]
	v_mfma_f32_16x16x32_bf16 v[108:111], v[112:115], v[66:69], v[108:111]
	ds_read_b128 v[112:115], v120 offset:2304
	ds_read_b128 v[120:123], v120 offset:2368
	s_waitcnt lgkmcnt(1)
	v_mfma_f32_16x16x32_bf16 v[124:127], v[112:115], v[54:57], 0
	v_mfma_f32_16x16x32_bf16 v[112:115], v[112:115], v[62:65], 0
	s_waitcnt lgkmcnt(0)
	v_mfma_f32_16x16x32_bf16 v[124:127], v[120:123], v[58:61], v[124:127]
	v_mfma_f32_16x16x32_bf16 v[112:115], v[120:123], v[66:69], v[112:115]
	s_setprio 0
	v_max3_f32 v120, v116, s81, v117
	v_max3_f32 v120, v120, v118, v119
	s_nop 3
	v_max3_f32 v120, v120, v124, v125
	v_max3_f32 v120, v120, v126, v127
	v_mov_b32_e32 v121, v120
	s_nop 1
	v_permlane16_swap_b32_e32 v120, v121
	v_max_f32_e32 v120, v120, v121
	v_mov_b32_e32 v121, v120
	s_nop 1
	v_permlane32_swap_b32_e32 v120, v121
	v_max3_f32 v203, v107, v120, v121
	v_cmp_eq_f32_e32 vcc, s81, v203
	s_nop 1
	v_cndmask_b32_e64 v120, v203, 0, vcc
	v_sub_f32_e32 v107, v107, v120
	v_mul_f32_e32 v107, 0x3e38aa3b, v107
	v_exp_f32_e32 v120, v107
	v_mul_f32_e32 v107, 0x3e38aa3b, v203
	v_cndmask_b32_e64 v107, v107, 0, vcc
	v_fma_f32 v116, v116, s42, -v107
	v_exp_f32_e32 v123, v116
	v_fma_f32 v116, v124, s42, -v107
	v_exp_f32_e32 v129, v116
	v_fma_f32 v116, v117, s42, -v107
	v_exp_f32_e32 v131, v116
	v_fma_f32 v116, v125, s42, -v107
	v_exp_f32_e32 v125, v116
	v_fma_f32 v116, v118, s42, -v107
	v_exp_f32_e32 v133, v116
	v_fma_f32 v116, v126, s42, -v107
	v_exp_f32_e32 v135, v116
	v_fma_f32 v116, v119, s42, -v107
	v_fma_f32 v107, v127, s42, -v107
	v_exp_f32_e32 v127, v107
	v_max3_f32 v107, v108, s81, v109
	v_max3_f32 v107, v107, v110, v111
	v_max3_f32 v107, v107, v112, v113
	v_max3_f32 v107, v107, v114, v115
	v_mov_b32_e32 v117, v107
	s_nop 1
	v_permlane16_swap_b32_e32 v107, v117
	v_max_f32_e32 v107, v107, v117
	v_mov_b32_e32 v117, v107
	s_nop 1
	v_permlane32_swap_b32_e32 v107, v117
	v_max3_f32 v204, v128, v107, v117
	v_cmp_eq_f32_e32 vcc, s81, v204
	v_exp_f32_e32 v137, v116
	v_pk_mul_f32 v[104:105], v[104:105], v[120:121] op_sel_hi:[1,0]
	v_cndmask_b32_e64 v107, v204, 0, vcc
	v_sub_f32_e32 v107, v128, v107
	v_mul_f32_e32 v107, 0x3e38aa3b, v107
	v_exp_f32_e32 v138, v107
	v_mul_f32_e32 v107, 0x3e38aa3b, v204
	v_cndmask_b32_e64 v107, v107, 0, vcc
	v_fma_f32 v108, v108, s42, -v107
	v_exp_f32_e32 v122, v108
	v_fma_f32 v108, v112, s42, -v107
	v_exp_f32_e32 v128, v108
	v_fma_f32 v108, v109, s42, -v107
	v_exp_f32_e32 v130, v108
	v_fma_f32 v108, v113, s42, -v107
	v_exp_f32_e32 v124, v108
	v_fma_f32 v108, v110, s42, -v107
	v_exp_f32_e32 v132, v108
	v_fma_f32 v108, v114, s42, -v107
	v_exp_f32_e32 v134, v108
	v_fma_f32 v108, v111, s42, -v107
	v_fma_f32 v107, v115, s42, -v107
	v_exp_f32_e32 v136, v108
	v_exp_f32_e32 v126, v107
	v_pk_add_f32 v[108:109], v[122:123], v[128:129]
	v_pk_add_f32 v[110:111], v[130:131], v[124:125]
	v_pk_mul_f32 v[48:49], v[48:49], v[138:139] op_sel_hi:[1,0]
	v_pk_add_f32 v[108:109], v[110:111], v[108:109]
	v_pk_add_f32 v[110:111], v[132:133], v[134:135]
	v_pk_mul_f32 v[46:47], v[46:47], v[138:139] op_sel_hi:[1,0]
	v_pk_add_f32 v[108:109], v[110:111], v[108:109]
	v_pk_add_f32 v[110:111], v[136:137], v[126:127]
	v_pk_mul_f32 v[44:45], v[44:45], v[138:139] op_sel_hi:[1,0]
	v_pk_mul_f32 v[42:43], v[42:43], v[138:139] op_sel_hi:[1,0]
	v_pk_mul_f32 v[40:41], v[40:41], v[138:139] op_sel_hi:[1,0]
	v_pk_mul_f32 v[38:39], v[38:39], v[138:139] op_sel_hi:[1,0]
	v_pk_mul_f32 v[36:37], v[36:37], v[138:139] op_sel_hi:[1,0]
	v_pk_mul_f32 v[34:35], v[34:35], v[138:139] op_sel_hi:[1,0]
	v_mov_b32_e32 v139, v120
	v_pk_add_f32 v[108:109], v[110:111], v[108:109]
	v_pk_mul_f32 v[102:103], v[102:103], v[120:121] op_sel_hi:[1,0]
	v_pk_mul_f32 v[92:93], v[92:93], v[120:121] op_sel_hi:[1,0]
	v_pk_mul_f32 v[90:91], v[90:91], v[120:121] op_sel_hi:[1,0]
	v_pk_mul_f32 v[72:73], v[72:73], v[120:121] op_sel_hi:[1,0]
	v_pk_mul_f32 v[70:71], v[70:71], v[120:121] op_sel_hi:[1,0]
	v_pk_mul_f32 v[52:53], v[52:53], v[120:121] op_sel_hi:[1,0]
	v_pk_mul_f32 v[50:51], v[50:51], v[120:121] op_sel_hi:[1,0]
	v_pk_fma_f32 v[172:173], v[172:173], v[138:139], v[108:109]
	v_cvt_pk_bf16_f32 v116, v123, v131
	v_cvt_pk_bf16_f32 v117, v133, v137
	v_cvt_pk_bf16_f32 v118, v129, v125
	v_cvt_pk_bf16_f32 v119, v135, v127
	v_cvt_pk_bf16_f32 v108, v122, v130
	v_cvt_pk_bf16_f32 v109, v132, v136
	v_cvt_pk_bf16_f32 v110, v128, v124
	v_cvt_pk_bf16_f32 v111, v134, v126
	s_setprio 1
	v_add3_u32 v107, v106, v142, v193
	ds_read_b64_tr_b16 v[114:115], v107 offset:11776
	ds_read_b64_tr_b16 v[112:113], v107 offset:9216
	ds_read_b64_tr_b16 v[120:121], v107 offset:9248
	ds_read_b64_tr_b16 v[122:123], v107 offset:11808
	s_waitcnt lgkmcnt(2)
	v_mfma_f32_16x16x32_bf16 v[102:105], v[112:115], v[116:119], v[102:105]
	v_mfma_f32_16x16x32_bf16 v[46:49], v[112:115], v[108:111], v[46:49]
	ds_read_b64_tr_b16 v[112:113], v107 offset:9280
	ds_read_b64_tr_b16 v[114:115], v107 offset:11840
	s_waitcnt lgkmcnt(0)
; template <int NT, int NKK, int NDT, int MODE, bool MASK> ...
;     ...
;       __builtin_amdgcn_s_setprio(1);
; #pragma unroll
;       for (int t = 0; t < 2; ++t)
; #pragma unroll
;         for (int kk = 0; kk < NKK; ++kk) {
;           const bf16x8 kf = *(LAS const bf16x8*)(Kl + oz + (32 * st + 16 * t + r) * KSTR + (32 * kk + 8 * lg) * 2);
; #pragma unroll
;           for (int jj = 0; jj < JB; ++jj) s[jj][t] = mfma16(kf, qf[jh * JB + jj][kk], kk == 0 ? (f32x4){0.f, 0.f, 0.f, 0.f} : s[jj][t]);
;         }
;       __builtin_amdgcn_s_setprio(0);
;       bf16x8 pf[JB];
;       if (NT > JB) __builtin_amdgcn_sched_barrier(0);
; #pragma unroll
;       for (int jj = 0; jj < JB; ++jj) {
;         const int j = jh * JB + jj;
;         float mx = -INFINITY;
; #pragma unroll
;         for (int t = 0; t < 2; ++t)
; #pragma unroll
;           for (int i = 0; i < 4; ++i) {
;             if (MASK) { const int kp = kpos0 + 32 * st + 16 * t + 4 * lg + i; if (!mask_ok<MODE>(tq[j], kp, W)) s[jj][t][i] = -INFINITY; }
;             mx = fmaxf(mx, s[jj][t][i]);
;           }
;         mx = max_x16_x32(mx);
;         if (NT > 2 || __any(mx > m[j] + 8.0f / c)) {
;           const float mnew = fmaxf(m[j], mx);
;           const float ms2 = (mnew == -INFINITY) ? 0.f : mnew;
;           const float alpha = ex2((m[j] - ms2) * c);
;           m[j] = mnew; l[j] *= alpha;
; #pragma unroll
;           for (int dt = 0; dt < NDT; ++dt) o[j][dt] *= alpha;
;         }
;         const float mc = ((m[j] == -INFINITY) ? 0.f : m[j]) * c;
;         float p0[4], p1[4], ps = 0.f;
; #pragma unroll
;         for (int i = 0; i < 4; ++i) { p0[i] = ex2(s[jj][0][i] * c - mc); p1[i] = ex2(s[jj][1][i] * c - mc); ps += p0[i] + p1[i]; }
;         l[j] += ps;
;         pf[jj] = pack8(p0, p1);
;       }
;       if (NT > JB) __builtin_amdgcn_sched_barrier(0);
;       __builtin_amdgcn_s_setprio(1);
; #pragma unroll
;       for (int dt = 0; dt < NDT; ++dt) {
;         const s16x4 v0 = ds_tr(Vl + oz + (32 * st + 4 * lg + vq) * VSTR + (16 * dt + 4 * vp) * 2);
;         const s16x4 v1 = ds_tr(Vl + oz + (32 * st + 16 + 4 * lg + vq) * VSTR + (16 * dt + 4 * vp) * 2);
;         const bf16x8 vf = (bf16x8){v0[0], v0[1], v0[2], v0[3], v1[0], v1[1], v1[2], v1[3]};
; #pragma unroll
;         for (int jj = 0; jj < JB; ++jj) o[jh * JB + jj][dt] = mfma16(vf, pf[jj], o[jh * JB + jj][dt]);
;       }
;       __builtin_amdgcn_s_setprio(0);
	v_mfma_f32_16x16x32_bf16 v[70:73], v[112:115], v[116:119], v[70:73]
	v_mfma_f32_16x16x32_bf16 v[38:41], v[112:115], v[108:111], v[38:41]
	ds_read_b64_tr_b16 v[112:113], v107 offset:9312
	ds_read_b64_tr_b16 v[114:115], v107 offset:11872
	v_mfma_f32_16x16x32_bf16 v[90:93], v[120:123], v[116:119], v[90:93]
	v_mfma_f32_16x16x32_bf16 v[42:45], v[120:123], v[108:111], v[42:45]
	s_waitcnt lgkmcnt(0)
	v_mfma_f32_16x16x32_bf16 v[50:53], v[112:115], v[116:119], v[50:53]
	v_mfma_f32_16x16x32_bf16 v[34:37], v[112:115], v[108:111], v[34:37]
	s_setprio 0
	v_mov_b32_e32 v107, 0
	s_setprio 1
	v_add3_u32 v120, v1, v107, v143
	ds_read_b128 v[108:111], v120
	ds_read_b128 v[112:115], v120 offset:64
	s_waitcnt lgkmcnt(1)
	v_mfma_f32_16x16x32_bf16 v[116:119], v[108:111], v[74:77], 0
	v_mfma_f32_16x16x32_bf16 v[108:111], v[108:111], v[82:85], 0
	s_waitcnt lgkmcnt(0)
	v_mfma_f32_16x16x32_bf16 v[116:119], v[112:115], v[78:81], v[116:119]
	v_mfma_f32_16x16x32_bf16 v[108:111], v[112:115], v[86:89], v[108:111]
	ds_read_b128 v[112:115], v120 offset:2304
	ds_read_b128 v[120:123], v120 offset:2368
	s_waitcnt lgkmcnt(1)
	v_mfma_f32_16x16x32_bf16 v[124:127], v[112:115], v[74:77], 0
	v_mfma_f32_16x16x32_bf16 v[112:115], v[112:115], v[82:85], 0
	s_waitcnt lgkmcnt(0)
	v_mfma_f32_16x16x32_bf16 v[124:127], v[120:123], v[78:81], v[124:127]
	v_mfma_f32_16x16x32_bf16 v[112:115], v[120:123], v[86:89], v[112:115]
	s_setprio 0
	v_max3_f32 v120, v116, s81, v117
	v_max3_f32 v120, v120, v118, v119
	s_nop 3
	v_max3_f32 v120, v120, v124, v125
	v_max3_f32 v120, v120, v126, v127
	v_mov_b32_e32 v121, v120
	s_nop 1
	v_permlane16_swap_b32_e32 v120, v121
	v_max_f32_e32 v120, v120, v121
	v_mov_b32_e32 v121, v120
	s_nop 1
	v_permlane32_swap_b32_e32 v120, v121
	v_max3_f32 v205, v140, v120, v121
	v_cmp_eq_f32_e32 vcc, s81, v205
	s_nop 1
	v_cndmask_b32_e64 v120, v205, 0, vcc
	v_sub_f32_e32 v120, v140, v120
	v_mul_f32_e32 v120, 0x3e38aa3b, v120
	v_exp_f32_e32 v120, v120
	s_nop 0
	v_pk_mul_f32 v[32:33], v[32:33], v[120:121] op_sel_hi:[1,0]
	v_pk_mul_f32 v[30:31], v[30:31], v[120:121] op_sel_hi:[1,0]
	v_pk_mul_f32 v[28:29], v[28:29], v[120:121] op_sel_hi:[1,0]
	v_pk_mul_f32 v[26:27], v[26:27], v[120:121] op_sel_hi:[1,0]
	v_pk_mul_f32 v[20:21], v[20:21], v[120:121] op_sel_hi:[1,0]
	v_pk_mul_f32 v[18:19], v[18:19], v[120:121] op_sel_hi:[1,0]
	v_pk_mul_f32 v[24:25], v[24:25], v[120:121] op_sel_hi:[1,0]
	v_pk_mul_f32 v[22:23], v[22:23], v[120:121] op_sel_hi:[1,0]
	v_mul_f32_e32 v121, 0x3e38aa3b, v205
	v_cndmask_b32_e64 v121, v121, 0, vcc
	v_fma_f32 v116, v116, s42, -v121
	v_exp_f32_e32 v123, v116
	v_fma_f32 v116, v124, s42, -v121
	v_exp_f32_e32 v129, v116
	v_fma_f32 v116, v117, s42, -v121
	v_max3_f32 v117, v108, s81, v109
	v_max3_f32 v117, v117, v110, v111
	v_max3_f32 v117, v117, v112, v113
	v_exp_f32_e32 v131, v116
	v_fma_f32 v116, v125, s42, -v121
	v_max3_f32 v117, v117, v114, v115
	v_exp_f32_e32 v125, v116
	v_fma_f32 v116, v118, s42, -v121
	v_mov_b32_e32 v118, v117
	s_nop 1
	v_permlane16_swap_b32_e32 v117, v118
	v_max_f32_e32 v117, v117, v118
	v_mov_b32_e32 v118, v117
	v_exp_f32_e32 v133, v116
	v_fma_f32 v116, v126, s42, -v121
	v_permlane32_swap_b32_e32 v117, v118
	v_exp_f32_e32 v135, v116
	v_fma_f32 v116, v119, s42, -v121
	v_max3_f32 v206, v141, v117, v118
	v_exp_f32_e32 v137, v116
	v_fma_f32 v116, v127, s42, -v121
	v_cmp_eq_f32_e32 vcc, s81, v206
	v_mul_f32_e32 v121, 0x3e38aa3b, v206
	v_exp_f32_e32 v127, v116
	v_cndmask_b32_e64 v121, v121, 0, vcc
	v_fma_f32 v108, v108, s42, -v121
	v_exp_f32_e32 v122, v108
	v_fma_f32 v108, v112, s42, -v121
	v_exp_f32_e32 v128, v108
	v_fma_f32 v108, v109, s42, -v121
	v_exp_f32_e32 v130, v108
	v_fma_f32 v108, v113, s42, -v121
	v_exp_f32_e32 v124, v108
	v_fma_f32 v108, v110, s42, -v121
	v_exp_f32_e32 v132, v108
	v_fma_f32 v108, v114, s42, -v121
	v_cndmask_b32_e64 v117, v206, 0, vcc
	v_exp_f32_e32 v134, v108
	v_fma_f32 v108, v111, s42, -v121
	v_sub_f32_e32 v117, v141, v117
	v_exp_f32_e32 v136, v108
	v_fma_f32 v108, v115, s42, -v121
	v_mul_f32_e32 v117, 0x3e38aa3b, v117
	v_exp_f32_e32 v126, v108
	v_exp_f32_e32 v138, v117
	v_pk_add_f32 v[108:109], v[122:123], v[128:129]
	v_pk_add_f32 v[110:111], v[130:131], v[124:125]
	v_pk_mul_f32 v[16:17], v[16:17], v[138:139] op_sel_hi:[1,0]
	v_pk_add_f32 v[108:109], v[110:111], v[108:109]
	v_pk_add_f32 v[110:111], v[132:133], v[134:135]
	v_pk_mul_f32 v[14:15], v[14:15], v[138:139] op_sel_hi:[1,0]
	v_pk_add_f32 v[108:109], v[110:111], v[108:109]
	v_pk_add_f32 v[110:111], v[136:137], v[126:127]
	v_pk_mul_f32 v[12:13], v[12:13], v[138:139] op_sel_hi:[1,0]
	v_pk_mul_f32 v[10:11], v[10:11], v[138:139] op_sel_hi:[1,0]
	v_pk_mul_f32 v[8:9], v[8:9], v[138:139] op_sel_hi:[1,0]
	v_pk_mul_f32 v[6:7], v[6:7], v[138:139] op_sel_hi:[1,0]
	v_pk_mul_f32 v[4:5], v[4:5], v[138:139] op_sel_hi:[1,0]
	v_pk_mul_f32 v[2:3], v[2:3], v[138:139] op_sel_hi:[1,0]
	v_mov_b32_e32 v139, v120
	v_pk_add_f32 v[108:109], v[110:111], v[108:109]
	v_cvt_pk_bf16_f32 v116, v123, v131
	v_pk_fma_f32 v[170:171], v[170:171], v[138:139], v[108:109]
	v_cvt_pk_bf16_f32 v117, v133, v137
	v_cvt_pk_bf16_f32 v118, v129, v125
	v_cvt_pk_bf16_f32 v119, v135, v127
	v_cvt_pk_bf16_f32 v108, v122, v130
	v_cvt_pk_bf16_f32 v109, v132, v136
	v_cvt_pk_bf16_f32 v110, v128, v124
	v_cvt_pk_bf16_f32 v111, v134, v126
	s_setprio 1
	v_add3_u32 v106, v106, v107, v193
	ds_read_b64_tr_b16 v[114:115], v106 offset:11776
	ds_read_b64_tr_b16 v[112:113], v106 offset:9216
	ds_read_b64_tr_b16 v[120:121], v106 offset:9248
	ds_read_b64_tr_b16 v[122:123], v106 offset:11808
	s_waitcnt lgkmcnt(2)
	v_mfma_f32_16x16x32_bf16 v[30:33], v[112:115], v[116:119], v[30:33]
	v_mfma_f32_16x16x32_bf16 v[14:17], v[112:115], v[108:111], v[14:17]
	ds_read_b64_tr_b16 v[112:113], v106 offset:9280
	ds_read_b64_tr_b16 v[114:115], v106 offset:11840
	s_waitcnt lgkmcnt(0)
	v_mfma_f32_16x16x32_bf16 v[18:21], v[112:115], v[116:119], v[18:21]
	v_mfma_f32_16x16x32_bf16 v[6:9], v[112:115], v[108:111], v[6:9]
	ds_read_b64_tr_b16 v[112:113], v106 offset:9312
	ds_read_b64_tr_b16 v[114:115], v106 offset:11872
	v_mfma_f32_16x16x32_bf16 v[26:29], v[120:123], v[116:119], v[26:29]
	v_mfma_f32_16x16x32_bf16 v[10:13], v[120:123], v[108:111], v[10:13]
	s_waitcnt lgkmcnt(0)
	v_mfma_f32_16x16x32_bf16 v[22:25], v[112:115], v[116:119], v[22:25]
	v_mfma_f32_16x16x32_bf16 v[2:5], v[112:115], v[108:111], v[2:5]
	s_setprio 0
	s_mov_b32 s8, 32
	s_andn2_b64 vcc, exec, s[12:13]
	s_mov_b64 s[12:13], 0
	s_cbranch_vccz .LBB0_1203
; #define LAS __attribute__((address_space(3)))
; template <int NT, int NKK, int NDT, int MODE, bool MASK> ...
;     ...
; #pragma unroll 1
;   for (int st = 0; st < 2; ++st) {
; #pragma unroll
;     for (int jh = 0; jh < NT / JB; ++jh) {
;       int oz = 0; if (NT > JB) asm volatile("" : "+v"(oz));
;       f32x4 s[JB][2];
;       __builtin_amdgcn_s_setprio(1);
; #pragma unroll
;       for (int t = 0; t < 2; ++t)
; #pragma unroll
;         for (int kk = 0; kk < NKK; ++kk) {
;           const bf16x8 kf = *(LAS const bf16x8*)(Kl + oz + (32 * st + 16 * t + r) * KSTR + (32 * kk + 8 * lg) * 2);
; #pragma unroll
;           for (int jj = 0; jj < JB; ++jj) s[jj][t] = mfma16(kf, qf[jh * JB + jj][kk], kk == 0 ? (f32x4){0.f, 0.f, 0.f, 0.f} : s[jj][t]);
;         }
;       __builtin_amdgcn_s_setprio(0);
;       bf16x8 pf[JB];
;       if (NT > JB) __builtin_amdgcn_sched_barrier(0);
; #pragma unroll
;       for (int jj = 0; jj < JB; ++jj) {
;         const int j = jh * JB + jj;
;         float mx = -INFINITY;
; #pragma unroll
;         for (int t = 0; t < 2; ++t)
; #pragma unroll
;           for (int i = 0; i < 4; ++i) {
;             if (MASK) { const int kp = kpos0 + 32 * st + 16 * t + 4 * lg + i; if (!mask_ok<MODE>(tq[j], kp, W)) s[jj][t][i] = -INFINITY; }
;             mx = fmaxf(mx, s[jj][t][i]);
;           }
;         mx = max_x16_x32(mx);
;         if (NT > 2 || __any(mx > m[j] + 8.0f / c)) {
;           const float mnew = fmaxf(m[j], mx);
;           const float ms2 = (mnew == -INFINITY) ? 0.f : mnew;
;           const float alpha = ex2((m[j] - ms2) * c);
;           m[j] = mnew; l[j] *= alpha;
; #pragma unroll
;           for (int dt = 0; dt < NDT; ++dt) o[j][dt] *= alpha;
;         }
;         const float mc = ((m[j] == -INFINITY) ? 0.f : m[j]) * c;
;         float p0[4], p1[4], ps = 0.f;
; #pragma unroll
;         for (int i = 0; i < 4; ++i) { p0[i] = ex2(s[jj][0][i] * c - mc); p1[i] = ex2(s[jj][1][i] * c - mc); ps += p0[i] + p1[i]; }
;         l[j] += ps;
;         pf[jj] = pack8(p0, p1);
;       }
;       if (NT > JB) __builtin_amdgcn_sched_barrier(0);
;       __builtin_amdgcn_s_setprio(1);
; #pragma unroll
;       for (int dt = 0; dt < NDT; ++dt) {
;         const s16x4 v0 = ds_tr(Vl + oz + (32 * st + 4 * lg + vq) * VSTR + (16 * dt + 4 * vp) * 2);
;         const s16x4 v1 = ds_tr(Vl + oz + (32 * st + 16 + 4 * lg + vq) * VSTR + (16 * dt + 4 * vp) * 2);
	s_branch .Lrt_skip_1
	v_mov_b64_e32 v[144:145], v[104:105]
	v_mov_b64_e32 v[140:141], v[92:93]
	v_mov_b64_e32 v[156:157], v[72:73]
	v_mov_b64_e32 v[164:165], v[52:53]
	v_mov_b64_e32 v[112:113], v[48:49]
	v_mov_b64_e32 v[108:109], v[44:45]
	v_mov_b64_e32 v[124:125], v[40:41]
	v_mov_b64_e32 v[132:133], v[36:37]
	v_mov_b64_e32 v[152:153], v[32:33]
	v_mov_b64_e32 v[148:149], v[28:29]
	v_mov_b64_e32 v[160:161], v[20:21]
	v_mov_b64_e32 v[168:169], v[24:25]
	v_mov_b64_e32 v[120:121], v[16:17]
	v_mov_b64_e32 v[116:117], v[12:13]
	v_mov_b64_e32 v[128:129], v[8:9]
	v_mov_b64_e32 v[136:137], v[4:5]
	v_mov_b64_e32 v[178:179], v[172:173]
	v_mov_b64_e32 v[180:181], v[170:171]
	v_mov_b32_e32 v207, v203
	v_mov_b64_e32 v[142:143], v[102:103]
	v_mov_b64_e32 v[138:139], v[90:91]
	v_mov_b64_e32 v[154:155], v[70:71]
	v_mov_b64_e32 v[162:163], v[50:51]
	v_mov_b32_e32 v209, v204
	v_mov_b64_e32 v[110:111], v[46:47]
	v_mov_b64_e32 v[106:107], v[42:43]
	v_mov_b64_e32 v[122:123], v[38:39]
	v_mov_b64_e32 v[130:131], v[34:35]
	v_mov_b32_e32 v213, v205
	v_mov_b64_e32 v[150:151], v[30:31]
	v_mov_b64_e32 v[146:147], v[26:27]
	v_mov_b64_e32 v[158:159], v[18:19]
	v_mov_b64_e32 v[166:167], v[22:23]
	v_mov_b32_e32 v212, v206
	v_mov_b64_e32 v[118:119], v[14:15]
	v_mov_b64_e32 v[114:115], v[10:11]
	v_mov_b64_e32 v[126:127], v[6:7]
	v_mov_b64_e32 v[134:135], v[2:3]

; #define LAS __attribute__((address_space(3)))
; __device__ __forceinline__ float ex2(float x) { return __builtin_amdgcn_exp2f(x); }
; __device__ __forceinline__ f32x4 mfma16(bf16x8 a, bf16x8 b, f32x4 c) { return __builtin_amdgcn_mfma_f32_16x16x32_bf16(a, b, c, 0, 0, 0); }
;   __device__ __forceinline__ bf16_t* W() const { return (bf16_t*)(ws + WS_W); }
; template <int NT, int NKK, int NDT, int MODE, bool MASK> ...
;     ...
;       __builtin_amdgcn_s_setprio(1);
; #pragma unroll
;       for (int t = 0; t < 2; ++t)
; #pragma unroll
;         for (int kk = 0; kk < NKK; ++kk) {
;           const bf16x8 kf = *(LAS const bf16x8*)(Kl + oz + (32 * st + 16 * t + r) * KSTR + (32 * kk + 8 * lg) * 2);
; #pragma unroll
;           for (int jj = 0; jj < JB; ++jj) s[jj][t] = mfma16(kf, qf[jh * JB + jj][kk], kk == 0 ? (f32x4){0.f, 0.f, 0.f, 0.f} : s[jj][t]);
;         }
;       __builtin_amdgcn_s_setprio(0);
;       bf16x8 pf[JB];
;       if (NT > JB) __builtin_amdgcn_sched_barrier(0);
; #pragma unroll
;       for (int jj = 0; jj < JB; ++jj) {
;         const int j = jh * JB + jj;
;         float mx = -INFINITY;
; #pragma unroll
;         for (int t = 0; t < 2; ++t)
; #pragma unroll
;           for (int i = 0; i < 4; ++i) {
;             if (MASK) { const int kp = kpos0 + 32 * st + 16 * t + 4 * lg + i; if (!mask_ok<MODE>(tq[j], kp, W)) s[jj][t][i] = -INFINITY; }
;             mx = fmaxf(mx, s[jj][t][i]);
;           }
;         mx = max_x16_x32(mx);
;         if (NT > 2 || __any(mx > m[j] + 8.0f / c)) {
;           const float mnew = fmaxf(m[j], mx);
;           const float ms2 = (mnew == -INFINITY) ? 0.f : mnew;
;           const float alpha = ex2((m[j] - ms2) * c);
;           m[j] = mnew; l[j] *= alpha;
; #pragma unroll
;           for (int dt = 0; dt < NDT; ++dt) o[j][dt] *= alpha;
;         }
.LBB0_1265:
	v_mov_b32_e32 v197, v1
	v_or_b32_e32 v1, s8, v183
	v_or_b32_e32 v196, s8, v204
	v_mov_b32_e32 v246, 0
	v_mov_b32_e32 v199, v212
	v_mov_b32_e32 v232, v214
	v_mov_b32_e32 v235, v215
	v_or_b32_e32 v198, s8, v211
	v_mad_u32_u24 v213, v196, s80, 0
	s_setprio 1
	v_mul_u32_u24_e32 v247, 0x90, v1
	v_add3_u32 v1, v207, v246, v247
	ds_read_b128 v[214:217], v1
	ds_read_b128 v[218:221], v1 offset:64
	s_waitcnt lgkmcnt(1)
	v_mfma_f32_16x16x32_bf16 v[222:225], v[214:217], v[12:15], 0
	v_mfma_f32_16x16x32_bf16 v[214:217], v[214:217], v[20:23], 0
	s_waitcnt lgkmcnt(0)
	v_mfma_f32_16x16x32_bf16 v[222:225], v[218:221], v[16:19], v[222:225]
	v_mfma_f32_16x16x32_bf16 v[214:217], v[218:221], v[24:27], v[214:217]
	ds_read_b128 v[218:221], v1 offset:2304
	ds_read_b128 v[228:231], v1 offset:2368
	s_waitcnt lgkmcnt(1)
	v_mfma_f32_16x16x32_bf16 v[236:239], v[218:221], v[12:15], 0
	v_mfma_f32_16x16x32_bf16 v[218:221], v[218:221], v[20:23], 0
	s_waitcnt lgkmcnt(0)
	v_mfma_f32_16x16x32_bf16 v[236:239], v[228:231], v[16:19], v[236:239]
	v_mfma_f32_16x16x32_bf16 v[218:221], v[228:231], v[24:27], v[218:221]
	s_setprio 0
	v_cmp_le_i32_e32 vcc, v198, v182
	v_cmp_gt_i32_e64 s[12:13], v198, v208
	v_mov_b32_e32 v196, s81
	s_and_b64 vcc, vcc, s[12:13]
	v_cndmask_b32_e32 v212, v196, v222, vcc
	v_cmp_lt_i32_e64 s[12:13], v198, v182
	v_cmp_ge_i32_e64 s[14:15], v198, v208
	v_or_b32_e32 v196, 2, v198
	s_and_b64 s[12:13], s[12:13], s[14:15]
	v_cmp_le_i32_e64 s[14:15], v196, v182
	v_cmp_gt_i32_e64 s[16:17], v196, v208
	v_or_b32_e32 v196, 3, v198
	s_and_b64 s[14:15], s[14:15], s[16:17]
	v_cmp_le_i32_e64 s[16:17], v196, v182
	v_cmp_gt_i32_e64 s[18:19], v196, v208
	s_and_b64 s[16:17], s[16:17], s[18:19]
	v_or_b32_e32 v196, 16, v198
	v_cndmask_b32_e64 v222, v200, v223, s[12:13]
	v_cndmask_b32_e64 v223, v200, v224, s[14:15]
	v_cndmask_b32_e64 v224, v200, v225, s[16:17]
	v_cmp_le_i32_e64 s[18:19], v196, v182
	v_cmp_gt_i32_e64 s[20:21], v196, v208
	v_or_b32_e32 v225, 17, v198
	s_and_b64 s[18:19], s[18:19], s[20:21]
	v_cmp_le_i32_e64 s[20:21], v225, v182
	v_cmp_gt_i32_e64 s[22:23], v225, v208
	v_or_b32_e32 v228, 18, v198
	s_and_b64 s[20:21], s[20:21], s[22:23]
	v_cmp_le_i32_e64 s[22:23], v228, v182
	v_cmp_gt_i32_e64 s[24:25], v228, v208
	v_or_b32_e32 v198, 19, v198
	v_max3_f32 v1, v212, s81, v222
	v_mov_b32_e32 v196, s81
	s_and_b64 s[22:23], s[22:23], s[24:25]
	v_cmp_le_i32_e64 s[24:25], v198, v182
	v_cmp_gt_i32_e64 s[28:29], v198, v208
	v_max3_f32 v1, v1, v223, v224
	v_cndmask_b32_e64 v196, v196, v236, s[18:19]
	v_cndmask_b32_e64 v225, v200, v237, s[20:21]
	s_and_b64 s[24:25], s[24:25], s[28:29]
	v_max3_f32 v1, v1, v196, v225
	v_cndmask_b32_e64 v228, v200, v238, s[22:23]
	v_cndmask_b32_e64 v230, v200, v239, s[24:25]
	v_max3_f32 v1, v1, v228, v230
	v_mov_b32_e32 v198, v1
	s_nop 1
	v_permlane16_swap_b32_e32 v1, v198
	v_max_f32_e32 v1, v1, v198
	v_mov_b32_e32 v198, v1
	s_nop 1
	v_permlane32_swap_b32_e32 v1, v198
	v_max3_f32 v1, v197, v1, v198
	v_cmp_eq_f32_e64 s[28:29], s81, v1
	v_cndmask_b32_e64 v215, v200, v215, s[12:13]
	v_cndmask_b32_e64 v238, v200, v216, s[14:15]
	v_cndmask_b32_e64 v198, v1, 0, s[28:29]
	v_sub_f32_e32 v197, v197, v198
	v_mul_f32_e32 v197, 0x3e38aa3b, v197
	v_exp_f32_e32 v198, v197
	v_mul_f32_e32 v197, 0x3e38aa3b, v1
	v_cndmask_b32_e64 v236, v197, 0, s[28:29]
	v_fma_f32 v196, v196, s42, -v236
	v_exp_f32_e32 v229, v196
	v_fma_f32 v196, v222, s42, -v236
	v_exp_f32_e32 v231, v196
	v_fma_f32 v196, v225, s42, -v236
	v_exp_f32_e32 v237, v196
	v_fma_f32 v196, v223, s42, -v236
	v_exp_f32_e32 v239, v196
	v_fma_f32 v196, v228, s42, -v236
	v_exp_f32_e32 v241, v196
	v_fma_f32 v196, v224, s42, -v236
	v_exp_f32_e32 v243, v196
	v_fma_f32 v196, v230, s42, -v236
	v_exp_f32_e32 v245, v196
	v_mov_b32_e32 v196, s81
	v_cndmask_b32_e32 v228, v196, v214, vcc
	v_max3_f32 v196, v228, s81, v215
	v_cndmask_b32_e64 v242, v200, v217, s[16:17]
	v_fma_f32 v197, v212, s42, -v236
	v_max3_f32 v212, v196, v238, v242
	v_mov_b32_e32 v196, s81
	v_cndmask_b32_e64 v216, v196, v218, s[18:19]
	v_cndmask_b32_e64 v217, v200, v219, s[20:21]
	v_max3_f32 v196, v212, v216, v217
	v_cndmask_b32_e64 v220, v200, v220, s[22:23]
	v_cndmask_b32_e64 v221, v200, v221, s[24:25]
	v_max3_f32 v196, v196, v220, v221
	v_mov_b32_e32 v212, v196
	s_nop 1
	v_permlane16_swap_b32_e32 v196, v212
	v_max_f32_e32 v196, v196, v212
	v_mov_b32_e32 v212, v196
	s_nop 1
	v_permlane32_swap_b32_e32 v196, v212
	v_max3_f32 v212, v199, v196, v212
	v_cmp_eq_f32_e64 s[28:29], s81, v212
	v_pk_mul_f32 v[154:155], v[154:155], v[198:199] op_sel_hi:[1,0]
	v_pk_mul_f32 v[152:153], v[152:153], v[198:199] op_sel_hi:[1,0]
	v_cndmask_b32_e64 v196, v212, 0, s[28:29]
	v_sub_f32_e32 v196, v199, v196
	v_mul_f32_e32 v196, 0x3e38aa3b, v196
	v_exp_f32_e32 v214, v196
	v_mul_f32_e32 v196, 0x3e38aa3b, v212
	v_pk_mul_f32 v[150:151], v[150:151], v[198:199] op_sel_hi:[1,0]
	v_pk_mul_f32 v[148:149], v[148:149], v[198:199] op_sel_hi:[1,0]
	v_pk_mul_f32 v[166:167], v[166:167], v[198:199] op_sel_hi:[1,0]
	v_pk_mul_f32 v[164:165], v[164:165], v[198:199] op_sel_hi:[1,0]
	v_pk_mul_f32 v[174:175], v[174:175], v[198:199] op_sel_hi:[1,0]
	v_pk_mul_f32 v[172:173], v[172:173], v[198:199] op_sel_hi:[1,0]
	v_cndmask_b32_e64 v199, v196, 0, s[28:29]
	v_fma_f32 v196, v228, s42, -v199
	v_fma_f32 v216, v216, s42, -v199
	v_exp_f32_e32 v197, v197
	v_exp_f32_e32 v196, v196
	v_exp_f32_e32 v228, v216
	v_pk_mul_f32 v[122:123], v[122:123], v[214:215] op_sel_hi:[1,0]
	v_pk_mul_f32 v[120:121], v[120:121], v[214:215] op_sel_hi:[1,0]
	v_pk_mul_f32 v[118:119], v[118:119], v[214:215] op_sel_hi:[1,0]
	v_pk_mul_f32 v[116:117], v[116:117], v[214:215] op_sel_hi:[1,0]
; #define LAS __attribute__((address_space(3)))
; template <int NT, int NKK, int NDT, int MODE, bool MASK> ...
;     ...
;       __builtin_amdgcn_s_setprio(1);
; #pragma unroll
;       for (int t = 0; t < 2; ++t)
; #pragma unroll
;         for (int kk = 0; kk < NKK; ++kk) {
;           const bf16x8 kf = *(LAS const bf16x8*)(Kl + oz + (32 * st + 16 * t + r) * KSTR + (32 * kk + 8 * lg) * 2);
; #pragma unroll
;           for (int jj = 0; jj < JB; ++jj) s[jj][t] = mfma16(kf, qf[jh * JB + jj][kk], kk == 0 ? (f32x4){0.f, 0.f, 0.f, 0.f} : s[jj][t]);
;         }
;       __builtin_amdgcn_s_setprio(0);
;       bf16x8 pf[JB];
;       if (NT > JB) __builtin_amdgcn_sched_barrier(0);
; #pragma unroll
;       for (int jj = 0; jj < JB; ++jj) {
;         const int j = jh * JB + jj;
;         float mx = -INFINITY;
; #pragma unroll
;         for (int t = 0; t < 2; ++t)
; #pragma unroll
;           for (int i = 0; i < 4; ++i) {
;             if (MASK) { const int kp = kpos0 + 32 * st + 16 * t + 4 * lg + i; if (!mask_ok<MODE>(tq[j], kp, W)) s[jj][t][i] = -INFINITY; }
;             mx = fmaxf(mx, s[jj][t][i]);
;           }
;         mx = max_x16_x32(mx);
;         if (NT > 2 || __any(mx > m[j] + 8.0f / c)) {
;           const float mnew = fmaxf(m[j], mx);
;           const float ms2 = (mnew == -INFINITY) ? 0.f : mnew;
;           const float alpha = ex2((m[j] - ms2) * c);
;           m[j] = mnew; l[j] *= alpha;
; #pragma unroll
;           for (int dt = 0; dt < NDT; ++dt) o[j][dt] *= alpha;
;         }
;         const float mc = ((m[j] == -INFINITY) ? 0.f : m[j]) * c;
;         float p0[4], p1[4], ps = 0.f;
; #pragma unroll
;         for (int i = 0; i < 4; ++i) { p0[i] = ex2(s[jj][0][i] * c - mc); p1[i] = ex2(s[jj][1][i] * c - mc); ps += p0[i] + p1[i]; }
;         l[j] += ps;
;         pf[jj] = pack8(p0, p1);
;       }
;       if (NT > JB) __builtin_amdgcn_sched_barrier(0);
;       __builtin_amdgcn_s_setprio(1);
; #pragma unroll
;       for (int dt = 0; dt < NDT; ++dt) {
;         const s16x4 v0 = ds_tr(Vl + oz + (32 * st + 4 * lg + vq) * VSTR + (16 * dt + 4 * vp) * 2);
;         const s16x4 v1 = ds_tr(Vl + oz + (32 * st + 16 + 4 * lg + vq) * VSTR + (16 * dt + 4 * vp) * 2);
;         const bf16x8 vf = (bf16x8){v0[0], v0[1], v0[2], v0[3], v1[0], v1[1], v1[2], v1[3]};
; #pragma unroll
;         for (int jj = 0; jj < JB; ++jj) o[jh * JB + jj][dt] = mfma16(vf, pf[jj], o[jh * JB + jj][dt]);
	v_pk_mul_f32 v[134:135], v[134:135], v[214:215] op_sel_hi:[1,0]
	v_pk_mul_f32 v[132:133], v[132:133], v[214:215] op_sel_hi:[1,0]
	v_pk_mul_f32 v[142:143], v[142:143], v[214:215] op_sel_hi:[1,0]
	v_fma_f32 v215, v215, s42, -v199
	v_cvt_pk_bf16_f32 v222, v197, v231
	v_exp_f32_e32 v230, v215
	v_fma_f32 v215, v217, s42, -v199
	v_pk_add_f32 v[216:217], v[196:197], v[228:229]
	v_fma_f32 v197, v238, s42, -v199
	v_exp_f32_e32 v238, v197
	v_fma_f32 v197, v220, s42, -v199
	v_exp_f32_e32 v236, v215
	v_exp_f32_e32 v240, v197
	v_fma_f32 v197, v242, s42, -v199
	v_exp_f32_e32 v242, v197
	v_fma_f32 v197, v221, s42, -v199
	v_exp_f32_e32 v244, v197
	v_pk_add_f32 v[218:219], v[230:231], v[236:237]
	v_pk_mul_f32 v[140:141], v[140:141], v[214:215] op_sel_hi:[1,0]
	v_mov_b32_e32 v215, v198
	v_pk_add_f32 v[198:199], v[218:219], v[216:217]
	v_pk_add_f32 v[216:217], v[238:239], v[240:241]
	v_cvt_pk_bf16_f32 v223, v239, v243
	v_pk_add_f32 v[198:199], v[216:217], v[198:199]
	v_pk_add_f32 v[216:217], v[242:243], v[244:245]
	v_cvt_pk_bf16_f32 v224, v229, v237
	v_pk_add_f32 v[198:199], v[216:217], v[198:199]
	v_cvt_pk_bf16_f32 v225, v241, v245
	v_pk_fma_f32 v[194:195], v[194:195], v[214:215], v[198:199]
	v_cvt_pk_bf16_f32 v214, v196, v230
	v_cvt_pk_bf16_f32 v215, v238, v242
	v_cvt_pk_bf16_f32 v216, v228, v236
	v_cvt_pk_bf16_f32 v217, v240, v244
	s_setprio 1
	v_add3_u32 v196, v213, v246, v206
	ds_read_b64_tr_b16 v[220:221], v196 offset:11776
	ds_read_b64_tr_b16 v[218:219], v196 offset:9216
	ds_read_b64_tr_b16 v[228:229], v196 offset:9248
	ds_read_b64_tr_b16 v[230:231], v196 offset:11808
	s_waitcnt lgkmcnt(2)
	v_mfma_f32_16x16x32_bf16 v[152:155], v[218:221], v[222:225], v[152:155]
	v_mfma_f32_16x16x32_bf16 v[120:123], v[218:221], v[214:217], v[120:123]
	ds_read_b64_tr_b16 v[218:219], v196 offset:9280
	ds_read_b64_tr_b16 v[220:221], v196 offset:11840
	s_waitcnt lgkmcnt(0)
	v_mfma_f32_16x16x32_bf16 v[164:167], v[218:221], v[222:225], v[164:167]
	v_mfma_f32_16x16x32_bf16 v[132:135], v[218:221], v[214:217], v[132:135]
	ds_read_b64_tr_b16 v[218:219], v196 offset:9312
	ds_read_b64_tr_b16 v[220:221], v196 offset:11872
	v_mfma_f32_16x16x32_bf16 v[148:151], v[228:231], v[222:225], v[148:151]
	v_mfma_f32_16x16x32_bf16 v[116:119], v[228:231], v[214:217], v[116:119]
	s_waitcnt lgkmcnt(0)
	v_mfma_f32_16x16x32_bf16 v[172:175], v[218:221], v[222:225], v[172:175]
	v_mfma_f32_16x16x32_bf16 v[140:143], v[218:221], v[214:217], v[140:143]
	s_setprio 0
	v_mov_b32_e32 v248, 0
	s_setprio 1
	v_add3_u32 v196, v207, v248, v247
	ds_read_b128 v[214:217], v196
	ds_read_b128 v[218:221], v196 offset:64
	ds_read_b128 v[228:231], v196 offset:2304
	ds_read_b128 v[236:239], v196 offset:2368
	s_waitcnt lgkmcnt(3)
	v_mfma_f32_16x16x32_bf16 v[222:225], v[214:217], v[28:31], 0
	v_mfma_f32_16x16x32_bf16 v[214:217], v[214:217], v[36:39], 0
	s_waitcnt lgkmcnt(1)
	v_mfma_f32_16x16x32_bf16 v[240:243], v[228:231], v[28:31], 0
	v_mfma_f32_16x16x32_bf16 v[228:231], v[228:231], v[36:39], 0
	v_mfma_f32_16x16x32_bf16 v[222:225], v[218:221], v[32:35], v[222:225]
	v_mfma_f32_16x16x32_bf16 v[216:219], v[218:221], v[40:43], v[214:217]
	s_waitcnt lgkmcnt(0)
; __device__ __forceinline__ float ex2(float x) { return __builtin_amdgcn_exp2f(x); }
; __device__ __forceinline__ f32x4 mfma16(bf16x8 a, bf16x8 b, f32x4 c) { return __builtin_amdgcn_mfma_f32_16x16x32_bf16(a, b, c, 0, 0, 0); }
; __device__ __forceinline__ s16x4 ds_tr(LAS const unsigned char* p) { return __builtin_bit_cast(s16x4, __builtin_amdgcn_ds_read_tr16_b64_v4i16((LAS v4i16_t*)p)); }
;   __device__ __forceinline__ bf16_t* W() const { return (bf16_t*)(ws + WS_W); }
; template <int NT, int NKK, int NDT, int MODE, bool MASK> ...
;     ...
;       for (int jj = 0; jj < JB; ++jj) {
;         const int j = jh * JB + jj;
;         float mx = -INFINITY;
; #pragma unroll
;         for (int t = 0; t < 2; ++t)
; #pragma unroll
;           for (int i = 0; i < 4; ++i) {
;             if (MASK) { const int kp = kpos0 + 32 * st + 16 * t + 4 * lg + i; if (!mask_ok<MODE>(tq[j], kp, W)) s[jj][t][i] = -INFINITY; }
;             mx = fmaxf(mx, s[jj][t][i]);
;           }
;         mx = max_x16_x32(mx);
;         if (NT > 2 || __any(mx > m[j] + 8.0f / c)) {
;           const float mnew = fmaxf(m[j], mx);
;           const float ms2 = (mnew == -INFINITY) ? 0.f : mnew;
;           const float alpha = ex2((m[j] - ms2) * c);
;           m[j] = mnew; l[j] *= alpha;
; #pragma unroll
;           for (int dt = 0; dt < NDT; ++dt) o[j][dt] *= alpha;
;         }
;         const float mc = ((m[j] == -INFINITY) ? 0.f : m[j]) * c;
;         float p0[4], p1[4], ps = 0.f;
; #pragma unroll
;         for (int i = 0; i < 4; ++i) { p0[i] = ex2(s[jj][0][i] * c - mc); p1[i] = ex2(s[jj][1][i] * c - mc); ps += p0[i] + p1[i]; }
;         l[j] += ps;
;         pf[jj] = pack8(p0, p1);
;       }
;       if (NT > JB) __builtin_amdgcn_sched_barrier(0);
;       __builtin_amdgcn_s_setprio(1);
; #pragma unroll
;       for (int dt = 0; dt < NDT; ++dt) {
;         const s16x4 v0 = ds_tr(Vl + oz + (32 * st + 4 * lg + vq) * VSTR + (16 * dt + 4 * vp) * 2);
;         const s16x4 v1 = ds_tr(Vl + oz + (32 * st + 16 + 4 * lg + vq) * VSTR + (16 * dt + 4 * vp) * 2);
;         const bf16x8 vf = (bf16x8){v0[0], v0[1], v0[2], v0[3], v1[0], v1[1], v1[2], v1[3]};
; #pragma unroll
;         for (int jj = 0; jj < JB; ++jj) o[jh * JB + jj][dt] = mfma16(vf, pf[jj], o[jh * JB + jj][dt]);
;       }
;       __builtin_amdgcn_s_setprio(0);
;       if (NT > JB) __builtin_amdgcn_sched_barrier(0);
	v_mfma_f32_16x16x32_bf16 v[240:243], v[236:239], v[32:35], v[240:243]
	v_mfma_f32_16x16x32_bf16 v[228:231], v[236:239], v[40:43], v[228:231]
	s_setprio 0
	v_mov_b32_e32 v196, s81
	s_nop 0
	v_cndmask_b32_e32 v197, v196, v222, vcc
	v_cndmask_b32_e64 v199, v200, v223, s[12:13]
	v_max3_f32 v196, v197, s81, v199
	v_cndmask_b32_e64 v215, v200, v224, s[14:15]
	v_cndmask_b32_e64 v220, v200, v225, s[16:17]
	v_max3_f32 v198, v196, v215, v220
	v_mov_b32_e32 v196, s81
	v_cndmask_b32_e64 v196, v196, v240, s[18:19]
	v_cndmask_b32_e64 v221, v200, v241, s[20:21]
	v_max3_f32 v198, v198, v196, v221
	v_cndmask_b32_e64 v222, v200, v242, s[22:23]
	v_cndmask_b32_e64 v223, v200, v243, s[24:25]
	v_max3_f32 v198, v198, v222, v223
	v_mov_b32_e32 v214, v198
	s_nop 1
	v_permlane16_swap_b32_e32 v198, v214
	v_max_f32_e32 v198, v198, v214
	v_mov_b32_e32 v214, v198
	s_nop 1
	v_permlane32_swap_b32_e32 v198, v214
	v_max3_f32 v214, v232, v198, v214
	v_cmp_eq_f32_e64 s[28:29], s81, v214
	v_mul_f32_e32 v224, 0x3e38aa3b, v214
	v_cndmask_b32_e64 v217, v200, v217, s[12:13]
	v_cndmask_b32_e64 v224, v224, 0, s[28:29]
	v_fma_f32 v196, v196, s42, -v224
	v_cndmask_b32_e64 v198, v214, 0, s[28:29]
	v_exp_f32_e32 v225, v196
	v_fma_f32 v196, v199, s42, -v224
	v_sub_f32_e32 v198, v232, v198
	v_exp_f32_e32 v237, v196
	v_fma_f32 v196, v221, s42, -v224
	v_mul_f32_e32 v198, 0x3e38aa3b, v198
	v_exp_f32_e32 v239, v196
	v_fma_f32 v196, v215, s42, -v224
	v_exp_f32_e32 v198, v198
	v_exp_f32_e32 v241, v196
	v_fma_f32 v196, v222, s42, -v224
	v_exp_f32_e32 v243, v196
	v_fma_f32 v196, v220, s42, -v224
	v_exp_f32_e32 v245, v196
	v_fma_f32 v196, v223, s42, -v224
	v_exp_f32_e32 v247, v196
	v_mov_b32_e32 v196, s81
	v_pk_mul_f32 v[162:163], v[162:163], v[198:199] op_sel_hi:[1,0]
	v_pk_mul_f32 v[160:161], v[160:161], v[198:199] op_sel_hi:[1,0]
	v_pk_mul_f32 v[158:159], v[158:159], v[198:199] op_sel_hi:[1,0]
	v_pk_mul_f32 v[156:157], v[156:157], v[198:199] op_sel_hi:[1,0]
	v_pk_mul_f32 v[170:171], v[170:171], v[198:199] op_sel_hi:[1,0]
	v_pk_mul_f32 v[168:169], v[168:169], v[198:199] op_sel_hi:[1,0]
	v_pk_mul_f32 v[178:179], v[178:179], v[198:199] op_sel_hi:[1,0]
	v_pk_mul_f32 v[176:177], v[176:177], v[198:199] op_sel_hi:[1,0]
	v_cndmask_b32_e32 v199, v196, v216, vcc
	v_max3_f32 v196, v199, s81, v217
	v_cndmask_b32_e64 v232, v200, v218, s[14:15]
	v_cndmask_b32_e64 v244, v200, v219, s[16:17]
	v_max3_f32 v215, v196, v232, v244
	v_mov_b32_e32 v196, s81
	v_cndmask_b32_e64 v218, v196, v228, s[18:19]
	v_cndmask_b32_e64 v219, v200, v229, s[20:21]
	v_max3_f32 v196, v215, v218, v219
	v_cndmask_b32_e64 v230, v200, v230, s[22:23]
	v_cndmask_b32_e64 v231, v200, v231, s[24:25]
	v_max3_f32 v196, v196, v230, v231
	v_mov_b32_e32 v215, v196
	s_nop 1
	v_permlane16_swap_b32_e32 v196, v215
	v_max_f32_e32 v196, v196, v215
	v_mov_b32_e32 v215, v196
	s_nop 1
	v_permlane32_swap_b32_e32 v196, v215
	v_max3_f32 v215, v235, v196, v215
	v_cmp_eq_f32_e32 vcc, s81, v215
	v_fma_f32 v197, v197, s42, -v224
	v_exp_f32_e32 v197, v197
	v_cndmask_b32_e64 v196, v215, 0, vcc
	v_sub_f32_e32 v196, v235, v196
	v_mul_f32_e32 v196, 0x3e38aa3b, v196
	v_exp_f32_e32 v216, v196
	v_mul_f32_e32 v196, 0x3e38aa3b, v215
	v_cndmask_b32_e64 v235, v196, 0, vcc
	v_fma_f32 v196, v199, s42, -v235
	v_fma_f32 v199, v218, s42, -v235
	v_exp_f32_e32 v196, v196
	v_exp_f32_e32 v224, v199
	v_fma_f32 v199, v217, s42, -v235
	v_cvt_pk_bf16_f32 v220, v197, v237
	v_exp_f32_e32 v236, v199
	v_fma_f32 v199, v219, s42, -v235
	v_pk_add_f32 v[218:219], v[196:197], v[224:225]
	v_fma_f32 v197, v232, s42, -v235
	v_exp_f32_e32 v240, v197
	v_fma_f32 v197, v230, s42, -v235
	v_exp_f32_e32 v238, v199
	v_exp_f32_e32 v242, v197
	v_fma_f32 v197, v244, s42, -v235
	v_exp_f32_e32 v244, v197
	v_fma_f32 v197, v231, s42, -v235
	v_exp_f32_e32 v246, v197
	v_pk_add_f32 v[228:229], v[236:237], v[238:239]
	v_pk_mul_f32 v[130:131], v[130:131], v[216:217] op_sel_hi:[1,0]
	v_pk_mul_f32 v[128:129], v[128:129], v[216:217] op_sel_hi:[1,0]
	v_pk_mul_f32 v[126:127], v[126:127], v[216:217] op_sel_hi:[1,0]
	v_pk_mul_f32 v[124:125], v[124:125], v[216:217] op_sel_hi:[1,0]
	v_pk_mul_f32 v[138:139], v[138:139], v[216:217] op_sel_hi:[1,0]
	v_pk_mul_f32 v[136:137], v[136:137], v[216:217] op_sel_hi:[1,0]
	v_pk_mul_f32 v[146:147], v[146:147], v[216:217] op_sel_hi:[1,0]
	v_pk_mul_f32 v[144:145], v[144:145], v[216:217] op_sel_hi:[1,0]
	v_mov_b32_e32 v217, v198
	v_pk_add_f32 v[198:199], v[228:229], v[218:219]
	v_pk_add_f32 v[218:219], v[240:241], v[242:243]
	v_cvt_pk_bf16_f32 v221, v241, v245
	v_pk_add_f32 v[198:199], v[218:219], v[198:199]
	v_pk_add_f32 v[218:219], v[244:245], v[246:247]
	v_cvt_pk_bf16_f32 v222, v225, v239
	v_pk_add_f32 v[198:199], v[218:219], v[198:199]
	v_cvt_pk_bf16_f32 v223, v243, v247
	v_pk_fma_f32 v[202:203], v[202:203], v[216:217], v[198:199]
	v_cvt_pk_bf16_f32 v216, v196, v236
	v_cvt_pk_bf16_f32 v217, v240, v244
	v_cvt_pk_bf16_f32 v218, v224, v238
	v_cvt_pk_bf16_f32 v219, v242, v246
	s_setprio 1
	v_add3_u32 v196, v213, v248, v206
	ds_read_b64_tr_b16 v[230:231], v196 offset:11776
	ds_read_b64_tr_b16 v[228:229], v196 offset:9216
	ds_read_b64_tr_b16 v[236:237], v196 offset:9248
	ds_read_b64_tr_b16 v[238:239], v196 offset:11808
	s_waitcnt lgkmcnt(2)
	v_mfma_f32_16x16x32_bf16 v[160:163], v[228:231], v[220:223], v[160:163]
	v_mfma_f32_16x16x32_bf16 v[128:131], v[228:231], v[216:219], v[128:131]
	ds_read_b64_tr_b16 v[228:229], v196 offset:9280
	ds_read_b64_tr_b16 v[230:231], v196 offset:11840
	s_waitcnt lgkmcnt(0)
	v_mfma_f32_16x16x32_bf16 v[168:171], v[228:231], v[220:223], v[168:171]
	v_mfma_f32_16x16x32_bf16 v[136:139], v[228:231], v[216:219], v[136:139]
	ds_read_b64_tr_b16 v[228:229], v196 offset:9312
	ds_read_b64_tr_b16 v[230:231], v196 offset:11872
	v_mfma_f32_16x16x32_bf16 v[156:159], v[236:239], v[220:223], v[156:159]
	v_mfma_f32_16x16x32_bf16 v[124:127], v[236:239], v[216:219], v[124:127]
	s_waitcnt lgkmcnt(0)
	v_mfma_f32_16x16x32_bf16 v[176:179], v[228:231], v[220:223], v[176:179]
	v_mfma_f32_16x16x32_bf16 v[144:147], v[228:231], v[216:219], v[144:147]
	s_setprio 0
	s_mov_b32 s8, 32
	s_and_b64 vcc, exec, s[70:71]
	s_mov_b64 s[70:71], 0
	s_cbranch_vccnz .LBB0_1265
	s_mov_b64 s[12:13], 0

; #define LAS __attribute__((address_space(3)))
; template <int NT, int NKK, int NDT, int MODE, bool MASK> ...
;     ...
;       __builtin_amdgcn_s_setprio(1);
; #pragma unroll
;       for (int t = 0; t < 2; ++t)
; #pragma unroll
;         for (int kk = 0; kk < NKK; ++kk) {
;           const bf16x8 kf = *(LAS const bf16x8*)(Kl + oz + (32 * st + 16 * t + r) * KSTR + (32 * kk + 8 * lg) * 2);
; #pragma unroll
;           for (int jj = 0; jj < JB; ++jj) s[jj][t] = mfma16(kf, qf[jh * JB + jj][kk], kk == 0 ? (f32x4){0.f, 0.f, 0.f, 0.f} : s[jj][t]);
;         }
;       __builtin_amdgcn_s_setprio(0);
;       bf16x8 pf[JB];
;       if (NT > JB) __builtin_amdgcn_sched_barrier(0);
; #pragma unroll
;       for (int jj = 0; jj < JB; ++jj) {
;         const int j = jh * JB + jj;
;         float mx = -INFINITY;
; #pragma unroll
;         for (int t = 0; t < 2; ++t)
; #pragma unroll
;           for (int i = 0; i < 4; ++i) {
;             if (MASK) { const int kp = kpos0 + 32 * st + 16 * t + 4 * lg + i; if (!mask_ok<MODE>(tq[j], kp, W)) s[jj][t][i] = -INFINITY; }
;             mx = fmaxf(mx, s[jj][t][i]);
;           }
;         mx = max_x16_x32(mx);
;         if (NT > 2 || __any(mx > m[j] + 8.0f / c)) {
;           const float mnew = fmaxf(m[j], mx);
;           const float ms2 = (mnew == -INFINITY) ? 0.f : mnew;
;           const float alpha = ex2((m[j] - ms2) * c);
;           m[j] = mnew; l[j] *= alpha;
; #pragma unroll
;           for (int dt = 0; dt < NDT; ++dt) o[j][dt] *= alpha;
;         }
;         const float mc = ((m[j] == -INFINITY) ? 0.f : m[j]) * c;
;         float p0[4], p1[4], ps = 0.f;
; #pragma unroll
;         for (int i = 0; i < 4; ++i) { p0[i] = ex2(s[jj][0][i] * c - mc); p1[i] = ex2(s[jj][1][i] * c - mc); ps += p0[i] + p1[i]; }
;         l[j] += ps;
;         pf[jj] = pack8(p0, p1);
;       }
;       if (NT > JB) __builtin_amdgcn_sched_barrier(0);
;       __builtin_amdgcn_s_setprio(1);
; #pragma unroll
;       for (int dt = 0; dt < NDT; ++dt) {
;         const s16x4 v0 = ds_tr(Vl + oz + (32 * st + 4 * lg + vq) * VSTR + (16 * dt + 4 * vp) * 2);
;         const s16x4 v1 = ds_tr(Vl + oz + (32 * st + 16 + 4 * lg + vq) * VSTR + (16 * dt + 4 * vp) * 2);
;         const bf16x8 vf = (bf16x8){v0[0], v0[1], v0[2], v0[3], v1[0], v1[1], v1[2], v1[3]};
; #pragma unroll
;         for (int jj = 0; jj < JB; ++jj) o[jh * JB + jj][dt] = mfma16(vf, pf[jj], o[jh * JB + jj][dt]);
.LBB0_1269:
	v_or_b32_e32 v1, s8, v204
	v_mov_b32_e32 v150, 0
	v_mov_b32_e32 v136, v190
	v_mov_b32_e32 v138, v191
	v_mov_b32_e32 v148, v192
	v_mov_b32_e32 v149, v193
	v_or_b32_e32 v116, s8, v183
	v_mad_u32_u24 v1, v1, s80, 0
	s_setprio 1
	v_mul_u32_u24_e32 v151, 0x90, v116
	v_add3_u32 v128, v207, v150, v151
	ds_read_b128 v[116:119], v128
	ds_read_b128 v[120:123], v128 offset:64
	s_waitcnt lgkmcnt(1)
	v_mfma_f32_16x16x32_bf16 v[124:127], v[116:119], v[12:15], 0
	v_mfma_f32_16x16x32_bf16 v[116:119], v[116:119], v[20:23], 0
	s_waitcnt lgkmcnt(0)
	v_mfma_f32_16x16x32_bf16 v[124:127], v[120:123], v[16:19], v[124:127]
	v_mfma_f32_16x16x32_bf16 v[116:119], v[120:123], v[24:27], v[116:119]
	ds_read_b128 v[120:123], v128 offset:2304
	ds_read_b128 v[128:131], v128 offset:2368
	s_waitcnt lgkmcnt(1)
	v_mfma_f32_16x16x32_bf16 v[132:135], v[120:123], v[12:15], 0
	v_mfma_f32_16x16x32_bf16 v[120:123], v[120:123], v[20:23], 0
	s_waitcnt lgkmcnt(0)
	v_mfma_f32_16x16x32_bf16 v[132:135], v[128:131], v[16:19], v[132:135]
	v_mfma_f32_16x16x32_bf16 v[120:123], v[128:131], v[24:27], v[120:123]
	s_setprio 0
	v_max3_f32 v128, v124, s81, v125
	v_max3_f32 v128, v128, v126, v127
	s_nop 3
	v_max3_f32 v128, v128, v132, v133
	v_max3_f32 v128, v128, v134, v135
	v_mov_b32_e32 v129, v128
	s_nop 1
	v_permlane16_swap_b32_e32 v128, v129
	v_max_f32_e32 v128, v128, v129
	v_mov_b32_e32 v129, v128
	s_nop 1
	v_permlane32_swap_b32_e32 v128, v129
	v_max3_f32 v190, v136, v128, v129
	v_cmp_eq_f32_e32 vcc, s81, v190
	s_nop 1
	v_cndmask_b32_e64 v128, v190, 0, vcc
	v_sub_f32_e32 v128, v136, v128
	v_mul_f32_e32 v128, 0x3e38aa3b, v128
	v_exp_f32_e32 v128, v128
	s_nop 0
	v_pk_mul_f32 v[106:107], v[106:107], v[128:129] op_sel_hi:[1,0]
	v_pk_mul_f32 v[104:105], v[104:105], v[128:129] op_sel_hi:[1,0]
	v_pk_mul_f32 v[102:103], v[102:103], v[128:129] op_sel_hi:[1,0]
	v_pk_mul_f32 v[100:101], v[100:101], v[128:129] op_sel_hi:[1,0]
	v_pk_mul_f32 v[110:111], v[110:111], v[128:129] op_sel_hi:[1,0]
	v_pk_mul_f32 v[108:109], v[108:109], v[128:129] op_sel_hi:[1,0]
	v_pk_mul_f32 v[114:115], v[114:115], v[128:129] op_sel_hi:[1,0]
	v_pk_mul_f32 v[112:113], v[112:113], v[128:129] op_sel_hi:[1,0]
	v_mul_f32_e32 v129, 0x3e38aa3b, v190
	v_cndmask_b32_e64 v129, v129, 0, vcc
	v_fma_f32 v124, v124, s42, -v129
	v_exp_f32_e32 v131, v124
	v_fma_f32 v124, v132, s42, -v129
	v_exp_f32_e32 v137, v124
	v_fma_f32 v124, v125, s42, -v129
	v_max3_f32 v125, v116, s81, v117
	v_max3_f32 v125, v125, v118, v119
	v_max3_f32 v125, v125, v120, v121
	v_exp_f32_e32 v139, v124
	v_fma_f32 v124, v133, s42, -v129
	v_max3_f32 v125, v125, v122, v123
	v_exp_f32_e32 v133, v124
	v_fma_f32 v124, v126, s42, -v129
	v_mov_b32_e32 v126, v125
	s_nop 1
	v_permlane16_swap_b32_e32 v125, v126
	v_max_f32_e32 v125, v125, v126
	v_mov_b32_e32 v126, v125
	v_exp_f32_e32 v141, v124
	v_fma_f32 v124, v134, s42, -v129
	v_permlane32_swap_b32_e32 v125, v126
	v_exp_f32_e32 v143, v124
	v_fma_f32 v124, v127, s42, -v129
	v_max3_f32 v191, v138, v125, v126
	v_exp_f32_e32 v145, v124
	v_fma_f32 v124, v135, s42, -v129
	v_cmp_eq_f32_e32 vcc, s81, v191
	v_mul_f32_e32 v129, 0x3e38aa3b, v191
	v_exp_f32_e32 v135, v124
	v_cndmask_b32_e64 v129, v129, 0, vcc
	v_fma_f32 v116, v116, s42, -v129
	v_exp_f32_e32 v130, v116
	v_fma_f32 v116, v120, s42, -v129
	v_cndmask_b32_e64 v125, v191, 0, vcc
	v_exp_f32_e32 v136, v116
	v_fma_f32 v116, v117, s42, -v129
	v_fma_f32 v118, v118, s42, -v129
	v_sub_f32_e32 v125, v138, v125
	v_exp_f32_e32 v138, v116
	v_fma_f32 v116, v121, s42, -v129
	v_exp_f32_e32 v140, v118
	v_fma_f32 v118, v122, s42, -v129
	v_exp_f32_e32 v132, v116
	v_exp_f32_e32 v142, v118
	v_fma_f32 v118, v119, s42, -v129
	v_exp_f32_e32 v144, v118
	v_fma_f32 v118, v123, s42, -v129
	v_mul_f32_e32 v125, 0x3e38aa3b, v125
	v_exp_f32_e32 v134, v118
	v_exp_f32_e32 v146, v125
	v_pk_add_f32 v[116:117], v[130:131], v[136:137]
	v_pk_add_f32 v[120:121], v[138:139], v[132:133]
	v_pk_add_f32 v[118:119], v[140:141], v[142:143]
	v_pk_add_f32 v[116:117], v[120:121], v[116:117]
	v_pk_mul_f32 v[74:75], v[74:75], v[146:147] op_sel_hi:[1,0]
	v_pk_add_f32 v[116:117], v[118:119], v[116:117]
	v_pk_add_f32 v[118:119], v[144:145], v[134:135]
	v_pk_mul_f32 v[72:73], v[72:73], v[146:147] op_sel_hi:[1,0]
	v_pk_mul_f32 v[70:71], v[70:71], v[146:147] op_sel_hi:[1,0]
	v_pk_mul_f32 v[68:69], v[68:69], v[146:147] op_sel_hi:[1,0]
	v_pk_mul_f32 v[78:79], v[78:79], v[146:147] op_sel_hi:[1,0]
	v_pk_mul_f32 v[76:77], v[76:77], v[146:147] op_sel_hi:[1,0]
	v_pk_mul_f32 v[82:83], v[82:83], v[146:147] op_sel_hi:[1,0]
	v_pk_mul_f32 v[80:81], v[80:81], v[146:147] op_sel_hi:[1,0]
	v_mov_b32_e32 v147, v128
	v_pk_add_f32 v[116:117], v[118:119], v[116:117]
	v_cvt_pk_bf16_f32 v124, v131, v139
	v_pk_fma_f32 v[2:3], v[2:3], v[146:147], v[116:117]
	v_cvt_pk_bf16_f32 v125, v141, v145
	v_cvt_pk_bf16_f32 v126, v137, v133
	v_cvt_pk_bf16_f32 v127, v143, v135
	v_cvt_pk_bf16_f32 v116, v130, v138
	v_cvt_pk_bf16_f32 v117, v140, v144
	v_cvt_pk_bf16_f32 v118, v136, v132
	v_cvt_pk_bf16_f32 v119, v142, v134
	s_setprio 1
	v_add3_u32 v132, v1, v150, v206
	ds_read_b64_tr_b16 v[122:123], v132 offset:11776
	ds_read_b64_tr_b16 v[120:121], v132 offset:9216
	ds_read_b64_tr_b16 v[128:129], v132 offset:9248
	ds_read_b64_tr_b16 v[130:131], v132 offset:11808
	s_waitcnt lgkmcnt(2)
	v_mfma_f32_16x16x32_bf16 v[104:107], v[120:123], v[124:127], v[104:107]
	v_mfma_f32_16x16x32_bf16 v[72:75], v[120:123], v[116:119], v[72:75]
	ds_read_b64_tr_b16 v[120:121], v132 offset:9280
	ds_read_b64_tr_b16 v[122:123], v132 offset:11840
	s_waitcnt lgkmcnt(0)
; template <int NT, int NKK, int NDT, int MODE, bool MASK> ...
;     ...
;       __builtin_amdgcn_s_setprio(1);
; #pragma unroll
;       for (int t = 0; t < 2; ++t)
; #pragma unroll
;         for (int kk = 0; kk < NKK; ++kk) {
;           const bf16x8 kf = *(LAS const bf16x8*)(Kl + oz + (32 * st + 16 * t + r) * KSTR + (32 * kk + 8 * lg) * 2);
; #pragma unroll
;           for (int jj = 0; jj < JB; ++jj) s[jj][t] = mfma16(kf, qf[jh * JB + jj][kk], kk == 0 ? (f32x4){0.f, 0.f, 0.f, 0.f} : s[jj][t]);
;         }
;       __builtin_amdgcn_s_setprio(0);
;       bf16x8 pf[JB];
;       if (NT > JB) __builtin_amdgcn_sched_barrier(0);
; #pragma unroll
;       for (int jj = 0; jj < JB; ++jj) {
;         const int j = jh * JB + jj;
;         float mx = -INFINITY;
; #pragma unroll
;         for (int t = 0; t < 2; ++t)
; #pragma unroll
;           for (int i = 0; i < 4; ++i) {
;             if (MASK) { const int kp = kpos0 + 32 * st + 16 * t + 4 * lg + i; if (!mask_ok<MODE>(tq[j], kp, W)) s[jj][t][i] = -INFINITY; }
;             mx = fmaxf(mx, s[jj][t][i]);
;           }
;         mx = max_x16_x32(mx);
;         if (NT > 2 || __any(mx > m[j] + 8.0f / c)) {
;           const float mnew = fmaxf(m[j], mx);
;           const float ms2 = (mnew == -INFINITY) ? 0.f : mnew;
;           const float alpha = ex2((m[j] - ms2) * c);
;           m[j] = mnew; l[j] *= alpha;
; #pragma unroll
;           for (int dt = 0; dt < NDT; ++dt) o[j][dt] *= alpha;
;         }
;         const float mc = ((m[j] == -INFINITY) ? 0.f : m[j]) * c;
;         float p0[4], p1[4], ps = 0.f;
; #pragma unroll
;         for (int i = 0; i < 4; ++i) { p0[i] = ex2(s[jj][0][i] * c - mc); p1[i] = ex2(s[jj][1][i] * c - mc); ps += p0[i] + p1[i]; }
;         l[j] += ps;
;         pf[jj] = pack8(p0, p1);
;       }
;       if (NT > JB) __builtin_amdgcn_sched_barrier(0);
;       __builtin_amdgcn_s_setprio(1);
; #pragma unroll
;       for (int dt = 0; dt < NDT; ++dt) {
;         const s16x4 v0 = ds_tr(Vl + oz + (32 * st + 4 * lg + vq) * VSTR + (16 * dt + 4 * vp) * 2);
;         const s16x4 v1 = ds_tr(Vl + oz + (32 * st + 16 + 4 * lg + vq) * VSTR + (16 * dt + 4 * vp) * 2);
;         const bf16x8 vf = (bf16x8){v0[0], v0[1], v0[2], v0[3], v1[0], v1[1], v1[2], v1[3]};
; #pragma unroll
;         for (int jj = 0; jj < JB; ++jj) o[jh * JB + jj][dt] = mfma16(vf, pf[jj], o[jh * JB + jj][dt]);
;       }
;       __builtin_amdgcn_s_setprio(0);
	v_mfma_f32_16x16x32_bf16 v[108:111], v[120:123], v[124:127], v[108:111]
	v_mfma_f32_16x16x32_bf16 v[76:79], v[120:123], v[116:119], v[76:79]
	ds_read_b64_tr_b16 v[120:121], v132 offset:9312
	ds_read_b64_tr_b16 v[122:123], v132 offset:11872
	v_mfma_f32_16x16x32_bf16 v[100:103], v[128:131], v[124:127], v[100:103]
	v_mfma_f32_16x16x32_bf16 v[68:71], v[128:131], v[116:119], v[68:71]
	s_waitcnt lgkmcnt(0)
	v_mfma_f32_16x16x32_bf16 v[112:115], v[120:123], v[124:127], v[112:115]
	v_mfma_f32_16x16x32_bf16 v[80:83], v[120:123], v[116:119], v[80:83]
	s_setprio 0
	v_mov_b32_e32 v150, 0
	s_setprio 1
	v_add3_u32 v128, v207, v150, v151
	ds_read_b128 v[116:119], v128
	ds_read_b128 v[120:123], v128 offset:64
	s_waitcnt lgkmcnt(1)
	v_mfma_f32_16x16x32_bf16 v[124:127], v[116:119], v[28:31], 0
	v_mfma_f32_16x16x32_bf16 v[116:119], v[116:119], v[36:39], 0
	s_waitcnt lgkmcnt(0)
	v_mfma_f32_16x16x32_bf16 v[124:127], v[120:123], v[32:35], v[124:127]
	v_mfma_f32_16x16x32_bf16 v[116:119], v[120:123], v[40:43], v[116:119]
	ds_read_b128 v[120:123], v128 offset:2304
	ds_read_b128 v[128:131], v128 offset:2368
	s_waitcnt lgkmcnt(1)
	v_mfma_f32_16x16x32_bf16 v[132:135], v[120:123], v[28:31], 0
	v_mfma_f32_16x16x32_bf16 v[120:123], v[120:123], v[36:39], 0
	s_waitcnt lgkmcnt(0)
	v_mfma_f32_16x16x32_bf16 v[132:135], v[128:131], v[32:35], v[132:135]
	v_mfma_f32_16x16x32_bf16 v[120:123], v[128:131], v[40:43], v[120:123]
	s_setprio 0
	v_max3_f32 v128, v124, s81, v125
	v_max3_f32 v128, v128, v126, v127
	s_nop 3
	v_max3_f32 v128, v128, v132, v133
	v_max3_f32 v128, v128, v134, v135
	v_mov_b32_e32 v129, v128
	s_nop 1
	v_permlane16_swap_b32_e32 v128, v129
	v_max_f32_e32 v128, v128, v129
	v_mov_b32_e32 v129, v128
	s_nop 1
	v_permlane32_swap_b32_e32 v128, v129
	v_max3_f32 v192, v148, v128, v129
	v_cmp_eq_f32_e32 vcc, s81, v192
	s_nop 1
	v_cndmask_b32_e64 v128, v192, 0, vcc
	v_sub_f32_e32 v128, v148, v128
	v_mul_f32_e32 v128, 0x3e38aa3b, v128
	v_exp_f32_e32 v128, v128
	s_nop 0
	v_pk_mul_f32 v[90:91], v[90:91], v[128:129] op_sel_hi:[1,0]
	v_pk_mul_f32 v[88:89], v[88:89], v[128:129] op_sel_hi:[1,0]
	v_pk_mul_f32 v[86:87], v[86:87], v[128:129] op_sel_hi:[1,0]
	v_pk_mul_f32 v[84:85], v[84:85], v[128:129] op_sel_hi:[1,0]
	v_pk_mul_f32 v[94:95], v[94:95], v[128:129] op_sel_hi:[1,0]
	v_pk_mul_f32 v[92:93], v[92:93], v[128:129] op_sel_hi:[1,0]
	v_pk_mul_f32 v[98:99], v[98:99], v[128:129] op_sel_hi:[1,0]
	v_pk_mul_f32 v[96:97], v[96:97], v[128:129] op_sel_hi:[1,0]
	v_mul_f32_e32 v129, 0x3e38aa3b, v192
	v_cndmask_b32_e64 v129, v129, 0, vcc
	v_fma_f32 v124, v124, s42, -v129
	v_exp_f32_e32 v131, v124
	v_fma_f32 v124, v132, s42, -v129
	v_exp_f32_e32 v137, v124
	v_fma_f32 v124, v125, s42, -v129
	v_max3_f32 v125, v116, s81, v117
	v_max3_f32 v125, v125, v118, v119
	v_max3_f32 v125, v125, v120, v121
	v_exp_f32_e32 v139, v124
	v_fma_f32 v124, v133, s42, -v129
	v_max3_f32 v125, v125, v122, v123
	v_exp_f32_e32 v133, v124
	v_fma_f32 v124, v126, s42, -v129
	v_mov_b32_e32 v126, v125
	s_nop 1
	v_permlane16_swap_b32_e32 v125, v126
	v_max_f32_e32 v125, v125, v126
	v_mov_b32_e32 v126, v125
	v_exp_f32_e32 v141, v124
	v_fma_f32 v124, v134, s42, -v129
	v_permlane32_swap_b32_e32 v125, v126
	v_exp_f32_e32 v143, v124
	v_fma_f32 v124, v127, s42, -v129
	v_max3_f32 v193, v149, v125, v126
	v_exp_f32_e32 v145, v124
	v_fma_f32 v124, v135, s42, -v129
	v_cmp_eq_f32_e32 vcc, s81, v193
	v_mul_f32_e32 v129, 0x3e38aa3b, v193
	v_exp_f32_e32 v135, v124
	v_cndmask_b32_e64 v129, v129, 0, vcc
	v_fma_f32 v116, v116, s42, -v129
	v_exp_f32_e32 v130, v116
	v_fma_f32 v116, v120, s42, -v129
	v_exp_f32_e32 v136, v116
	v_fma_f32 v116, v117, s42, -v129
	v_fma_f32 v118, v118, s42, -v129
	v_exp_f32_e32 v138, v116
	v_fma_f32 v116, v121, s42, -v129
	v_exp_f32_e32 v140, v118
	v_fma_f32 v118, v122, s42, -v129
	v_cndmask_b32_e64 v125, v193, 0, vcc
	v_exp_f32_e32 v132, v116
	v_exp_f32_e32 v142, v118
	v_fma_f32 v118, v119, s42, -v129
	v_sub_f32_e32 v125, v149, v125
	v_exp_f32_e32 v144, v118
	v_fma_f32 v118, v123, s42, -v129
	v_mul_f32_e32 v125, 0x3e38aa3b, v125
	v_exp_f32_e32 v134, v118
	v_exp_f32_e32 v146, v125
	v_pk_add_f32 v[116:117], v[130:131], v[136:137]
	v_pk_add_f32 v[120:121], v[138:139], v[132:133]
	v_pk_add_f32 v[118:119], v[140:141], v[142:143]
	v_pk_add_f32 v[116:117], v[120:121], v[116:117]
	v_pk_mul_f32 v[58:59], v[58:59], v[146:147] op_sel_hi:[1,0]
	v_pk_add_f32 v[116:117], v[118:119], v[116:117]
	v_pk_add_f32 v[118:119], v[144:145], v[134:135]
	v_pk_mul_f32 v[56:57], v[56:57], v[146:147] op_sel_hi:[1,0]
	v_pk_mul_f32 v[54:55], v[54:55], v[146:147] op_sel_hi:[1,0]
	v_pk_mul_f32 v[52:53], v[52:53], v[146:147] op_sel_hi:[1,0]
	v_pk_mul_f32 v[62:63], v[62:63], v[146:147] op_sel_hi:[1,0]
	v_pk_mul_f32 v[60:61], v[60:61], v[146:147] op_sel_hi:[1,0]
	v_pk_mul_f32 v[66:67], v[66:67], v[146:147] op_sel_hi:[1,0]
	v_pk_mul_f32 v[64:65], v[64:65], v[146:147] op_sel_hi:[1,0]
	v_mov_b32_e32 v147, v128
	v_pk_add_f32 v[116:117], v[118:119], v[116:117]
	v_cvt_pk_bf16_f32 v124, v131, v139
	v_pk_fma_f32 v[184:185], v[184:185], v[146:147], v[116:117]
	v_cvt_pk_bf16_f32 v125, v141, v145
	v_cvt_pk_bf16_f32 v126, v137, v133
	v_cvt_pk_bf16_f32 v127, v143, v135
	v_cvt_pk_bf16_f32 v116, v130, v138
	v_cvt_pk_bf16_f32 v117, v140, v144
	v_cvt_pk_bf16_f32 v118, v136, v132
	v_cvt_pk_bf16_f32 v119, v142, v134
	s_setprio 1
	v_add3_u32 v1, v1, v150, v206
	ds_read_b64_tr_b16 v[122:123], v1 offset:11776
	ds_read_b64_tr_b16 v[120:121], v1 offset:9216
	ds_read_b64_tr_b16 v[128:129], v1 offset:9248
	ds_read_b64_tr_b16 v[130:131], v1 offset:11808
	s_waitcnt lgkmcnt(2)
	v_mfma_f32_16x16x32_bf16 v[88:91], v[120:123], v[124:127], v[88:91]
	v_mfma_f32_16x16x32_bf16 v[56:59], v[120:123], v[116:119], v[56:59]
	ds_read_b64_tr_b16 v[120:121], v1 offset:9280
	ds_read_b64_tr_b16 v[122:123], v1 offset:11840
	s_waitcnt lgkmcnt(0)
	v_mfma_f32_16x16x32_bf16 v[92:95], v[120:123], v[124:127], v[92:95]
	v_mfma_f32_16x16x32_bf16 v[60:63], v[120:123], v[116:119], v[60:63]
	ds_read_b64_tr_b16 v[120:121], v1 offset:9312
	ds_read_b64_tr_b16 v[122:123], v1 offset:11872
	v_mfma_f32_16x16x32_bf16 v[84:87], v[128:131], v[124:127], v[84:87]
	v_mfma_f32_16x16x32_bf16 v[52:55], v[128:131], v[116:119], v[52:55]
	s_waitcnt lgkmcnt(0)
	v_mfma_f32_16x16x32_bf16 v[96:99], v[120:123], v[124:127], v[96:99]
	v_mfma_f32_16x16x32_bf16 v[64:67], v[120:123], v[116:119], v[64:67]
	s_setprio 0
	s_mov_b32 s8, 32
	s_andn2_b64 vcc, exec, s[12:13]
	s_mov_b64 s[12:13], 0
	s_cbranch_vccz .LBB0_1269
; #define LAS __attribute__((address_space(3)))
; template <int NT, int NKK, int NDT, int MODE, bool MASK> ...
;     ...
; #pragma unroll 1
;   for (int st = 0; st < 2; ++st) {
; #pragma unroll
;     for (int jh = 0; jh < NT / JB; ++jh) {
;       int oz = 0; if (NT > JB) asm volatile("" : "+v"(oz));
;       f32x4 s[JB][2];
;       __builtin_amdgcn_s_setprio(1);
; #pragma unroll
;       for (int t = 0; t < 2; ++t)
; #pragma unroll
;         for (int kk = 0; kk < NKK; ++kk) {
;           const bf16x8 kf = *(LAS const bf16x8*)(Kl + oz + (32 * st + 16 * t + r) * KSTR + (32 * kk + 8 * lg) * 2);
; #pragma unroll
;           for (int jj = 0; jj < JB; ++jj) s[jj][t] = mfma16(kf, qf[jh * JB + jj][kk], kk == 0 ? (f32x4){0.f, 0.f, 0.f, 0.f} : s[jj][t]);
;         }
;       __builtin_amdgcn_s_setprio(0);
;       bf16x8 pf[JB];
;       if (NT > JB) __builtin_amdgcn_sched_barrier(0);
; #pragma unroll
;       for (int jj = 0; jj < JB; ++jj) {
;         const int j = jh * JB + jj;
;         float mx = -INFINITY;
; #pragma unroll
;         for (int t = 0; t < 2; ++t)
; #pragma unroll
;           for (int i = 0; i < 4; ++i) {
;             if (MASK) { const int kp = kpos0 + 32 * st + 16 * t + 4 * lg + i; if (!mask_ok<MODE>(tq[j], kp, W)) s[jj][t][i] = -INFINITY; }
;             mx = fmaxf(mx, s[jj][t][i]);
;           }
;         mx = max_x16_x32(mx);
;         if (NT > 2 || __any(mx > m[j] + 8.0f / c)) {
;           const float mnew = fmaxf(m[j], mx);
;           const float ms2 = (mnew == -INFINITY) ? 0.f : mnew;
;           const float alpha = ex2((m[j] - ms2) * c);
;           m[j] = mnew; l[j] *= alpha;
; #pragma unroll
;           for (int dt = 0; dt < NDT; ++dt) o[j][dt] *= alpha;
;         }
;         const float mc = ((m[j] == -INFINITY) ? 0.f : m[j]) * c;
;         float p0[4], p1[4], ps = 0.f;
; #pragma unroll
;         for (int i = 0; i < 4; ++i) { p0[i] = ex2(s[jj][0][i] * c - mc); p1[i] = ex2(s[jj][1][i] * c - mc); ps += p0[i] + p1[i]; }
;         l[j] += ps;
;         pf[jj] = pack8(p0, p1);
;       }
;       if (NT > JB) __builtin_amdgcn_sched_barrier(0);
;       __builtin_amdgcn_s_setprio(1);
; #pragma unroll
;       for (int dt = 0; dt < NDT; ++dt) {
;         const s16x4 v0 = ds_tr(Vl + oz + (32 * st + 4 * lg + vq) * VSTR + (16 * dt + 4 * vp) * 2);
;         const s16x4 v1 = ds_tr(Vl + oz + (32 * st + 16 + 4 * lg + vq) * VSTR + (16 * dt + 4 * vp) * 2);
	s_branch .Lrt_skip_2
	v_mov_b64_e32 v[154:155], v[106:107]
	v_mov_b64_e32 v[150:151], v[102:103]
	v_mov_b64_e32 v[166:167], v[110:111]
	v_mov_b64_e32 v[174:175], v[114:115]
	v_mov_b64_e32 v[122:123], v[74:75]
	v_mov_b64_e32 v[118:119], v[70:71]
	v_mov_b64_e32 v[134:135], v[78:79]
	v_mov_b64_e32 v[142:143], v[82:83]
	v_mov_b64_e32 v[162:163], v[90:91]
	v_mov_b64_e32 v[158:159], v[86:87]
	v_mov_b64_e32 v[170:171], v[94:95]
	v_mov_b64_e32 v[178:179], v[98:99]
	v_mov_b64_e32 v[130:131], v[58:59]
	v_mov_b64_e32 v[126:127], v[54:55]
	v_mov_b64_e32 v[138:139], v[62:63]
	v_mov_b64_e32 v[146:147], v[66:67]
	v_mov_b32_e32 v212, v191
	v_mov_b32_e32 v1, v190
	v_mov_b32_e32 v215, v193
	v_mov_b32_e32 v214, v192
	v_mov_b64_e32 v[194:195], v[2:3]
	v_mov_b64_e32 v[202:203], v[184:185]
	v_mov_b64_e32 v[152:153], v[104:105]
	v_mov_b64_e32 v[148:149], v[100:101]
	v_mov_b64_e32 v[164:165], v[108:109]
	v_mov_b64_e32 v[172:173], v[112:113]
	v_mov_b64_e32 v[120:121], v[72:73]
	v_mov_b64_e32 v[116:117], v[68:69]
	v_mov_b64_e32 v[132:133], v[76:77]
	v_mov_b64_e32 v[140:141], v[80:81]
	v_mov_b64_e32 v[160:161], v[88:89]
	v_mov_b64_e32 v[156:157], v[84:85]
	v_mov_b64_e32 v[168:169], v[92:93]
	v_mov_b64_e32 v[176:177], v[96:97]
	v_mov_b64_e32 v[128:129], v[56:57]
	v_mov_b64_e32 v[124:125], v[52:53]
	v_mov_b64_e32 v[136:137], v[60:61]
	v_mov_b64_e32 v[144:145], v[64:65]

; #define LAS __attribute__((address_space(3)))
; __device__ __forceinline__ float ex2(float x) { return __builtin_amdgcn_exp2f(x); }
; __device__ __forceinline__ f32x4 mfma16(bf16x8 a, bf16x8 b, f32x4 c) { return __builtin_amdgcn_mfma_f32_16x16x32_bf16(a, b, c, 0, 0, 0); }
;   __device__ __forceinline__ bf16_t* W() const { return (bf16_t*)(ws + WS_W); }
; template <int NT, int NKK, int NDT, int MODE, bool MASK> ...
;     ...
;       __builtin_amdgcn_s_setprio(1);
; #pragma unroll
;       for (int t = 0; t < 2; ++t)
; #pragma unroll
;         for (int kk = 0; kk < NKK; ++kk) {
;           const bf16x8 kf = *(LAS const bf16x8*)(Kl + oz + (32 * st + 16 * t + r) * KSTR + (32 * kk + 8 * lg) * 2);
; #pragma unroll
;           for (int jj = 0; jj < JB; ++jj) s[jj][t] = mfma16(kf, qf[jh * JB + jj][kk], kk == 0 ? (f32x4){0.f, 0.f, 0.f, 0.f} : s[jj][t]);
;         }
;       __builtin_amdgcn_s_setprio(0);
;       bf16x8 pf[JB];
;       if (NT > JB) __builtin_amdgcn_sched_barrier(0);
; #pragma unroll
;       for (int jj = 0; jj < JB; ++jj) {
;         const int j = jh * JB + jj;
;         float mx = -INFINITY;
; #pragma unroll
;         for (int t = 0; t < 2; ++t)
; #pragma unroll
;           for (int i = 0; i < 4; ++i) {
;             if (MASK) { const int kp = kpos0 + 32 * st + 16 * t + 4 * lg + i; if (!mask_ok<MODE>(tq[j], kp, W)) s[jj][t][i] = -INFINITY; }
;             mx = fmaxf(mx, s[jj][t][i]);
;           }
;         mx = max_x16_x32(mx);
;         if (NT > 2 || __any(mx > m[j] + 8.0f / c)) {
;           const float mnew = fmaxf(m[j], mx);
;           const float ms2 = (mnew == -INFINITY) ? 0.f : mnew;
;           const float alpha = ex2((m[j] - ms2) * c);
;           m[j] = mnew; l[j] *= alpha;
; #pragma unroll
;           for (int dt = 0; dt < NDT; ++dt) o[j][dt] *= alpha;
;         }
.LBB0_1281:
	v_mov_b32_e32 v197, v1
	v_or_b32_e32 v1, s8, v211
	v_cmp_le_i32_e32 vcc, v1, v182
	v_cmp_gt_i32_e64 s[12:13], v1, v208
	s_and_b64 vcc, vcc, s[12:13]
	v_cmp_lt_i32_e64 s[12:13], v1, v182
	v_cmp_ge_i32_e64 s[14:15], v1, v208
	v_or_b32_e32 v196, 2, v1
	s_and_b64 s[12:13], s[12:13], s[14:15]
	v_cmp_le_i32_e64 s[14:15], v196, v182
	v_cmp_gt_i32_e64 s[16:17], v196, v208
	v_or_b32_e32 v196, 3, v1
	s_and_b64 s[14:15], s[14:15], s[16:17]
	v_cmp_le_i32_e64 s[16:17], v196, v182
	v_cmp_gt_i32_e64 s[18:19], v196, v208
	v_or_b32_e32 v196, 16, v1
	s_and_b64 s[16:17], s[16:17], s[18:19]
	v_cmp_le_i32_e64 s[18:19], v196, v182
	v_cmp_gt_i32_e64 s[20:21], v196, v208
	v_or_b32_e32 v196, 17, v1
	s_and_b64 s[18:19], s[18:19], s[20:21]
	v_cmp_le_i32_e64 s[20:21], v196, v182
	v_cmp_gt_i32_e64 s[22:23], v196, v208
	v_or_b32_e32 v196, 18, v1
	s_and_b64 s[20:21], s[20:21], s[22:23]
	v_cmp_le_i32_e64 s[22:23], v196, v182
	v_cmp_gt_i32_e64 s[24:25], v196, v208
	v_or_b32_e32 v1, 19, v1
	s_and_b64 s[22:23], s[22:23], s[24:25]
	v_cmp_le_i32_e64 s[24:25], v1, v182
	v_cmp_gt_i32_e64 s[28:29], v1, v208
	v_or_b32_e32 v1, s8, v183
	v_or_b32_e32 v196, s8, v204
	v_mov_b32_e32 v246, 0
	v_mov_b32_e32 v199, v212
	v_mov_b32_e32 v232, v214
	v_mov_b32_e32 v235, v215
	s_and_b64 s[24:25], s[24:25], s[28:29]
	v_mad_u32_u24 v213, v196, s80, 0
	s_setprio 1
	v_mul_u32_u24_e32 v247, 0x90, v1
	v_add3_u32 v1, v207, v246, v247
	ds_read_b128 v[214:217], v1 offset:19456
	ds_read_b128 v[218:221], v1 offset:19520
	s_waitcnt lgkmcnt(1)
	v_mfma_f32_16x16x32_bf16 v[222:225], v[214:217], v[12:15], 0
	v_mfma_f32_16x16x32_bf16 v[214:217], v[214:217], v[20:23], 0
	s_waitcnt lgkmcnt(0)
	v_mfma_f32_16x16x32_bf16 v[222:225], v[218:221], v[16:19], v[222:225]
	v_mfma_f32_16x16x32_bf16 v[214:217], v[218:221], v[24:27], v[214:217]
	ds_read_b128 v[218:221], v1 offset:21760
	ds_read_b128 v[228:231], v1 offset:21824
	s_waitcnt lgkmcnt(1)
	v_mfma_f32_16x16x32_bf16 v[236:239], v[218:221], v[12:15], 0
	v_mfma_f32_16x16x32_bf16 v[218:221], v[218:221], v[20:23], 0
	s_waitcnt lgkmcnt(0)
	v_mfma_f32_16x16x32_bf16 v[236:239], v[228:231], v[16:19], v[236:239]
	v_mfma_f32_16x16x32_bf16 v[218:221], v[228:231], v[24:27], v[218:221]
	s_setprio 0
	v_mov_b32_e32 v196, s81
	v_cndmask_b32_e32 v212, v196, v222, vcc
	v_cndmask_b32_e64 v222, v200, v223, s[12:13]
	v_max3_f32 v1, v212, s81, v222
	v_cndmask_b32_e64 v223, v200, v224, s[14:15]
	v_cndmask_b32_e64 v224, v200, v225, s[16:17]
	v_max3_f32 v1, v1, v223, v224
	v_cndmask_b32_e64 v196, v196, v236, s[18:19]
	v_cndmask_b32_e64 v225, v200, v237, s[20:21]
	v_max3_f32 v1, v1, v196, v225
	v_cndmask_b32_e64 v228, v200, v238, s[22:23]
	v_cndmask_b32_e64 v230, v200, v239, s[24:25]
	v_max3_f32 v1, v1, v228, v230
	v_mov_b32_e32 v198, v1
	s_nop 1
	v_permlane16_swap_b32_e32 v1, v198
	v_max_f32_e32 v1, v1, v198
	v_mov_b32_e32 v198, v1
	s_nop 1
	v_permlane32_swap_b32_e32 v1, v198
	v_max3_f32 v1, v197, v1, v198
	v_cmp_eq_f32_e64 s[28:29], s81, v1
	v_cndmask_b32_e64 v215, v200, v215, s[12:13]
	v_cndmask_b32_e64 v216, v200, v216, s[14:15]
	v_cndmask_b32_e64 v198, v1, 0, s[28:29]
	v_sub_f32_e32 v197, v197, v198
	v_mul_f32_e32 v197, 0x3e38aa3b, v197
	v_exp_f32_e32 v198, v197
	v_mul_f32_e32 v197, 0x3e38aa3b, v1
	v_cndmask_b32_e64 v236, v197, 0, s[28:29]
	v_fma_f32 v196, v196, s42, -v236
	v_exp_f32_e32 v229, v196
	v_fma_f32 v196, v222, s42, -v236
	v_exp_f32_e32 v231, v196
	v_fma_f32 v196, v225, s42, -v236
	v_exp_f32_e32 v237, v196
	v_fma_f32 v196, v223, s42, -v236
	v_exp_f32_e32 v239, v196
	v_fma_f32 v196, v228, s42, -v236
	v_exp_f32_e32 v241, v196
	v_fma_f32 v196, v224, s42, -v236
	v_exp_f32_e32 v243, v196
	v_fma_f32 v196, v230, s42, -v236
	v_exp_f32_e32 v245, v196
	v_mov_b32_e32 v196, s81
	v_cndmask_b32_e32 v228, v196, v214, vcc
	v_max3_f32 v196, v228, s81, v215
	v_cndmask_b32_e64 v217, v200, v217, s[16:17]
	v_fma_f32 v197, v212, s42, -v236
	v_max3_f32 v212, v196, v216, v217
	v_mov_b32_e32 v196, s81
	v_cndmask_b32_e64 v218, v196, v218, s[18:19]
	v_cndmask_b32_e64 v219, v200, v219, s[20:21]
	v_max3_f32 v196, v212, v218, v219
	v_cndmask_b32_e64 v220, v200, v220, s[22:23]
	v_cndmask_b32_e64 v221, v200, v221, s[24:25]
	v_max3_f32 v196, v196, v220, v221
	v_mov_b32_e32 v212, v196
	s_nop 1
	v_permlane16_swap_b32_e32 v196, v212
	v_max_f32_e32 v196, v196, v212
	v_mov_b32_e32 v212, v196
	s_nop 1
	v_permlane32_swap_b32_e32 v196, v212
	v_max3_f32 v212, v199, v196, v212
	v_cmp_eq_f32_e64 s[28:29], s81, v212
	v_pk_mul_f32 v[154:155], v[154:155], v[198:199] op_sel_hi:[1,0]
	v_pk_mul_f32 v[152:153], v[152:153], v[198:199] op_sel_hi:[1,0]
	v_cndmask_b32_e64 v196, v212, 0, s[28:29]
	v_sub_f32_e32 v196, v199, v196
	v_mul_f32_e32 v196, 0x3e38aa3b, v196
	v_exp_f32_e32 v214, v196
	v_mul_f32_e32 v196, 0x3e38aa3b, v212
	v_pk_mul_f32 v[150:151], v[150:151], v[198:199] op_sel_hi:[1,0]
	v_pk_mul_f32 v[148:149], v[148:149], v[198:199] op_sel_hi:[1,0]
	v_pk_mul_f32 v[166:167], v[166:167], v[198:199] op_sel_hi:[1,0]
	v_pk_mul_f32 v[164:165], v[164:165], v[198:199] op_sel_hi:[1,0]
	v_pk_mul_f32 v[174:175], v[174:175], v[198:199] op_sel_hi:[1,0]
	v_pk_mul_f32 v[172:173], v[172:173], v[198:199] op_sel_hi:[1,0]
	v_cndmask_b32_e64 v199, v196, 0, s[28:29]
	v_pk_mul_f32 v[122:123], v[122:123], v[214:215] op_sel_hi:[1,0]
	v_pk_mul_f32 v[120:121], v[120:121], v[214:215] op_sel_hi:[1,0]
	v_pk_mul_f32 v[118:119], v[118:119], v[214:215] op_sel_hi:[1,0]
	v_pk_mul_f32 v[116:117], v[116:117], v[214:215] op_sel_hi:[1,0]
	v_pk_mul_f32 v[134:135], v[134:135], v[214:215] op_sel_hi:[1,0]
	v_pk_mul_f32 v[132:133], v[132:133], v[214:215] op_sel_hi:[1,0]
	v_pk_mul_f32 v[142:143], v[142:143], v[214:215] op_sel_hi:[1,0]
; #define LAS __attribute__((address_space(3)))
; template <int NT, int NKK, int NDT, int MODE, bool MASK> ...
;     ...
;       __builtin_amdgcn_s_setprio(1);
; #pragma unroll
;       for (int t = 0; t < 2; ++t)
; #pragma unroll
;         for (int kk = 0; kk < NKK; ++kk) {
;           const bf16x8 kf = *(LAS const bf16x8*)(Kl + oz + (32 * st + 16 * t + r) * KSTR + (32 * kk + 8 * lg) * 2);
; #pragma unroll
;           for (int jj = 0; jj < JB; ++jj) s[jj][t] = mfma16(kf, qf[jh * JB + jj][kk], kk == 0 ? (f32x4){0.f, 0.f, 0.f, 0.f} : s[jj][t]);
;         }
;       __builtin_amdgcn_s_setprio(0);
;       bf16x8 pf[JB];
;       if (NT > JB) __builtin_amdgcn_sched_barrier(0);
; #pragma unroll
;       for (int jj = 0; jj < JB; ++jj) {
;         const int j = jh * JB + jj;
;         float mx = -INFINITY;
; #pragma unroll
;         for (int t = 0; t < 2; ++t)
; #pragma unroll
;           for (int i = 0; i < 4; ++i) {
;             if (MASK) { const int kp = kpos0 + 32 * st + 16 * t + 4 * lg + i; if (!mask_ok<MODE>(tq[j], kp, W)) s[jj][t][i] = -INFINITY; }
;             mx = fmaxf(mx, s[jj][t][i]);
;           }
;         mx = max_x16_x32(mx);
;         if (NT > 2 || __any(mx > m[j] + 8.0f / c)) {
;           const float mnew = fmaxf(m[j], mx);
;           const float ms2 = (mnew == -INFINITY) ? 0.f : mnew;
;           const float alpha = ex2((m[j] - ms2) * c);
;           m[j] = mnew; l[j] *= alpha;
; #pragma unroll
;           for (int dt = 0; dt < NDT; ++dt) o[j][dt] *= alpha;
;         }
;         const float mc = ((m[j] == -INFINITY) ? 0.f : m[j]) * c;
;         float p0[4], p1[4], ps = 0.f;
; #pragma unroll
;         for (int i = 0; i < 4; ++i) { p0[i] = ex2(s[jj][0][i] * c - mc); p1[i] = ex2(s[jj][1][i] * c - mc); ps += p0[i] + p1[i]; }
;         l[j] += ps;
;         pf[jj] = pack8(p0, p1);
;       }
;       if (NT > JB) __builtin_amdgcn_sched_barrier(0);
;       __builtin_amdgcn_s_setprio(1);
; #pragma unroll
;       for (int dt = 0; dt < NDT; ++dt) {
;         const s16x4 v0 = ds_tr(Vl + oz + (32 * st + 4 * lg + vq) * VSTR + (16 * dt + 4 * vp) * 2);
;         const s16x4 v1 = ds_tr(Vl + oz + (32 * st + 16 + 4 * lg + vq) * VSTR + (16 * dt + 4 * vp) * 2);
;         const bf16x8 vf = (bf16x8){v0[0], v0[1], v0[2], v0[3], v1[0], v1[1], v1[2], v1[3]};
; #pragma unroll
;         for (int jj = 0; jj < JB; ++jj) o[jh * JB + jj][dt] = mfma16(vf, pf[jj], o[jh * JB + jj][dt]);
	v_pk_mul_f32 v[140:141], v[140:141], v[214:215] op_sel_hi:[1,0]
	v_fma_f32 v215, v215, s42, -v199
	v_fma_f32 v196, v228, s42, -v199
	v_fma_f32 v218, v218, s42, -v199
	v_exp_f32_e32 v230, v215
	v_fma_f32 v215, v219, s42, -v199
	v_exp_f32_e32 v197, v197
	v_exp_f32_e32 v196, v196
	v_exp_f32_e32 v228, v218
	v_exp_f32_e32 v236, v215
	v_fma_f32 v215, v216, s42, -v199
	v_exp_f32_e32 v238, v215
	v_fma_f32 v215, v220, s42, -v199
	v_exp_f32_e32 v240, v215
	v_fma_f32 v215, v217, s42, -v199
	v_fma_f32 v199, v221, s42, -v199
	v_exp_f32_e32 v242, v215
	v_exp_f32_e32 v244, v199
	v_mov_b32_e32 v215, v198
	v_pk_add_f32 v[198:199], v[196:197], v[228:229]
	v_pk_add_f32 v[216:217], v[230:231], v[236:237]
	v_cvt_pk_bf16_f32 v222, v197, v231
	v_pk_add_f32 v[198:199], v[216:217], v[198:199]
	v_pk_add_f32 v[216:217], v[238:239], v[240:241]
	v_cvt_pk_bf16_f32 v223, v239, v243
	v_pk_add_f32 v[198:199], v[216:217], v[198:199]
	v_pk_add_f32 v[216:217], v[242:243], v[244:245]
	v_cvt_pk_bf16_f32 v224, v229, v237
	v_pk_add_f32 v[198:199], v[216:217], v[198:199]
	v_cvt_pk_bf16_f32 v225, v241, v245
	v_pk_fma_f32 v[194:195], v[194:195], v[214:215], v[198:199]
	v_cvt_pk_bf16_f32 v214, v196, v230
	v_cvt_pk_bf16_f32 v215, v238, v242
	v_cvt_pk_bf16_f32 v216, v228, v236
	v_cvt_pk_bf16_f32 v217, v240, v244
	s_setprio 1
	v_add3_u32 v196, v213, v246, v206
	ds_read_b64_tr_b16 v[220:221], v196 offset:31232
	ds_read_b64_tr_b16 v[218:219], v196 offset:28672
	ds_read_b64_tr_b16 v[228:229], v196 offset:28704
	ds_read_b64_tr_b16 v[230:231], v196 offset:31264
	s_waitcnt lgkmcnt(2)
	v_mfma_f32_16x16x32_bf16 v[152:155], v[218:221], v[222:225], v[152:155]
	v_mfma_f32_16x16x32_bf16 v[120:123], v[218:221], v[214:217], v[120:123]
	ds_read_b64_tr_b16 v[218:219], v196 offset:28736
	ds_read_b64_tr_b16 v[220:221], v196 offset:31296
	s_waitcnt lgkmcnt(0)
	v_mfma_f32_16x16x32_bf16 v[164:167], v[218:221], v[222:225], v[164:167]
	v_mfma_f32_16x16x32_bf16 v[132:135], v[218:221], v[214:217], v[132:135]
	ds_read_b64_tr_b16 v[218:219], v196 offset:28768
	ds_read_b64_tr_b16 v[220:221], v196 offset:31328
	v_mfma_f32_16x16x32_bf16 v[148:151], v[228:231], v[222:225], v[148:151]
	v_mfma_f32_16x16x32_bf16 v[116:119], v[228:231], v[214:217], v[116:119]
	s_waitcnt lgkmcnt(0)
	v_mfma_f32_16x16x32_bf16 v[172:175], v[218:221], v[222:225], v[172:175]
	v_mfma_f32_16x16x32_bf16 v[140:143], v[218:221], v[214:217], v[140:143]
	s_setprio 0
	v_mov_b32_e32 v248, 0
	s_setprio 1
	v_add3_u32 v196, v207, v248, v247
	ds_read_b128 v[214:217], v196 offset:19456
	ds_read_b128 v[218:221], v196 offset:19520
	ds_read_b128 v[228:231], v196 offset:21760
	ds_read_b128 v[236:239], v196 offset:21824
	s_waitcnt lgkmcnt(3)
	v_mfma_f32_16x16x32_bf16 v[222:225], v[214:217], v[28:31], 0
	v_mfma_f32_16x16x32_bf16 v[214:217], v[214:217], v[36:39], 0
	s_waitcnt lgkmcnt(1)
	v_mfma_f32_16x16x32_bf16 v[240:243], v[228:231], v[28:31], 0
	v_mfma_f32_16x16x32_bf16 v[228:231], v[228:231], v[36:39], 0
	v_mfma_f32_16x16x32_bf16 v[222:225], v[218:221], v[32:35], v[222:225]
	v_mfma_f32_16x16x32_bf16 v[216:219], v[218:221], v[40:43], v[214:217]
	s_waitcnt lgkmcnt(0)
; __device__ __forceinline__ float ex2(float x) { return __builtin_amdgcn_exp2f(x); }
; __device__ __forceinline__ f32x4 mfma16(bf16x8 a, bf16x8 b, f32x4 c) { return __builtin_amdgcn_mfma_f32_16x16x32_bf16(a, b, c, 0, 0, 0); }
; __device__ __forceinline__ s16x4 ds_tr(LAS const unsigned char* p) { return __builtin_bit_cast(s16x4, __builtin_amdgcn_ds_read_tr16_b64_v4i16((LAS v4i16_t*)p)); }
;   __device__ __forceinline__ bf16_t* W() const { return (bf16_t*)(ws + WS_W); }
; template <int NT, int NKK, int NDT, int MODE, bool MASK> ...
;     ...
;       for (int jj = 0; jj < JB; ++jj) {
;         const int j = jh * JB + jj;
;         float mx = -INFINITY;
; #pragma unroll
;         for (int t = 0; t < 2; ++t)
; #pragma unroll
;           for (int i = 0; i < 4; ++i) {
;             if (MASK) { const int kp = kpos0 + 32 * st + 16 * t + 4 * lg + i; if (!mask_ok<MODE>(tq[j], kp, W)) s[jj][t][i] = -INFINITY; }
;             mx = fmaxf(mx, s[jj][t][i]);
;           }
;         mx = max_x16_x32(mx);
;         if (NT > 2 || __any(mx > m[j] + 8.0f / c)) {
;           const float mnew = fmaxf(m[j], mx);
;           const float ms2 = (mnew == -INFINITY) ? 0.f : mnew;
;           const float alpha = ex2((m[j] - ms2) * c);
;           m[j] = mnew; l[j] *= alpha;
; #pragma unroll
;           for (int dt = 0; dt < NDT; ++dt) o[j][dt] *= alpha;
;         }
;         const float mc = ((m[j] == -INFINITY) ? 0.f : m[j]) * c;
;         float p0[4], p1[4], ps = 0.f;
; #pragma unroll
;         for (int i = 0; i < 4; ++i) { p0[i] = ex2(s[jj][0][i] * c - mc); p1[i] = ex2(s[jj][1][i] * c - mc); ps += p0[i] + p1[i]; }
;         l[j] += ps;
;         pf[jj] = pack8(p0, p1);
;       }
;       if (NT > JB) __builtin_amdgcn_sched_barrier(0);
;       __builtin_amdgcn_s_setprio(1);
; #pragma unroll
;       for (int dt = 0; dt < NDT; ++dt) {
;         const s16x4 v0 = ds_tr(Vl + oz + (32 * st + 4 * lg + vq) * VSTR + (16 * dt + 4 * vp) * 2);
;         const s16x4 v1 = ds_tr(Vl + oz + (32 * st + 16 + 4 * lg + vq) * VSTR + (16 * dt + 4 * vp) * 2);
;         const bf16x8 vf = (bf16x8){v0[0], v0[1], v0[2], v0[3], v1[0], v1[1], v1[2], v1[3]};
; #pragma unroll
;         for (int jj = 0; jj < JB; ++jj) o[jh * JB + jj][dt] = mfma16(vf, pf[jj], o[jh * JB + jj][dt]);
;       }
;       __builtin_amdgcn_s_setprio(0);
;       if (NT > JB) __builtin_amdgcn_sched_barrier(0);
	v_mfma_f32_16x16x32_bf16 v[240:243], v[236:239], v[32:35], v[240:243]
	v_mfma_f32_16x16x32_bf16 v[228:231], v[236:239], v[40:43], v[228:231]
	s_setprio 0
	v_mov_b32_e32 v196, s81
	s_nop 0
	v_cndmask_b32_e32 v197, v196, v222, vcc
	v_cndmask_b32_e64 v199, v200, v223, s[12:13]
	v_max3_f32 v196, v197, s81, v199
	v_cndmask_b32_e64 v215, v200, v224, s[14:15]
	v_cndmask_b32_e64 v220, v200, v225, s[16:17]
	v_max3_f32 v198, v196, v215, v220
	v_mov_b32_e32 v196, s81
	v_cndmask_b32_e64 v196, v196, v240, s[18:19]
	v_cndmask_b32_e64 v221, v200, v241, s[20:21]
	v_max3_f32 v198, v198, v196, v221
	v_cndmask_b32_e64 v222, v200, v242, s[22:23]
	v_cndmask_b32_e64 v223, v200, v243, s[24:25]
	v_max3_f32 v198, v198, v222, v223
	v_mov_b32_e32 v214, v198
	s_nop 1
	v_permlane16_swap_b32_e32 v198, v214
	v_max_f32_e32 v198, v198, v214
	v_mov_b32_e32 v214, v198
	s_nop 1
	v_permlane32_swap_b32_e32 v198, v214
	v_max3_f32 v214, v232, v198, v214
	v_cmp_eq_f32_e64 s[28:29], s81, v214
	v_mul_f32_e32 v224, 0x3e38aa3b, v214
	v_cndmask_b32_e64 v217, v200, v217, s[12:13]
	v_cndmask_b32_e64 v224, v224, 0, s[28:29]
	v_fma_f32 v196, v196, s42, -v224
	v_cndmask_b32_e64 v198, v214, 0, s[28:29]
	v_exp_f32_e32 v225, v196
	v_fma_f32 v196, v199, s42, -v224
	v_sub_f32_e32 v198, v232, v198
	v_exp_f32_e32 v237, v196
	v_fma_f32 v196, v221, s42, -v224
	v_mul_f32_e32 v198, 0x3e38aa3b, v198
	v_exp_f32_e32 v239, v196
	v_fma_f32 v196, v215, s42, -v224
	v_exp_f32_e32 v198, v198
	v_exp_f32_e32 v241, v196
	v_fma_f32 v196, v222, s42, -v224
	v_exp_f32_e32 v243, v196
	v_fma_f32 v196, v220, s42, -v224
	v_exp_f32_e32 v245, v196
	v_fma_f32 v196, v223, s42, -v224
	v_exp_f32_e32 v247, v196
	v_mov_b32_e32 v196, s81
	v_pk_mul_f32 v[162:163], v[162:163], v[198:199] op_sel_hi:[1,0]
	v_pk_mul_f32 v[160:161], v[160:161], v[198:199] op_sel_hi:[1,0]
	v_pk_mul_f32 v[158:159], v[158:159], v[198:199] op_sel_hi:[1,0]
	v_pk_mul_f32 v[156:157], v[156:157], v[198:199] op_sel_hi:[1,0]
	v_pk_mul_f32 v[170:171], v[170:171], v[198:199] op_sel_hi:[1,0]
	v_pk_mul_f32 v[168:169], v[168:169], v[198:199] op_sel_hi:[1,0]
	v_pk_mul_f32 v[178:179], v[178:179], v[198:199] op_sel_hi:[1,0]
	v_pk_mul_f32 v[176:177], v[176:177], v[198:199] op_sel_hi:[1,0]
	v_cndmask_b32_e32 v199, v196, v216, vcc
	v_max3_f32 v196, v199, s81, v217
	v_cndmask_b32_e64 v218, v200, v218, s[14:15]
	v_cndmask_b32_e64 v219, v200, v219, s[16:17]
	v_max3_f32 v215, v196, v218, v219
	v_mov_b32_e32 v196, s81
	v_fma_f32 v197, v197, s42, -v224
	v_cndmask_b32_e64 v224, v196, v228, s[18:19]
	v_cndmask_b32_e64 v228, v200, v229, s[20:21]
	v_max3_f32 v196, v215, v224, v228
	v_cndmask_b32_e64 v229, v200, v230, s[22:23]
	v_cndmask_b32_e64 v230, v200, v231, s[24:25]
	v_max3_f32 v196, v196, v229, v230
	v_mov_b32_e32 v215, v196
	s_nop 1
	v_permlane16_swap_b32_e32 v196, v215
	v_max_f32_e32 v196, v196, v215
	v_mov_b32_e32 v215, v196
	s_nop 1
	v_permlane32_swap_b32_e32 v196, v215
	v_max3_f32 v215, v235, v196, v215
	v_cmp_eq_f32_e32 vcc, s81, v215
	v_exp_f32_e32 v197, v197
	v_cvt_pk_bf16_f32 v221, v241, v245
	v_cndmask_b32_e64 v196, v215, 0, vcc
	v_sub_f32_e32 v196, v235, v196
	v_mul_f32_e32 v196, 0x3e38aa3b, v196
	v_exp_f32_e32 v216, v196
	v_mul_f32_e32 v196, 0x3e38aa3b, v215
	v_cndmask_b32_e64 v231, v196, 0, vcc
	v_fma_f32 v196, v199, s42, -v231
	v_fma_f32 v199, v224, s42, -v231
	v_exp_f32_e32 v224, v199
	v_fma_f32 v199, v217, s42, -v231
	v_exp_f32_e32 v236, v199
	v_fma_f32 v199, v228, s42, -v231
	v_exp_f32_e32 v238, v199
	v_fma_f32 v199, v218, s42, -v231
	v_exp_f32_e32 v196, v196
	v_exp_f32_e32 v240, v199
	v_fma_f32 v199, v229, s42, -v231
	v_exp_f32_e32 v242, v199
	v_fma_f32 v199, v219, s42, -v231
	v_exp_f32_e32 v244, v199
	v_fma_f32 v199, v230, s42, -v231
	v_exp_f32_e32 v246, v199
	v_pk_mul_f32 v[130:131], v[130:131], v[216:217] op_sel_hi:[1,0]
	v_pk_mul_f32 v[128:129], v[128:129], v[216:217] op_sel_hi:[1,0]
	v_pk_mul_f32 v[126:127], v[126:127], v[216:217] op_sel_hi:[1,0]
	v_pk_mul_f32 v[124:125], v[124:125], v[216:217] op_sel_hi:[1,0]
	v_pk_mul_f32 v[138:139], v[138:139], v[216:217] op_sel_hi:[1,0]
	v_pk_mul_f32 v[136:137], v[136:137], v[216:217] op_sel_hi:[1,0]
	v_pk_mul_f32 v[146:147], v[146:147], v[216:217] op_sel_hi:[1,0]
	v_pk_mul_f32 v[144:145], v[144:145], v[216:217] op_sel_hi:[1,0]
	v_mov_b32_e32 v217, v198
	v_pk_add_f32 v[198:199], v[196:197], v[224:225]
	v_pk_add_f32 v[218:219], v[236:237], v[238:239]
	v_cvt_pk_bf16_f32 v220, v197, v237
	v_pk_add_f32 v[198:199], v[218:219], v[198:199]
	v_pk_add_f32 v[218:219], v[240:241], v[242:243]
	v_cvt_pk_bf16_f32 v222, v225, v239
	v_pk_add_f32 v[198:199], v[218:219], v[198:199]
	v_pk_add_f32 v[218:219], v[244:245], v[246:247]
	v_cvt_pk_bf16_f32 v223, v243, v247
	v_pk_add_f32 v[198:199], v[218:219], v[198:199]
	v_cvt_pk_bf16_f32 v218, v224, v238
	v_pk_fma_f32 v[202:203], v[202:203], v[216:217], v[198:199]
	v_cvt_pk_bf16_f32 v216, v196, v236
	v_cvt_pk_bf16_f32 v217, v240, v244
	v_cvt_pk_bf16_f32 v219, v242, v246
	s_setprio 1
	v_add3_u32 v196, v213, v248, v206
	ds_read_b64_tr_b16 v[230:231], v196 offset:31232
	ds_read_b64_tr_b16 v[228:229], v196 offset:28672
	ds_read_b64_tr_b16 v[236:237], v196 offset:28704
	ds_read_b64_tr_b16 v[238:239], v196 offset:31264
	s_waitcnt lgkmcnt(2)
	v_mfma_f32_16x16x32_bf16 v[160:163], v[228:231], v[220:223], v[160:163]
	v_mfma_f32_16x16x32_bf16 v[128:131], v[228:231], v[216:219], v[128:131]
	ds_read_b64_tr_b16 v[228:229], v196 offset:28736
	ds_read_b64_tr_b16 v[230:231], v196 offset:31296
	s_waitcnt lgkmcnt(0)
	v_mfma_f32_16x16x32_bf16 v[168:171], v[228:231], v[220:223], v[168:171]
	v_mfma_f32_16x16x32_bf16 v[136:139], v[228:231], v[216:219], v[136:139]
	ds_read_b64_tr_b16 v[228:229], v196 offset:28768
	ds_read_b64_tr_b16 v[230:231], v196 offset:31328
	v_mfma_f32_16x16x32_bf16 v[156:159], v[236:239], v[220:223], v[156:159]
	v_mfma_f32_16x16x32_bf16 v[124:127], v[236:239], v[216:219], v[124:127]
	s_waitcnt lgkmcnt(0)
	v_mfma_f32_16x16x32_bf16 v[176:179], v[228:231], v[220:223], v[176:179]
	v_mfma_f32_16x16x32_bf16 v[144:147], v[228:231], v[216:219], v[144:147]
	s_setprio 0
	s_mov_b32 s8, 32
	s_andn2_b64 vcc, exec, s[64:65]
	s_mov_b64 s[64:65], 0
	s_cbranch_vccz .LBB0_1281
	s_mov_b64 s[12:13], 0

; #define LAS __attribute__((address_space(3)))
; template <int NT, int NKK, int NDT, int MODE, bool MASK> ...
;     ...
;       __builtin_amdgcn_s_setprio(1);
; #pragma unroll
;       for (int t = 0; t < 2; ++t)
; #pragma unroll
;         for (int kk = 0; kk < NKK; ++kk) {
;           const bf16x8 kf = *(LAS const bf16x8*)(Kl + oz + (32 * st + 16 * t + r) * KSTR + (32 * kk + 8 * lg) * 2);
; #pragma unroll
;           for (int jj = 0; jj < JB; ++jj) s[jj][t] = mfma16(kf, qf[jh * JB + jj][kk], kk == 0 ? (f32x4){0.f, 0.f, 0.f, 0.f} : s[jj][t]);
;         }
;       __builtin_amdgcn_s_setprio(0);
;       bf16x8 pf[JB];
;       if (NT > JB) __builtin_amdgcn_sched_barrier(0);
; #pragma unroll
;       for (int jj = 0; jj < JB; ++jj) {
;         const int j = jh * JB + jj;
;         float mx = -INFINITY;
; #pragma unroll
;         for (int t = 0; t < 2; ++t)
; #pragma unroll
;           for (int i = 0; i < 4; ++i) {
;             if (MASK) { const int kp = kpos0 + 32 * st + 16 * t + 4 * lg + i; if (!mask_ok<MODE>(tq[j], kp, W)) s[jj][t][i] = -INFINITY; }
;             mx = fmaxf(mx, s[jj][t][i]);
;           }
;         mx = max_x16_x32(mx);
;         if (NT > 2 || __any(mx > m[j] + 8.0f / c)) {
;           const float mnew = fmaxf(m[j], mx);
;           const float ms2 = (mnew == -INFINITY) ? 0.f : mnew;
;           const float alpha = ex2((m[j] - ms2) * c);
;           m[j] = mnew; l[j] *= alpha;
; #pragma unroll
;           for (int dt = 0; dt < NDT; ++dt) o[j][dt] *= alpha;
;         }
;         const float mc = ((m[j] == -INFINITY) ? 0.f : m[j]) * c;
;         float p0[4], p1[4], ps = 0.f;
; #pragma unroll
;         for (int i = 0; i < 4; ++i) { p0[i] = ex2(s[jj][0][i] * c - mc); p1[i] = ex2(s[jj][1][i] * c - mc); ps += p0[i] + p1[i]; }
;         l[j] += ps;
;         pf[jj] = pack8(p0, p1);
;       }
;       if (NT > JB) __builtin_amdgcn_sched_barrier(0);
;       __builtin_amdgcn_s_setprio(1);
; #pragma unroll
;       for (int dt = 0; dt < NDT; ++dt) {
;         const s16x4 v0 = ds_tr(Vl + oz + (32 * st + 4 * lg + vq) * VSTR + (16 * dt + 4 * vp) * 2);
;         const s16x4 v1 = ds_tr(Vl + oz + (32 * st + 16 + 4 * lg + vq) * VSTR + (16 * dt + 4 * vp) * 2);
;         const bf16x8 vf = (bf16x8){v0[0], v0[1], v0[2], v0[3], v1[0], v1[1], v1[2], v1[3]};
; #pragma unroll
;         for (int jj = 0; jj < JB; ++jj) o[jh * JB + jj][dt] = mfma16(vf, pf[jj], o[jh * JB + jj][dt]);
.LBB0_1285:
	v_or_b32_e32 v1, s8, v204
	v_mov_b32_e32 v150, 0
	v_mov_b32_e32 v136, v190
	v_mov_b32_e32 v138, v191
	v_mov_b32_e32 v148, v192
	v_mov_b32_e32 v149, v193
	v_or_b32_e32 v116, s8, v183
	v_mad_u32_u24 v1, v1, s80, 0
	s_setprio 1
	v_mul_u32_u24_e32 v151, 0x90, v116
	v_add3_u32 v128, v207, v150, v151
	ds_read_b128 v[116:119], v128 offset:19456
	ds_read_b128 v[120:123], v128 offset:19520
	s_waitcnt lgkmcnt(1)
	v_mfma_f32_16x16x32_bf16 v[124:127], v[116:119], v[12:15], 0
	v_mfma_f32_16x16x32_bf16 v[116:119], v[116:119], v[20:23], 0
	s_waitcnt lgkmcnt(0)
	v_mfma_f32_16x16x32_bf16 v[124:127], v[120:123], v[16:19], v[124:127]
	v_mfma_f32_16x16x32_bf16 v[116:119], v[120:123], v[24:27], v[116:119]
	ds_read_b128 v[120:123], v128 offset:21760
	ds_read_b128 v[128:131], v128 offset:21824
	s_waitcnt lgkmcnt(1)
	v_mfma_f32_16x16x32_bf16 v[132:135], v[120:123], v[12:15], 0
	v_mfma_f32_16x16x32_bf16 v[120:123], v[120:123], v[20:23], 0
	s_waitcnt lgkmcnt(0)
	v_mfma_f32_16x16x32_bf16 v[132:135], v[128:131], v[16:19], v[132:135]
	v_mfma_f32_16x16x32_bf16 v[120:123], v[128:131], v[24:27], v[120:123]
	s_setprio 0
	v_max3_f32 v128, v124, s81, v125
	v_max3_f32 v128, v128, v126, v127
	s_nop 3
	v_max3_f32 v128, v128, v132, v133
	v_max3_f32 v128, v128, v134, v135
	v_mov_b32_e32 v129, v128
	s_nop 1
	v_permlane16_swap_b32_e32 v128, v129
	v_max_f32_e32 v128, v128, v129
	v_mov_b32_e32 v129, v128
	s_nop 1
	v_permlane32_swap_b32_e32 v128, v129
	v_max3_f32 v190, v136, v128, v129
	v_cmp_eq_f32_e32 vcc, s81, v190
	s_nop 1
	v_cndmask_b32_e64 v128, v190, 0, vcc
	v_sub_f32_e32 v128, v136, v128
	v_mul_f32_e32 v128, 0x3e38aa3b, v128
	v_exp_f32_e32 v128, v128
	s_nop 0
	v_pk_mul_f32 v[106:107], v[106:107], v[128:129] op_sel_hi:[1,0]
	v_pk_mul_f32 v[104:105], v[104:105], v[128:129] op_sel_hi:[1,0]
	v_pk_mul_f32 v[102:103], v[102:103], v[128:129] op_sel_hi:[1,0]
	v_pk_mul_f32 v[100:101], v[100:101], v[128:129] op_sel_hi:[1,0]
	v_pk_mul_f32 v[110:111], v[110:111], v[128:129] op_sel_hi:[1,0]
	v_pk_mul_f32 v[108:109], v[108:109], v[128:129] op_sel_hi:[1,0]
	v_pk_mul_f32 v[114:115], v[114:115], v[128:129] op_sel_hi:[1,0]
	v_pk_mul_f32 v[112:113], v[112:113], v[128:129] op_sel_hi:[1,0]
	v_mul_f32_e32 v129, 0x3e38aa3b, v190
	v_cndmask_b32_e64 v129, v129, 0, vcc
	v_fma_f32 v124, v124, s42, -v129
	v_exp_f32_e32 v131, v124
	v_fma_f32 v124, v132, s42, -v129
	v_exp_f32_e32 v137, v124
	v_fma_f32 v124, v125, s42, -v129
	v_max3_f32 v125, v116, s81, v117
	v_max3_f32 v125, v125, v118, v119
	v_max3_f32 v125, v125, v120, v121
	v_exp_f32_e32 v139, v124
	v_fma_f32 v124, v133, s42, -v129
	v_max3_f32 v125, v125, v122, v123
	v_exp_f32_e32 v133, v124
	v_fma_f32 v124, v126, s42, -v129
	v_mov_b32_e32 v126, v125
	s_nop 1
	v_permlane16_swap_b32_e32 v125, v126
	v_max_f32_e32 v125, v125, v126
	v_mov_b32_e32 v126, v125
	v_exp_f32_e32 v141, v124
	v_fma_f32 v124, v134, s42, -v129
	v_permlane32_swap_b32_e32 v125, v126
	v_exp_f32_e32 v143, v124
	v_fma_f32 v124, v127, s42, -v129
	v_max3_f32 v191, v138, v125, v126
	v_exp_f32_e32 v145, v124
	v_fma_f32 v124, v135, s42, -v129
	v_cmp_eq_f32_e32 vcc, s81, v191
	v_mul_f32_e32 v129, 0x3e38aa3b, v191
	v_exp_f32_e32 v135, v124
	v_cndmask_b32_e64 v129, v129, 0, vcc
	v_fma_f32 v116, v116, s42, -v129
	v_exp_f32_e32 v130, v116
	v_fma_f32 v116, v120, s42, -v129
	v_cndmask_b32_e64 v125, v191, 0, vcc
	v_exp_f32_e32 v136, v116
	v_fma_f32 v116, v117, s42, -v129
	v_sub_f32_e32 v125, v138, v125
	v_exp_f32_e32 v138, v116
	v_fma_f32 v116, v121, s42, -v129
	v_exp_f32_e32 v132, v116
	v_fma_f32 v116, v118, s42, -v129
	v_exp_f32_e32 v140, v116
	v_fma_f32 v116, v122, s42, -v129
	v_exp_f32_e32 v142, v116
	v_fma_f32 v116, v119, s42, -v129
	v_exp_f32_e32 v144, v116
	v_fma_f32 v116, v123, s42, -v129
	v_mul_f32_e32 v125, 0x3e38aa3b, v125
	v_exp_f32_e32 v134, v116
	v_exp_f32_e32 v146, v125
	v_pk_add_f32 v[116:117], v[130:131], v[136:137]
	v_pk_add_f32 v[118:119], v[138:139], v[132:133]
	v_pk_mul_f32 v[74:75], v[74:75], v[146:147] op_sel_hi:[1,0]
	v_pk_add_f32 v[116:117], v[118:119], v[116:117]
	v_pk_add_f32 v[118:119], v[140:141], v[142:143]
	v_pk_mul_f32 v[72:73], v[72:73], v[146:147] op_sel_hi:[1,0]
	v_pk_add_f32 v[116:117], v[118:119], v[116:117]
	v_pk_add_f32 v[118:119], v[144:145], v[134:135]
	v_pk_mul_f32 v[70:71], v[70:71], v[146:147] op_sel_hi:[1,0]
	v_pk_mul_f32 v[68:69], v[68:69], v[146:147] op_sel_hi:[1,0]
	v_pk_mul_f32 v[78:79], v[78:79], v[146:147] op_sel_hi:[1,0]
	v_pk_mul_f32 v[76:77], v[76:77], v[146:147] op_sel_hi:[1,0]
	v_pk_mul_f32 v[82:83], v[82:83], v[146:147] op_sel_hi:[1,0]
	v_pk_mul_f32 v[80:81], v[80:81], v[146:147] op_sel_hi:[1,0]
	v_mov_b32_e32 v147, v128
	v_pk_add_f32 v[116:117], v[118:119], v[116:117]
	v_cvt_pk_bf16_f32 v124, v131, v139
	v_pk_fma_f32 v[2:3], v[2:3], v[146:147], v[116:117]
	v_cvt_pk_bf16_f32 v125, v141, v145
	v_cvt_pk_bf16_f32 v126, v137, v133
	v_cvt_pk_bf16_f32 v127, v143, v135
	v_cvt_pk_bf16_f32 v116, v130, v138
	v_cvt_pk_bf16_f32 v117, v140, v144
	v_cvt_pk_bf16_f32 v118, v136, v132
	v_cvt_pk_bf16_f32 v119, v142, v134
	s_setprio 1
	v_add3_u32 v132, v1, v150, v206
	ds_read_b64_tr_b16 v[122:123], v132 offset:31232
	ds_read_b64_tr_b16 v[120:121], v132 offset:28672
	ds_read_b64_tr_b16 v[128:129], v132 offset:28704
	ds_read_b64_tr_b16 v[130:131], v132 offset:31264
	s_waitcnt lgkmcnt(2)
	v_mfma_f32_16x16x32_bf16 v[104:107], v[120:123], v[124:127], v[104:107]
	v_mfma_f32_16x16x32_bf16 v[72:75], v[120:123], v[116:119], v[72:75]
	ds_read_b64_tr_b16 v[120:121], v132 offset:28736
	ds_read_b64_tr_b16 v[122:123], v132 offset:31296
	s_waitcnt lgkmcnt(0)
; template <int NT, int NKK, int NDT, int MODE, bool MASK> ...
;     ...
;       __builtin_amdgcn_s_setprio(1);
; #pragma unroll
;       for (int t = 0; t < 2; ++t)
; #pragma unroll
;         for (int kk = 0; kk < NKK; ++kk) {
;           const bf16x8 kf = *(LAS const bf16x8*)(Kl + oz + (32 * st + 16 * t + r) * KSTR + (32 * kk + 8 * lg) * 2);
; #pragma unroll
;           for (int jj = 0; jj < JB; ++jj) s[jj][t] = mfma16(kf, qf[jh * JB + jj][kk], kk == 0 ? (f32x4){0.f, 0.f, 0.f, 0.f} : s[jj][t]);
;         }
;       __builtin_amdgcn_s_setprio(0);
;       bf16x8 pf[JB];
;       if (NT > JB) __builtin_amdgcn_sched_barrier(0);
; #pragma unroll
;       for (int jj = 0; jj < JB; ++jj) {
;         const int j = jh * JB + jj;
;         float mx = -INFINITY;
; #pragma unroll
;         for (int t = 0; t < 2; ++t)
; #pragma unroll
;           for (int i = 0; i < 4; ++i) {
;             if (MASK) { const int kp = kpos0 + 32 * st + 16 * t + 4 * lg + i; if (!mask_ok<MODE>(tq[j], kp, W)) s[jj][t][i] = -INFINITY; }
;             mx = fmaxf(mx, s[jj][t][i]);
;           }
;         mx = max_x16_x32(mx);
;         if (NT > 2 || __any(mx > m[j] + 8.0f / c)) {
;           const float mnew = fmaxf(m[j], mx);
;           const float ms2 = (mnew == -INFINITY) ? 0.f : mnew;
;           const float alpha = ex2((m[j] - ms2) * c);
;           m[j] = mnew; l[j] *= alpha;
; #pragma unroll
;           for (int dt = 0; dt < NDT; ++dt) o[j][dt] *= alpha;
;         }
;         const float mc = ((m[j] == -INFINITY) ? 0.f : m[j]) * c;
;         float p0[4], p1[4], ps = 0.f;
; #pragma unroll
;         for (int i = 0; i < 4; ++i) { p0[i] = ex2(s[jj][0][i] * c - mc); p1[i] = ex2(s[jj][1][i] * c - mc); ps += p0[i] + p1[i]; }
;         l[j] += ps;
;         pf[jj] = pack8(p0, p1);
;       }
;       if (NT > JB) __builtin_amdgcn_sched_barrier(0);
;       __builtin_amdgcn_s_setprio(1);
; #pragma unroll
;       for (int dt = 0; dt < NDT; ++dt) {
;         const s16x4 v0 = ds_tr(Vl + oz + (32 * st + 4 * lg + vq) * VSTR + (16 * dt + 4 * vp) * 2);
;         const s16x4 v1 = ds_tr(Vl + oz + (32 * st + 16 + 4 * lg + vq) * VSTR + (16 * dt + 4 * vp) * 2);
;         const bf16x8 vf = (bf16x8){v0[0], v0[1], v0[2], v0[3], v1[0], v1[1], v1[2], v1[3]};
; #pragma unroll
;         for (int jj = 0; jj < JB; ++jj) o[jh * JB + jj][dt] = mfma16(vf, pf[jj], o[jh * JB + jj][dt]);
;       }
;       __builtin_amdgcn_s_setprio(0);
	v_mfma_f32_16x16x32_bf16 v[108:111], v[120:123], v[124:127], v[108:111]
	v_mfma_f32_16x16x32_bf16 v[76:79], v[120:123], v[116:119], v[76:79]
	ds_read_b64_tr_b16 v[120:121], v132 offset:28768
	ds_read_b64_tr_b16 v[122:123], v132 offset:31328
	v_mfma_f32_16x16x32_bf16 v[100:103], v[128:131], v[124:127], v[100:103]
	v_mfma_f32_16x16x32_bf16 v[68:71], v[128:131], v[116:119], v[68:71]
	s_waitcnt lgkmcnt(0)
	v_mfma_f32_16x16x32_bf16 v[112:115], v[120:123], v[124:127], v[112:115]
	v_mfma_f32_16x16x32_bf16 v[80:83], v[120:123], v[116:119], v[80:83]
	s_setprio 0
	v_mov_b32_e32 v150, 0
	s_setprio 1
	v_add3_u32 v128, v207, v150, v151
	ds_read_b128 v[116:119], v128 offset:19456
	ds_read_b128 v[120:123], v128 offset:19520
	s_waitcnt lgkmcnt(1)
	v_mfma_f32_16x16x32_bf16 v[124:127], v[116:119], v[28:31], 0
	v_mfma_f32_16x16x32_bf16 v[116:119], v[116:119], v[36:39], 0
	s_waitcnt lgkmcnt(0)
	v_mfma_f32_16x16x32_bf16 v[124:127], v[120:123], v[32:35], v[124:127]
	v_mfma_f32_16x16x32_bf16 v[116:119], v[120:123], v[40:43], v[116:119]
	ds_read_b128 v[120:123], v128 offset:21760
	ds_read_b128 v[128:131], v128 offset:21824
	s_waitcnt lgkmcnt(1)
	v_mfma_f32_16x16x32_bf16 v[132:135], v[120:123], v[28:31], 0
	v_mfma_f32_16x16x32_bf16 v[120:123], v[120:123], v[36:39], 0
	s_waitcnt lgkmcnt(0)
	v_mfma_f32_16x16x32_bf16 v[132:135], v[128:131], v[32:35], v[132:135]
	v_mfma_f32_16x16x32_bf16 v[120:123], v[128:131], v[40:43], v[120:123]
	s_setprio 0
	v_max3_f32 v128, v124, s81, v125
	v_max3_f32 v128, v128, v126, v127
	s_nop 3
	v_max3_f32 v128, v128, v132, v133
	v_max3_f32 v128, v128, v134, v135
	v_mov_b32_e32 v129, v128
	s_nop 1
	v_permlane16_swap_b32_e32 v128, v129
	v_max_f32_e32 v128, v128, v129
	v_mov_b32_e32 v129, v128
	s_nop 1
	v_permlane32_swap_b32_e32 v128, v129
	v_max3_f32 v192, v148, v128, v129
	v_cmp_eq_f32_e32 vcc, s81, v192
	s_nop 1
	v_cndmask_b32_e64 v128, v192, 0, vcc
	v_sub_f32_e32 v128, v148, v128
	v_mul_f32_e32 v128, 0x3e38aa3b, v128
	v_exp_f32_e32 v128, v128
	s_nop 0
	v_pk_mul_f32 v[90:91], v[90:91], v[128:129] op_sel_hi:[1,0]
	v_pk_mul_f32 v[88:89], v[88:89], v[128:129] op_sel_hi:[1,0]
	v_pk_mul_f32 v[86:87], v[86:87], v[128:129] op_sel_hi:[1,0]
	v_pk_mul_f32 v[84:85], v[84:85], v[128:129] op_sel_hi:[1,0]
	v_pk_mul_f32 v[94:95], v[94:95], v[128:129] op_sel_hi:[1,0]
	v_pk_mul_f32 v[92:93], v[92:93], v[128:129] op_sel_hi:[1,0]
	v_pk_mul_f32 v[98:99], v[98:99], v[128:129] op_sel_hi:[1,0]
	v_pk_mul_f32 v[96:97], v[96:97], v[128:129] op_sel_hi:[1,0]
	v_mul_f32_e32 v129, 0x3e38aa3b, v192
	v_cndmask_b32_e64 v129, v129, 0, vcc
	v_fma_f32 v124, v124, s42, -v129
	v_exp_f32_e32 v131, v124
	v_fma_f32 v124, v132, s42, -v129
	v_exp_f32_e32 v137, v124
	v_fma_f32 v124, v125, s42, -v129
	v_max3_f32 v125, v116, s81, v117
	v_max3_f32 v125, v125, v118, v119
	v_max3_f32 v125, v125, v120, v121
	v_exp_f32_e32 v139, v124
	v_fma_f32 v124, v133, s42, -v129
	v_max3_f32 v125, v125, v122, v123
	v_exp_f32_e32 v133, v124
	v_fma_f32 v124, v126, s42, -v129
	v_mov_b32_e32 v126, v125
	s_nop 1
	v_permlane16_swap_b32_e32 v125, v126
	v_max_f32_e32 v125, v125, v126
	v_mov_b32_e32 v126, v125
	v_exp_f32_e32 v141, v124
	v_fma_f32 v124, v134, s42, -v129
	v_permlane32_swap_b32_e32 v125, v126
	v_exp_f32_e32 v143, v124
	v_fma_f32 v124, v127, s42, -v129
	v_max3_f32 v193, v149, v125, v126
	v_exp_f32_e32 v145, v124
	v_fma_f32 v124, v135, s42, -v129
	v_cmp_eq_f32_e32 vcc, s81, v193
	v_mul_f32_e32 v129, 0x3e38aa3b, v193
	v_exp_f32_e32 v135, v124
	v_cndmask_b32_e64 v129, v129, 0, vcc
	v_fma_f32 v116, v116, s42, -v129
	v_exp_f32_e32 v130, v116
	v_fma_f32 v116, v120, s42, -v129
	v_exp_f32_e32 v136, v116
	v_fma_f32 v116, v117, s42, -v129
	v_exp_f32_e32 v138, v116
	v_fma_f32 v116, v121, s42, -v129
	v_exp_f32_e32 v132, v116
	v_fma_f32 v116, v118, s42, -v129
	v_exp_f32_e32 v140, v116
	v_fma_f32 v116, v122, s42, -v129
	v_cndmask_b32_e64 v125, v193, 0, vcc
	v_exp_f32_e32 v142, v116
	v_fma_f32 v116, v119, s42, -v129
	v_sub_f32_e32 v125, v149, v125
	v_exp_f32_e32 v144, v116
	v_fma_f32 v116, v123, s42, -v129
	v_mul_f32_e32 v125, 0x3e38aa3b, v125
	v_exp_f32_e32 v134, v116
	v_exp_f32_e32 v146, v125
	v_pk_add_f32 v[116:117], v[130:131], v[136:137]
	v_pk_add_f32 v[118:119], v[138:139], v[132:133]
	v_pk_mul_f32 v[58:59], v[58:59], v[146:147] op_sel_hi:[1,0]
	v_pk_add_f32 v[116:117], v[118:119], v[116:117]
	v_pk_add_f32 v[118:119], v[140:141], v[142:143]
	v_pk_mul_f32 v[56:57], v[56:57], v[146:147] op_sel_hi:[1,0]
	v_pk_add_f32 v[116:117], v[118:119], v[116:117]
	v_pk_add_f32 v[118:119], v[144:145], v[134:135]
	v_pk_mul_f32 v[54:55], v[54:55], v[146:147] op_sel_hi:[1,0]
	v_pk_mul_f32 v[52:53], v[52:53], v[146:147] op_sel_hi:[1,0]
	v_pk_mul_f32 v[62:63], v[62:63], v[146:147] op_sel_hi:[1,0]
	v_pk_mul_f32 v[60:61], v[60:61], v[146:147] op_sel_hi:[1,0]
	v_pk_mul_f32 v[66:67], v[66:67], v[146:147] op_sel_hi:[1,0]
	v_pk_mul_f32 v[64:65], v[64:65], v[146:147] op_sel_hi:[1,0]
	v_mov_b32_e32 v147, v128
	v_pk_add_f32 v[116:117], v[118:119], v[116:117]
	v_cvt_pk_bf16_f32 v124, v131, v139
	v_pk_fma_f32 v[184:185], v[184:185], v[146:147], v[116:117]
	v_cvt_pk_bf16_f32 v125, v141, v145
	v_cvt_pk_bf16_f32 v126, v137, v133
	v_cvt_pk_bf16_f32 v127, v143, v135
	v_cvt_pk_bf16_f32 v116, v130, v138
	v_cvt_pk_bf16_f32 v117, v140, v144
	v_cvt_pk_bf16_f32 v118, v136, v132
	v_cvt_pk_bf16_f32 v119, v142, v134
	s_setprio 1
	v_add3_u32 v1, v1, v150, v206
	ds_read_b64_tr_b16 v[122:123], v1 offset:31232
	ds_read_b64_tr_b16 v[120:121], v1 offset:28672
	ds_read_b64_tr_b16 v[128:129], v1 offset:28704
	ds_read_b64_tr_b16 v[130:131], v1 offset:31264
	s_waitcnt lgkmcnt(2)
	v_mfma_f32_16x16x32_bf16 v[88:91], v[120:123], v[124:127], v[88:91]
	v_mfma_f32_16x16x32_bf16 v[56:59], v[120:123], v[116:119], v[56:59]
	ds_read_b64_tr_b16 v[120:121], v1 offset:28736
	ds_read_b64_tr_b16 v[122:123], v1 offset:31296
	s_waitcnt lgkmcnt(0)
	v_mfma_f32_16x16x32_bf16 v[92:95], v[120:123], v[124:127], v[92:95]
	v_mfma_f32_16x16x32_bf16 v[60:63], v[120:123], v[116:119], v[60:63]
	ds_read_b64_tr_b16 v[120:121], v1 offset:28768
	ds_read_b64_tr_b16 v[122:123], v1 offset:31328
	v_mfma_f32_16x16x32_bf16 v[84:87], v[128:131], v[124:127], v[84:87]
	v_mfma_f32_16x16x32_bf16 v[52:55], v[128:131], v[116:119], v[52:55]
	s_waitcnt lgkmcnt(0)
	v_mfma_f32_16x16x32_bf16 v[96:99], v[120:123], v[124:127], v[96:99]
	v_mfma_f32_16x16x32_bf16 v[64:67], v[120:123], v[116:119], v[64:67]
	s_setprio 0
	s_mov_b32 s8, 32
	s_andn2_b64 vcc, exec, s[12:13]
	s_mov_b64 s[12:13], 0
	s_cbranch_vccz .LBB0_1285
; #define LAS __attribute__((address_space(3)))
; #define LBAR() asm volatile("s_waitcnt lgkmcnt(0)\n\ts_barrier" ::: "memory")
;   __device__ __forceinline__ bf16_t* W() const { return (bf16_t*)(ws + WS_W); }
; template <int NT, int DQK, int DV, int MODE, int PD, class Src> ...
;     ...
;   for (int kcb = kc0; kcb < kc1; kcb += PD) {
; #pragma unroll
;     for (int u = 0; u < PD; ++u) {
;       const int kc = kcb + u;
;       if (kc < kc1) {
;         LAS unsigned char* buf = lds + ((kc - kc0) & 1) * BUF;
; #pragma unroll
;         for (int rr = 0; rr < NKR; ++rr) { const int idx = tid + 512 * rr; if (idx < NKI) { const int row = idx / KCH, ch = idx % KCH; *(LAS u32x4*)(buf + row * KSTR + ch * 16) = kreg[u][rr]; } }
; #pragma unroll
;         for (int rr = 0; rr < NVR; ++rr) { const int idx = tid + 512 * rr; if (idx < NVI) { const int row = idx / VCH, ch = idx % VCH; *(LAS u32x4*)(buf + KB + row * VSTR + ch * 16) = vreg[u][rr]; } }
;         if (kc + PD < kc1) ABL_LOAD(u, kc + PD);
;         LBAR();
;         const int lo = kbase + 64 * kc, hi = lo + 63;
;         bool rel = true, full = true;
;         if (MODE == MODE_CAUSAL) { rel = lo <= tq_max; full = hi <= tq_min; }
;         if (MODE == MODE_WINDOW) { rel = (lo <= tq_max) && (hi > tq_min - W); full = (hi <= tq_min) && (lo > tq_max - W); }
;         if (MODE == MODE_CMP) { rel = 16 * lo + 31 <= tq_max; full = 16 * hi + 31 <= tq_min; }
;         if (rel) {
;           if (NT <= 2) {
;             if (full) attn_chunk_wide<NT, DQK / 32, DV / 16, MODE, false>(o, m, l, qf, buf, KSTR, buf + KB, VSTR, lo, tq, c, W, lane);
;             else attn_chunk_wide<NT, DQK / 32, DV / 16, MODE, true>(o, m, l, qf, buf, KSTR, buf + KB, VSTR, lo, tq, c, W, lane);
;           } else {
;             if (full) attn_chunk<NT, DQK / 32, DV / 16, MODE, false>(o, m, l, qf, buf, KSTR, buf + KB, VSTR, lo, tq, c, W, lane);
;             else attn_chunk<NT, DQK / 32, DV / 16, MODE, true>(o, m, l, qf, buf, KSTR, buf + KB, VSTR, lo, tq, c, W, lane);
;           }
;         }
;       }
;     }
;   }
	v_mov_b64_e32 v[154:155], v[106:107]
	v_mov_b64_e32 v[150:151], v[102:103]
	v_mov_b64_e32 v[166:167], v[110:111]
	v_mov_b64_e32 v[174:175], v[114:115]
	v_mov_b64_e32 v[122:123], v[74:75]
	v_mov_b64_e32 v[118:119], v[70:71]
	v_mov_b64_e32 v[134:135], v[78:79]
	v_mov_b64_e32 v[142:143], v[82:83]
	v_mov_b64_e32 v[162:163], v[90:91]
	v_mov_b64_e32 v[158:159], v[86:87]
	v_mov_b64_e32 v[170:171], v[94:95]
	v_mov_b64_e32 v[178:179], v[98:99]
	v_mov_b64_e32 v[130:131], v[58:59]
	v_mov_b64_e32 v[126:127], v[54:55]
	v_mov_b64_e32 v[138:139], v[62:63]
	v_mov_b64_e32 v[146:147], v[66:67]
	v_mov_b32_e32 v212, v191
	v_mov_b32_e32 v1, v190
	v_mov_b32_e32 v215, v193
	v_mov_b32_e32 v214, v192
	v_mov_b64_e32 v[194:195], v[2:3]
	v_mov_b64_e32 v[202:203], v[184:185]
	v_mov_b64_e32 v[152:153], v[104:105]
	v_mov_b64_e32 v[148:149], v[100:101]
	v_mov_b64_e32 v[164:165], v[108:109]
	v_mov_b64_e32 v[172:173], v[112:113]
	v_mov_b64_e32 v[120:121], v[72:73]
	v_mov_b64_e32 v[116:117], v[68:69]
	v_mov_b64_e32 v[132:133], v[76:77]
	v_mov_b64_e32 v[140:141], v[80:81]
	v_mov_b64_e32 v[160:161], v[88:89]
	v_mov_b64_e32 v[156:157], v[84:85]
	v_mov_b64_e32 v[168:169], v[92:93]
	v_mov_b64_e32 v[176:177], v[96:97]
	v_mov_b64_e32 v[128:129], v[56:57]
	v_mov_b64_e32 v[124:125], v[52:53]
	v_mov_b64_e32 v[136:137], v[60:61]
	v_mov_b64_e32 v[144:145], v[64:65]
	s_branch .LBB0_1250

; __device__ __forceinline__ float ex2(float x) { return __builtin_amdgcn_exp2f(x); }
; __device__ __forceinline__ long as_long(unsigned lo, unsigned hi) { return (long)(((unsigned long long)hi << 32) | (unsigned long long)lo); }
; __device__ __forceinline__ f32x4 mfma16_fp8(long a, long b, f32x4 c) { return __builtin_amdgcn_mfma_f32_16x16x32_fp8_fp8(a, b, c, 0, 0, 0); }
; __device__ __forceinline__ void sel_load(SelFrag& F, const bf16_t* kst, const bf16_t* vst, int blk, int cq, int lg) {
;   const unsigned char* kp = (const unsigned char*)kst + (size_t)blk * 4096 + (cq * 4 + lg) * 16;
;   const unsigned char* vp = (const unsigned char*)vst + (size_t)blk * 4096 + (cq * 4 + lg) * 16;
; #pragma unroll
;   for (int t4 = 0; t4 < 4; ++t4) F.kf[t4] = *(const u32x4*)(kp + t4 * 1024);
; #pragma unroll
;   for (int dt = 0; dt < 4; ++dt) F.vf[dt] = *(const u32x4*)(vp + dt * 1024);
; __device__ __forceinline__ void sel_compute(const SelFrag& F, const long (&qs)[2], f32x4 (&os)[4], float& m, float& l, int blk, int cur, int t, int lg, float c) {
;     ...
;   const float mcc = ((m == -INFINITY) ? 0.f : m) * c;
;   float p[4][4], ps = 0.f;
; #pragma unroll
;   for (int t4 = 0; t4 < 4; ++t4)
; #pragma unroll
;     for (int i = 0; i < 4; ++i) { p[t4][i] = ex2(s[t4][i] * c - mcc); ps += p[t4][i]; }
;   l += ps;
;   const u32x2 pa = pack8_fp8(p[0], p[1]), pb = pack8_fp8(p[2], p[3]);
;   const long pf0 = as_long(pa.x, pa.y), pf1 = as_long(pb.x, pb.y);
; #pragma unroll
;   for (int dt = 0; dt < 4; ++dt) { os[dt] = mfma16_fp8(as_long(F.vf[dt].x, F.vf[dt].y), pf0, os[dt]); os[dt] = mfma16_fp8(as_long(F.vf[dt].z, F.vf[dt].w), pf1, os[dt]); }
; }
; __device__ __forceinline__ int sel_slot(const u32x4& sl, int slot) {
;   const unsigned wsel = slot < 4 ? sl.x : slot < 8 ? sl.y : slot < 12 ? sl.z : sl.w;
;   return __builtin_amdgcn_readfirstlane((int)((wsel >> (8 * (slot & 3))) & 127u));
.LBB0_1350:
	v_mul_f32_e32 v110, 0x3e38aa3b, v109
	v_cmp_neq_f32_e32 vcc, s81, v109
	s_add_i32 s46, s70, 2
	s_nop 0
	v_cndmask_b32_e32 v110, 0, v110, vcc
	v_fma_f32 v115, v115, s42, -v110
	v_exp_f32_e32 v115, v115
	v_fma_f32 v118, v118, s42, -v110
	v_exp_f32_e32 v118, v118
	v_fma_f32 v121, v121, s42, -v110
	v_exp_f32_e32 v121, v121
	v_fma_f32 v123, v123, s42, -v110
	v_exp_f32_e32 v123, v123
	v_fma_f32 v125, v125, s42, -v110
	v_exp_f32_e32 v125, v125
	v_fma_f32 v126, v126, s42, -v110
	v_add_f32_e32 v127, v118, v115
	v_exp_f32_e32 v126, v126
	v_fma_f32 v124, v124, s42, -v110
	v_add_f32_e32 v127, v121, v127
	v_exp_f32_e32 v124, v124
	v_fma_f32 v122, v122, s42, -v110
	v_add_f32_e32 v127, v123, v127
	v_exp_f32_e32 v122, v122
	v_fma_f32 v120, v120, s42, -v110
	v_add_f32_e32 v127, v125, v127
	v_exp_f32_e32 v120, v120
	v_fma_f32 v119, v119, s42, -v110
	v_add_f32_e32 v127, v126, v127
	v_exp_f32_e32 v119, v119
	v_fma_f32 v117, v117, s42, -v110
	v_add_f32_e32 v127, v124, v127
	v_exp_f32_e32 v117, v117
	v_fma_f32 v116, v116, s42, -v110
	v_add_f32_e32 v127, v122, v127
	v_exp_f32_e32 v116, v116
	v_fma_f32 v114, v114, s42, -v110
	v_add_f32_e32 v127, v120, v127
	v_exp_f32_e32 v128, v114
	v_add_f32_e32 v127, v119, v127
	v_add_f32_e32 v127, v117, v127
	v_add_f32_e32 v127, v116, v127
	v_fma_f32 v113, v113, s42, -v110
	v_add_f32_e32 v114, v128, v127
	v_exp_f32_e32 v127, v113
	v_fma_f32 v111, v111, s42, -v110
	v_exp_f32_e32 v111, v111
	v_fma_f32 v112, v112, s42, -v110
	v_exp_f32_e32 v129, v112
	v_add_f32_e32 v113, v127, v114
	v_add_f32_e32 v113, v111, v113
	v_mov_b32_e32 v114, 0
	v_add_f32_e32 v112, v129, v113
	v_add_f32_e32 v99, v99, v112
	v_mov_b32_e32 v112, 0
	v_mov_b32_e32 v113, 0
	v_cvt_pk_fp8_f32 v112, v115, v118
	v_cvt_pk_fp8_f32 v113, v125, v126
	v_mov_b32_e32 v115, 0
	v_cvt_pk_fp8_f32 v114, v120, v119
	v_cvt_pk_fp8_f32 v112, v121, v123 op_sel:[0,0,1]
	v_cvt_pk_fp8_f32 v113, v124, v122 op_sel:[0,0,1]
	v_cvt_pk_fp8_f32 v115, v128, v127
	v_cvt_pk_fp8_f32 v114, v117, v116 op_sel:[0,0,1]
	v_mfma_f32_16x16x32_fp8_fp8 v[82:85], v[2:3], v[112:113], v[82:85]
	v_cvt_pk_fp8_f32 v115, v111, v129 op_sel:[0,0,1]
	s_andn2_b64 vcc, exec, s[38:39]
	v_mfma_f32_16x16x32_fp8_fp8 v[78:81], v[6:7], v[112:113], v[78:81]
	v_mfma_f32_16x16x32_fp8_fp8 v[74:77], v[10:11], v[112:113], v[74:77]
	v_mfma_f32_16x16x32_fp8_fp8 v[86:89], v[14:15], v[112:113], v[86:89]
	v_mfma_f32_16x16x32_fp8_fp8 v[82:85], v[4:5], v[114:115], v[82:85]
	v_mfma_f32_16x16x32_fp8_fp8 v[78:81], v[8:9], v[114:115], v[78:81]
	v_mfma_f32_16x16x32_fp8_fp8 v[74:77], v[12:13], v[114:115], v[74:77]
	v_mfma_f32_16x16x32_fp8_fp8 v[86:89], v[16:17], v[114:115], v[86:89]
	s_cbranch_vccnz .LBB0_1356
	s_cmp_gt_i32 s46, s64
	s_cbranch_scc1 .Lsel_b0
	s_cmp_lt_u32 s70, 10
	s_cselect_b32 s8, 2, 3
	s_cmp_gt_u32 s70, 5
	s_cselect_b32 s8, s8, 1
	s_cmp_lg_u32 s68, 0
	s_cselect_b32 s8, s8, 0
	s_cmp_eq_u32 s8, 1
	s_cselect_b64 vcc, -1, 0
	s_cmp_eq_u32 s8, 2
	v_cndmask_b32_e32 v2, v70, v71, vcc
	s_cselect_b64 vcc, -1, 0
	s_cmp_eq_u32 s8, 3
	v_cndmask_b32_e32 v2, v2, v72, vcc
	s_cselect_b64 vcc, -1, 0
	s_add_i32 s8, s68, 16
	v_cndmask_b32_e32 v2, v2, v73, vcc
	s_and_b32 s8, s8, 16
	v_lshrrev_b32_e32 v2, s8, v2
	s_nop 0
	v_readfirstlane_b32 s8, v2
	s_and_b32 s65, s8, 0x7f
	s_lshl_b32 s40, s65, 12
	v_lshl_add_u64 v[2:3], v[104:105], 0, s[40:41]
	v_lshl_add_u64 v[14:15], v[106:107], 0, s[40:41]
	global_load_dwordx4 v[18:21], v[2:3], off
	global_load_dwordx4 v[22:25], v[2:3], off offset:1024
	global_load_dwordx4 v[26:29], v[2:3], off offset:2048
	global_load_dwordx4 v[30:33], v[2:3], off offset:3072
	s_nop 0
	global_load_dwordx4 v[2:5], v[14:15], off
	global_load_dwordx4 v[6:9], v[14:15], off offset:1024
	global_load_dwordx4 v[10:13], v[14:15], off offset:2048
	s_nop 0
	global_load_dwordx4 v[14:17], v[14:15], off offset:3072

; __device__ __forceinline__ float ex2(float x) { return __builtin_amdgcn_exp2f(x); }
; __device__ __forceinline__ long as_long(unsigned lo, unsigned hi) { return (long)(((unsigned long long)hi << 32) | (unsigned long long)lo); }
; __device__ __forceinline__ f32x4 mfma16_fp8(long a, long b, f32x4 c) { return __builtin_amdgcn_mfma_f32_16x16x32_fp8_fp8(a, b, c, 0, 0, 0); }
; __device__ __forceinline__ void sel_compute(const SelFrag& F, const long (&qs)[2], f32x4 (&os)[4], float& m, float& l, int blk, int cur, int t, int lg, float c) {
;     ...
;   const float mcc = ((m == -INFINITY) ? 0.f : m) * c;
;   float p[4][4], ps = 0.f;
; #pragma unroll
;   for (int t4 = 0; t4 < 4; ++t4)
; #pragma unroll
;     for (int i = 0; i < 4; ++i) { p[t4][i] = ex2(s[t4][i] * c - mcc); ps += p[t4][i]; }
;   l += ps;
;   const u32x2 pa = pack8_fp8(p[0], p[1]), pb = pack8_fp8(p[2], p[3]);
;   const long pf0 = as_long(pa.x, pa.y), pf1 = as_long(pb.x, pb.y);
; #pragma unroll
;   for (int dt = 0; dt < 4; ++dt) { os[dt] = mfma16_fp8(as_long(F.vf[dt].x, F.vf[dt].y), pf0, os[dt]); os[dt] = mfma16_fp8(as_long(F.vf[dt].z, F.vf[dt].w), pf1, os[dt]); }
.LBB0_1355:
	v_fma_f32 v115, v115, s42, -v110
	v_exp_f32_e32 v115, v115
	v_fma_f32 v118, v118, s42, -v110
	v_exp_f32_e32 v118, v118
	v_fma_f32 v121, v121, s42, -v110
	v_exp_f32_e32 v121, v121
	v_fma_f32 v123, v123, s42, -v110
	v_exp_f32_e32 v123, v123
	v_fma_f32 v125, v125, s42, -v110
	v_exp_f32_e32 v125, v125
	v_fma_f32 v126, v126, s42, -v110
	v_add_f32_e32 v127, v118, v115
	v_exp_f32_e32 v126, v126
	v_fma_f32 v124, v124, s42, -v110
	v_add_f32_e32 v127, v121, v127
	v_exp_f32_e32 v124, v124
	v_fma_f32 v122, v122, s42, -v110
	v_add_f32_e32 v127, v123, v127
	v_exp_f32_e32 v122, v122
	v_fma_f32 v120, v120, s42, -v110
	v_add_f32_e32 v127, v125, v127
	v_exp_f32_e32 v120, v120
	v_fma_f32 v119, v119, s42, -v110
	v_add_f32_e32 v127, v126, v127
	v_exp_f32_e32 v119, v119
	v_fma_f32 v117, v117, s42, -v110
	v_add_f32_e32 v127, v124, v127
	v_exp_f32_e32 v117, v117
	v_fma_f32 v116, v116, s42, -v110
	v_add_f32_e32 v127, v122, v127
	v_exp_f32_e32 v116, v116
	v_fma_f32 v114, v114, s42, -v110
	v_add_f32_e32 v127, v120, v127
	v_exp_f32_e32 v114, v114
	v_fma_f32 v113, v113, s42, -v110
	v_add_f32_e32 v127, v119, v127
	v_exp_f32_e32 v128, v113
	v_add_f32_e32 v127, v117, v127
	v_add_f32_e32 v127, v116, v127
	v_add_f32_e32 v127, v114, v127
	v_fma_f32 v111, v111, s42, -v110
	v_add_f32_e32 v113, v128, v127
	v_exp_f32_e32 v127, v111
	v_fma_f32 v110, v112, s42, -v110
	v_exp_f32_e32 v129, v110
	v_mov_b32_e32 v112, 0
	v_add_f32_e32 v111, v127, v113
	v_mov_b32_e32 v113, 0
	v_add_f32_e32 v110, v129, v111
	v_add_f32_e32 v99, v99, v110
	v_mov_b32_e32 v110, 0
	v_mov_b32_e32 v111, 0
	v_cvt_pk_fp8_f32 v110, v115, v118
	v_cvt_pk_fp8_f32 v111, v125, v126
	v_cvt_pk_fp8_f32 v112, v120, v119
	v_cvt_pk_fp8_f32 v113, v114, v128
	v_cvt_pk_fp8_f32 v110, v121, v123 op_sel:[0,0,1]
	v_cvt_pk_fp8_f32 v111, v124, v122 op_sel:[0,0,1]
	v_cvt_pk_fp8_f32 v112, v117, v116 op_sel:[0,0,1]
	v_cvt_pk_fp8_f32 v113, v127, v129 op_sel:[0,0,1]
	s_waitcnt vmcnt(11)
	v_mfma_f32_16x16x32_fp8_fp8 v[82:85], v[58:59], v[110:111], v[82:85]
	s_waitcnt vmcnt(10)
	v_mfma_f32_16x16x32_fp8_fp8 v[78:81], v[62:63], v[110:111], v[78:81]
	s_waitcnt vmcnt(9)
	v_mfma_f32_16x16x32_fp8_fp8 v[74:77], v[66:67], v[110:111], v[74:77]
	s_waitcnt vmcnt(8)
	v_mfma_f32_16x16x32_fp8_fp8 v[86:89], v[50:51], v[110:111], v[86:89]
	v_mfma_f32_16x16x32_fp8_fp8 v[82:85], v[60:61], v[112:113], v[82:85]
	v_mfma_f32_16x16x32_fp8_fp8 v[78:81], v[64:65], v[112:113], v[78:81]
	v_mfma_f32_16x16x32_fp8_fp8 v[74:77], v[68:69], v[112:113], v[74:77]
	v_mfma_f32_16x16x32_fp8_fp8 v[86:89], v[52:53], v[112:113], v[86:89]

; __device__ __forceinline__ float ex2(float x) { return __builtin_amdgcn_exp2f(x); }
; __device__ __forceinline__ f32x4 mfma16(bf16x8 a, bf16x8 b, f32x4 c) { return __builtin_amdgcn_mfma_f32_16x16x32_bf16(a, b, c, 0, 0, 0); }
; __device__ __forceinline__ s16x4 ds_tr(LAS const unsigned char* p) { return __builtin_bit_cast(s16x4, __builtin_amdgcn_ds_read_tr16_b64_v4i16((LAS v4i16_t*)p)); }
; template <int NT, int NKK, int NDT, int MODE, bool MASK> ...
;     ...
;     const float mc = ((m[j] == -INFINITY) ? 0.f : m[j]) * c;
;     float p[4][4], ps = 0.f;
; #pragma unroll
;     for (int t = 0; t < 4; ++t)
; #pragma unroll
;       for (int i = 0; i < 4; ++i) { p[t][i] = ex2(s[j][t][i] * c - mc); ps += p[t][i]; }
;     l[j] += ps;
;     pf[j][0] = pack8(p[0], p[1]); pf[j][1] = pack8(p[2], p[3]);
;   }
;   __builtin_amdgcn_s_setprio(1);
; #pragma unroll
;   for (int st = 0; st < 2; ++st)
; #pragma unroll
;     for (int dt = 0; dt < NDT; ++dt) {
;       const s16x4 v0 = ds_tr(Vl + (32 * st + 4 * lg + vq) * VSTR + (16 * dt + 4 * vp) * 2);
;       const s16x4 v1 = ds_tr(Vl + (32 * st + 16 + 4 * lg + vq) * VSTR + (16 * dt + 4 * vp) * 2);
;       const bf16x8 vf = (bf16x8){v0[0], v0[1], v0[2], v0[3], v1[0], v1[1], v1[2], v1[3]};
; #pragma unroll
;       for (int j = 0; j < NT; ++j) o[j][dt] = mfma16(vf, pf[j][st], o[j][dt]);
;     }
.LBB0_1772:
	v_fma_f32 v148, v148, s92, -v202
	v_exp_f32_e32 v196, v148
	v_fma_f32 v148, v149, s92, -v202
	v_exp_f32_e32 v197, v148
	v_fma_f32 v148, v150, s92, -v202
	v_exp_f32_e32 v198, v148
	v_fma_f32 v148, v151, s92, -v202
	v_exp_f32_e32 v199, v148
	v_fma_f32 v149, v152, s92, -v202
	v_exp_f32_e32 v203, v149
	v_fma_f32 v149, v153, s92, -v202
	v_add_f32_e32 v148, v197, v196
	v_exp_f32_e32 v204, v149
	v_fma_f32 v149, v154, s92, -v202
	v_add_f32_e32 v148, v198, v148
	v_exp_f32_e32 v205, v149
	v_fma_f32 v149, v155, s92, -v202
	v_add_f32_e32 v148, v199, v148
	v_exp_f32_e32 v155, v149
	v_fma_f32 v149, v156, s92, -v202
	v_add_f32_e32 v148, v203, v148
	v_exp_f32_e32 v149, v149
	v_fma_f32 v150, v157, s92, -v202
	v_add_f32_e32 v148, v204, v148
	v_exp_f32_e32 v150, v150
	v_fma_f32 v151, v158, s92, -v202
	v_add_f32_e32 v148, v205, v148
	v_exp_f32_e32 v151, v151
	v_fma_f32 v152, v159, s92, -v202
	v_add_f32_e32 v148, v155, v148
	v_exp_f32_e32 v152, v152
	v_fma_f32 v153, v160, s92, -v202
	v_add_f32_e32 v148, v149, v148
	v_exp_f32_e32 v153, v153
	v_fma_f32 v154, v161, s92, -v202
	v_add_f32_e32 v148, v150, v148
	v_exp_f32_e32 v154, v154
	v_fma_f32 v156, v162, s92, -v202
	v_add_f32_e32 v148, v151, v148
	v_exp_f32_e32 v156, v156
	v_fma_f32 v157, v163, s92, -v202
	v_add_f32_e32 v148, v152, v148
	v_exp_f32_e32 v157, v157
	v_fma_f32 v132, v132, s92, -v3
	v_add_f32_e32 v148, v153, v148
	v_exp_f32_e32 v132, v132
	v_fma_f32 v133, v133, s92, -v3
	v_add_f32_e32 v148, v154, v148
	v_exp_f32_e32 v133, v133
	v_fma_f32 v134, v134, s92, -v3
	v_add_f32_e32 v148, v156, v148
	v_exp_f32_e32 v134, v134
	v_fma_f32 v135, v135, s92, -v3
	v_add_f32_e32 v148, v157, v148
	v_exp_f32_e32 v135, v135
	v_fma_f32 v136, v136, s92, -v3
	v_add_f32_e32 v2, v2, v148
	v_cvt_pk_bf16_f32 v148, v149, v150
	v_cvt_pk_bf16_f32 v149, v151, v152
	v_cvt_pk_bf16_f32 v151, v156, v157
	v_exp_f32_e32 v157, v136
	v_fma_f32 v136, v137, s92, -v3
	v_add_f32_e32 v156, v133, v132
	v_exp_f32_e32 v158, v136
	v_fma_f32 v136, v138, s92, -v3
	v_add_f32_e32 v156, v134, v156
	v_exp_f32_e32 v159, v136
	v_fma_f32 v136, v139, s92, -v3
	v_add_f32_e32 v156, v135, v156
	v_exp_f32_e32 v139, v136
	v_fma_f32 v137, v140, s92, -v3
	v_add_f32_e32 v136, v157, v156
	v_exp_f32_e32 v140, v137
	v_fma_f32 v137, v141, s92, -v3
	v_add_f32_e32 v136, v158, v136
	v_exp_f32_e32 v141, v137
	v_fma_f32 v137, v142, s92, -v3
	v_add_f32_e32 v136, v159, v136
	v_exp_f32_e32 v142, v137
	v_fma_f32 v137, v143, s92, -v3
	v_add_f32_e32 v136, v139, v136
	v_exp_f32_e32 v143, v137
	v_fma_f32 v137, v144, s92, -v3
	v_add_f32_e32 v136, v140, v136
	v_exp_f32_e32 v144, v137
	v_fma_f32 v137, v145, s92, -v3
	v_add_f32_e32 v136, v141, v136
	v_exp_f32_e32 v145, v137
	v_fma_f32 v137, v146, s92, -v3
	v_add_f32_e32 v136, v142, v136
	v_exp_f32_e32 v146, v137
	v_fma_f32 v3, v147, s92, -v3
	v_add_f32_e32 v136, v143, v136
	v_exp_f32_e32 v3, v3
	v_add_f32_e32 v136, v144, v136
	v_add_f32_e32 v136, v145, v136
	v_add_f32_e32 v136, v146, v136
	v_add_f32_e32 v136, v3, v136
	v_add_f32_e32 v195, v195, v136
	v_cvt_pk_bf16_f32 v150, v153, v154
	v_cvt_pk_bf16_f32 v152, v196, v197
	v_cvt_pk_bf16_f32 v153, v198, v199
	v_cvt_pk_bf16_f32 v154, v203, v204
	v_cvt_pk_bf16_f32 v155, v205, v155
	v_cvt_pk_bf16_f32 v136, v132, v133
	v_cvt_pk_bf16_f32 v137, v134, v135
	v_cvt_pk_bf16_f32 v138, v157, v158
	v_cvt_pk_bf16_f32 v139, v159, v139
	v_cvt_pk_bf16_f32 v132, v140, v141
	v_cvt_pk_bf16_f32 v133, v142, v143
	v_cvt_pk_bf16_f32 v134, v144, v145
	v_cvt_pk_bf16_f32 v135, v146, v3
	s_setprio 1
	ds_read_b64_tr_b16 v[142:143], v189 offset:57856
	ds_read_b64_tr_b16 v[140:141], v189 offset:53248
	ds_read_b64_tr_b16 v[144:145], v189 offset:53280
	ds_read_b64_tr_b16 v[146:147], v189 offset:57888
	s_waitcnt lgkmcnt(2)
	v_mfma_f32_16x16x32_bf16 v[68:71], v[140:143], v[152:155], v[68:71]
	v_mfma_f32_16x16x32_bf16 v[72:75], v[140:143], v[136:139], v[72:75]
	s_waitcnt lgkmcnt(0)
; __device__ __forceinline__ f32x4 mfma16(bf16x8 a, bf16x8 b, f32x4 c) { return __builtin_amdgcn_mfma_f32_16x16x32_bf16(a, b, c, 0, 0, 0); }
; __device__ __forceinline__ s16x4 ds_tr(LAS const unsigned char* p) { return __builtin_bit_cast(s16x4, __builtin_amdgcn_ds_read_tr16_b64_v4i16((LAS v4i16_t*)p)); }
; template <int NT, int NKK, int NDT, int MODE, bool MASK> ...
;     ...
;   __builtin_amdgcn_s_setprio(1);
; #pragma unroll
;   for (int st = 0; st < 2; ++st)
; #pragma unroll
;     for (int dt = 0; dt < NDT; ++dt) {
;       const s16x4 v0 = ds_tr(Vl + (32 * st + 4 * lg + vq) * VSTR + (16 * dt + 4 * vp) * 2);
;       const s16x4 v1 = ds_tr(Vl + (32 * st + 16 + 4 * lg + vq) * VSTR + (16 * dt + 4 * vp) * 2);
;       const bf16x8 vf = (bf16x8){v0[0], v0[1], v0[2], v0[3], v1[0], v1[1], v1[2], v1[3]};
; #pragma unroll
;       for (int j = 0; j < NT; ++j) o[j][dt] = mfma16(vf, pf[j][st], o[j][dt]);
;     }
;   __builtin_amdgcn_s_setprio(0);
	v_mfma_f32_16x16x32_bf16 v[140:143], v[144:147], v[152:155], v[124:127]
	s_nop 2
	ds_read_b64_tr_b16 v[124:125], v189 offset:53312
	ds_read_b64_tr_b16 v[126:127], v189 offset:57920
	s_waitcnt lgkmcnt(0)
	v_mfma_f32_16x16x32_bf16 v[156:159], v[124:127], v[152:155], v[96:99]
	s_nop 2
	ds_read_b64_tr_b16 v[96:97], v189 offset:53344
	ds_read_b64_tr_b16 v[98:99], v189 offset:57952
	s_waitcnt lgkmcnt(0)
	v_mfma_f32_16x16x32_bf16 v[202:205], v[96:99], v[152:155], v[92:95]
	s_nop 2
	ds_read_b64_tr_b16 v[92:93], v189 offset:53376
	ds_read_b64_tr_b16 v[94:95], v189 offset:57984
	s_waitcnt lgkmcnt(0)
	v_mfma_f32_16x16x32_bf16 v[210:213], v[92:95], v[152:155], v[88:91]
	s_nop 2
	ds_read_b64_tr_b16 v[88:89], v189 offset:53408
	ds_read_b64_tr_b16 v[90:91], v189 offset:58016
	s_waitcnt lgkmcnt(0)
	v_mfma_f32_16x16x32_bf16 v[218:221], v[88:91], v[152:155], v[84:87]
	s_nop 2
	ds_read_b64_tr_b16 v[84:85], v189 offset:53440
	ds_read_b64_tr_b16 v[86:87], v189 offset:58048
	s_waitcnt lgkmcnt(0)
	v_mfma_f32_16x16x32_bf16 v[228:231], v[84:87], v[152:155], v[80:83]
	s_nop 2
	ds_read_b64_tr_b16 v[80:81], v189 offset:53472
	ds_read_b64_tr_b16 v[82:83], v189 offset:58080
	v_mfma_f32_16x16x32_bf16 v[144:147], v[144:147], v[136:139], v[128:131]
	v_mfma_f32_16x16x32_bf16 v[160:163], v[124:127], v[136:139], v[120:123]
	v_mfma_f32_16x16x32_bf16 v[206:209], v[96:99], v[136:139], v[116:119]
	v_mfma_f32_16x16x32_bf16 v[214:217], v[92:95], v[136:139], v[112:115]
	v_mfma_f32_16x16x32_bf16 v[222:225], v[88:91], v[136:139], v[108:111]
	v_mfma_f32_16x16x32_bf16 v[236:239], v[84:87], v[136:139], v[104:107]
	s_waitcnt lgkmcnt(0)
	v_mfma_f32_16x16x32_bf16 v[152:155], v[80:83], v[152:155], v[76:79]
	v_mfma_f32_16x16x32_bf16 v[136:139], v[80:83], v[136:139], v[100:103]
	s_nop 1
	ds_read_b64_tr_b16 v[76:77], v189 offset:62464
	ds_read_b64_tr_b16 v[78:79], v190 offset:13824
	ds_read_b64_tr_b16 v[80:81], v190 offset:13856
	s_waitcnt lgkmcnt(1)
	v_mfma_f32_16x16x32_bf16 v[124:127], v[76:79], v[148:151], v[68:71]
	v_mfma_f32_16x16x32_bf16 v[92:95], v[76:79], v[132:135], v[72:75]
	ds_read_b64_tr_b16 v[78:79], v189 offset:62496
	s_nop 0
	ds_read_b64_tr_b16 v[68:69], v189 offset:62528
	ds_read_b64_tr_b16 v[70:71], v190 offset:13888
	s_waitcnt lgkmcnt(0)
	v_mfma_f32_16x16x32_bf16 v[120:123], v[68:71], v[148:151], v[156:159]
	v_mfma_f32_16x16x32_bf16 v[88:91], v[68:71], v[132:135], v[160:163]
	ds_read_b64_tr_b16 v[68:69], v189 offset:62560
	ds_read_b64_tr_b16 v[70:71], v190 offset:13920
	s_waitcnt lgkmcnt(0)
	v_mfma_f32_16x16x32_bf16 v[116:119], v[68:71], v[148:151], v[202:205]
	v_mfma_f32_16x16x32_bf16 v[84:87], v[68:71], v[132:135], v[206:209]
	ds_read_b64_tr_b16 v[68:69], v189 offset:62592
	ds_read_b64_tr_b16 v[70:71], v190 offset:13952
	v_mfma_f32_16x16x32_bf16 v[128:131], v[78:81], v[148:151], v[140:143]
	v_mfma_f32_16x16x32_bf16 v[96:99], v[78:81], v[132:135], v[144:147]
	s_waitcnt lgkmcnt(0)
	v_mfma_f32_16x16x32_bf16 v[112:115], v[68:71], v[148:151], v[210:213]
	v_mfma_f32_16x16x32_bf16 v[80:83], v[68:71], v[132:135], v[214:217]
	ds_read_b64_tr_b16 v[68:69], v189 offset:62624
	ds_read_b64_tr_b16 v[70:71], v190 offset:13984
	s_waitcnt lgkmcnt(0)
	v_mfma_f32_16x16x32_bf16 v[108:111], v[68:71], v[148:151], v[218:221]
	v_mfma_f32_16x16x32_bf16 v[76:79], v[68:71], v[132:135], v[222:225]
	ds_read_b64_tr_b16 v[68:69], v189 offset:62656
	ds_read_b64_tr_b16 v[70:71], v190 offset:14016
	s_waitcnt lgkmcnt(0)
	v_mfma_f32_16x16x32_bf16 v[104:107], v[68:71], v[148:151], v[228:231]
	v_mfma_f32_16x16x32_bf16 v[72:75], v[68:71], v[132:135], v[236:239]
	ds_read_b64_tr_b16 v[68:69], v189 offset:62688
	ds_read_b64_tr_b16 v[70:71], v190 offset:14048
	s_waitcnt lgkmcnt(0)
	v_mfma_f32_16x16x32_bf16 v[100:103], v[68:71], v[148:151], v[152:155]
	v_mfma_f32_16x16x32_bf16 v[68:71], v[68:71], v[132:135], v[136:139]
	s_setprio 0
	s_andn2_b64 vcc, exec, s[16:17]
	s_mov_b64 s[18:19], 0
	s_cbranch_vccz .LBB0_1757

; #define LAS __attribute__((address_space(3)))
; __device__ __forceinline__ float ex2(float x) { return __builtin_amdgcn_exp2f(x); }
; #define LBAR() asm volatile("s_waitcnt lgkmcnt(0)\n\ts_barrier" ::: "memory")
; __device__ __forceinline__ f32x4 mfma16(bf16x8 a, bf16x8 b, f32x4 c) { return __builtin_amdgcn_mfma_f32_16x16x32_bf16(a, b, c, 0, 0, 0); }
;   __device__ __forceinline__ bf16_t* W() const { return (bf16_t*)(ws + WS_W); }
; template <int NT, int NKK, int NDT, int MODE, bool MASK> ...
;     ...
;   __builtin_amdgcn_s_setprio(1);
; #pragma unroll
;   for (int t = 0; t < 4; ++t)
; #pragma unroll
;     for (int kk = 0; kk < NKK; ++kk) {
;       const bf16x8 kf = *(LAS const bf16x8*)(Kl + (16 * t + r) * KSTR + (32 * kk + 8 * lg) * 2);
; #pragma unroll
;       for (int j = 0; j < NT; ++j) s[j][t] = mfma16(kf, qf[j][kk], kk == 0 ? (f32x4){0.f, 0.f, 0.f, 0.f} : s[j][t]);
;     }
;   __builtin_amdgcn_s_setprio(0);
;   bf16x8 pf[NT][2];
; #pragma unroll
;   for (int j = 0; j < NT; ++j) {
;     float mx = -INFINITY;
; #pragma unroll
;     for (int t = 0; t < 4; ++t)
; #pragma unroll
;       for (int i = 0; i < 4; ++i) {
;         if (MASK) { const int kp = kpos0 + 16 * t + 4 * lg + i; if (!mask_ok<MODE>(tq[j], kp, W)) s[j][t][i] = -INFINITY; }
;         mx = fmaxf(mx, s[j][t][i]);
;       }
;     mx = max_x16_x32(mx);
;     if (__any(mx > m[j] + 8.0f / c)) {
;       const float mnew = fmaxf(m[j], mx);
;       const float ms2 = (mnew == -INFINITY) ? 0.f : mnew;
;       const float alpha = ex2((m[j] - ms2) * c);
;       m[j] = mnew; l[j] *= alpha;
; #pragma unroll
;       for (int dt = 0; dt < NDT; ++dt) o[j][dt] *= alpha;
;     }
; template <int NT, int DQK, int DV, int MODE, int PD, class Src> ...
;     ...
;         LBAR();
.LBB0_1807:
	v_add_f32_e32 v132, v222, v221
	v_add_f32_e32 v132, v223, v132
	v_add_f32_e32 v132, v224, v132
	v_add_f32_e32 v132, v148, v132
	v_add_f32_e32 v132, v149, v132
	v_add_f32_e32 v132, v150, v132
	v_add_f32_e32 v132, v151, v132
	v_add_f32_e32 v132, v156, v132
	v_add_f32_e32 v132, v157, v132
	v_add_f32_e32 v132, v158, v132
	v_add_f32_e32 v132, v159, v132
	v_add_f32_e32 v132, v160, v132
	v_add_f32_e32 v132, v161, v132
	v_add_f32_e32 v132, v162, v132
	s_waitcnt lgkmcnt(0)
	s_barrier
	v_add_f32_e32 v132, v163, v132
	v_add_f32_e32 v2, v2, v132
	s_setprio 1
	ds_read_b128 v[132:135], v193 offset:35840
	ds_read_b128 v[140:143], v193 offset:35904
	s_waitcnt lgkmcnt(1)
	v_mfma_f32_16x16x32_bf16 v[136:139], v[132:135], v[4:7], 0
	ds_read_b128 v[144:147], v193 offset:40256
	ds_read_b128 v[156:159], v193 offset:44608
	ds_read_b128 v[160:163], v193 offset:44736
	v_mfma_f32_16x16x32_bf16 v[132:135], v[132:135], v[20:23], 0
	ds_read_b128 v[222:225], v194 offset:35904
	s_waitcnt lgkmcnt(4)
	v_mfma_f32_16x16x32_bf16 v[136:139], v[140:143], v[8:11], v[136:139]
	v_mfma_f32_16x16x32_bf16 v[132:135], v[140:143], v[24:27], v[132:135]
	ds_read_b128 v[140:143], v193 offset:35968
	s_waitcnt lgkmcnt(0)
	v_mfma_f32_16x16x32_bf16 v[136:139], v[140:143], v[12:15], v[136:139]
	v_mfma_f32_16x16x32_bf16 v[132:135], v[140:143], v[28:31], v[132:135]
	ds_read_b128 v[140:143], v193 offset:36032
	s_waitcnt lgkmcnt(0)
	v_mfma_f32_16x16x32_bf16 v[148:151], v[140:143], v[16:19], v[136:139]
	s_nop 3
	ds_read_b128 v[136:139], v193 offset:40192
	v_mfma_f32_16x16x32_bf16 v[132:135], v[140:143], v[32:35], v[132:135]
	s_waitcnt lgkmcnt(0)
	v_mfma_f32_16x16x32_bf16 v[140:143], v[136:139], v[4:7], 0
	v_mfma_f32_16x16x32_bf16 v[136:139], v[136:139], v[20:23], 0
	v_mfma_f32_16x16x32_bf16 v[140:143], v[144:147], v[8:11], v[140:143]
	v_mfma_f32_16x16x32_bf16 v[136:139], v[144:147], v[24:27], v[136:139]
	ds_read_b128 v[144:147], v193 offset:40320
	s_waitcnt lgkmcnt(0)
	v_mfma_f32_16x16x32_bf16 v[140:143], v[144:147], v[12:15], v[140:143]
	v_mfma_f32_16x16x32_bf16 v[136:139], v[144:147], v[28:31], v[136:139]
	ds_read_b128 v[144:147], v193 offset:40384
	s_waitcnt lgkmcnt(0)
	v_mfma_f32_16x16x32_bf16 v[152:155], v[144:147], v[16:19], v[140:143]
	s_nop 3
	ds_read_b128 v[140:143], v193 offset:44544
	v_mfma_f32_16x16x32_bf16 v[136:139], v[144:147], v[32:35], v[136:139]
	s_waitcnt lgkmcnt(0)
	v_mfma_f32_16x16x32_bf16 v[144:147], v[140:143], v[4:7], 0
	v_mfma_f32_16x16x32_bf16 v[140:143], v[140:143], v[20:23], 0
	v_mfma_f32_16x16x32_bf16 v[144:147], v[156:159], v[8:11], v[144:147]
	v_mfma_f32_16x16x32_bf16 v[140:143], v[156:159], v[24:27], v[140:143]
	ds_read_b128 v[156:159], v193 offset:44672
	s_waitcnt lgkmcnt(0)
	v_mfma_f32_16x16x32_bf16 v[144:147], v[156:159], v[12:15], v[144:147]
	v_mfma_f32_16x16x32_bf16 v[140:143], v[156:159], v[28:31], v[140:143]
	v_mfma_f32_16x16x32_bf16 v[156:159], v[160:163], v[16:19], v[144:147]
	s_nop 5
	ds_read_b128 v[144:147], v194 offset:35840
	v_mfma_f32_16x16x32_bf16 v[140:143], v[160:163], v[32:35], v[140:143]
	s_waitcnt lgkmcnt(0)
	v_mfma_f32_16x16x32_bf16 v[160:163], v[144:147], v[4:7], 0
	v_mfma_f32_16x16x32_bf16 v[144:147], v[144:147], v[20:23], 0
	v_mfma_f32_16x16x32_bf16 v[160:163], v[222:225], v[8:11], v[160:163]
	v_mfma_f32_16x16x32_bf16 v[144:147], v[222:225], v[24:27], v[144:147]
	ds_read_b128 v[222:225], v194 offset:35968
	s_waitcnt lgkmcnt(0)
	v_mfma_f32_16x16x32_bf16 v[160:163], v[222:225], v[12:15], v[160:163]
	v_mfma_f32_16x16x32_bf16 v[144:147], v[222:225], v[28:31], v[144:147]
	ds_read_b128 v[222:225], v194 offset:36032
	s_waitcnt lgkmcnt(0)
	v_mfma_f32_16x16x32_bf16 v[160:163], v[222:225], v[16:19], v[160:163]
	v_mfma_f32_16x16x32_bf16 v[144:147], v[222:225], v[32:35], v[144:147]
	s_setprio 0
	v_max3_f32 v196, v148, s81, v149
	v_max3_f32 v196, v196, v150, v151
	v_max3_f32 v196, v196, v152, v153
	v_max3_f32 v196, v196, v154, v155
	v_max3_f32 v196, v196, v156, v157
	v_max3_f32 v196, v196, v158, v159
	v_max3_f32 v196, v196, v160, v161
	v_max3_f32 v196, v196, v162, v163
	v_mov_b32_e32 v197, v196
	s_nop 1
	v_permlane16_swap_b32_e32 v196, v197
	v_max_f32_e32 v196, v196, v197
	v_mov_b32_e32 v197, v196
	s_nop 1
	v_permlane32_swap_b32_e32 v196, v197
	v_max_f32_e32 v196, v196, v197
	v_add_f32_e32 v197, 0x427af232, v1
	v_cmp_gt_f32_e32 vcc, v196, v197
	s_cbranch_vccz .LBB0_1809
	v_max_f32_e32 v196, v196, v196
	v_max_f32_e32 v197, v1, v1
	v_max_f32_e32 v197, v197, v196
	v_cmp_eq_f32_e32 vcc, s81, v197
	s_nop 1
	v_cndmask_b32_e64 v196, v197, 0, vcc
	v_sub_f32_e32 v1, v1, v196
	v_mul_f32_e32 v1, 0x3e0293ee, v1
	v_exp_f32_e32 v196, v1
	v_mul_f32_e32 v1, 0x3e0293ee, v197
	v_cndmask_b32_e64 v202, v1, 0, vcc
	v_mov_b32_e32 v1, v197
	v_mul_f32_e32 v2, v2, v196
	v_pk_mul_f32 v[70:71], v[70:71], v[196:197] op_sel_hi:[1,0]
	v_pk_mul_f32 v[68:69], v[68:69], v[196:197] op_sel_hi:[1,0]
	v_pk_mul_f32 v[126:127], v[126:127], v[196:197] op_sel_hi:[1,0]
	v_pk_mul_f32 v[124:125], v[124:125], v[196:197] op_sel_hi:[1,0]
	v_pk_mul_f32 v[98:99], v[98:99], v[196:197] op_sel_hi:[1,0]
	v_pk_mul_f32 v[96:97], v[96:97], v[196:197] op_sel_hi:[1,0]
	v_pk_mul_f32 v[94:95], v[94:95], v[196:197] op_sel_hi:[1,0]
	v_pk_mul_f32 v[92:93], v[92:93], v[196:197] op_sel_hi:[1,0]
	v_pk_mul_f32 v[90:91], v[90:91], v[196:197] op_sel_hi:[1,0]
	v_pk_mul_f32 v[88:89], v[88:89], v[196:197] op_sel_hi:[1,0]
	v_pk_mul_f32 v[86:87], v[86:87], v[196:197] op_sel_hi:[1,0]
	v_pk_mul_f32 v[84:85], v[84:85], v[196:197] op_sel_hi:[1,0]
	v_pk_mul_f32 v[82:83], v[82:83], v[196:197] op_sel_hi:[1,0]
	v_pk_mul_f32 v[80:81], v[80:81], v[196:197] op_sel_hi:[1,0]
	v_pk_mul_f32 v[78:79], v[78:79], v[196:197] op_sel_hi:[1,0]
	v_pk_mul_f32 v[76:77], v[76:77], v[196:197] op_sel_hi:[1,0]
; __device__ __forceinline__ float ex2(float x) { return __builtin_amdgcn_exp2f(x); }
;   __device__ __forceinline__ bf16_t* W() const { return (bf16_t*)(ws + WS_W); }
; template <int NT, int NKK, int NDT, int MODE, bool MASK> ...
;     ...
;   for (int j = 0; j < NT; ++j) {
;     float mx = -INFINITY;
; #pragma unroll
;     for (int t = 0; t < 4; ++t)
; #pragma unroll
;       for (int i = 0; i < 4; ++i) {
;         if (MASK) { const int kp = kpos0 + 16 * t + 4 * lg + i; if (!mask_ok<MODE>(tq[j], kp, W)) s[j][t][i] = -INFINITY; }
;         mx = fmaxf(mx, s[j][t][i]);
;       }
;     mx = max_x16_x32(mx);
;     if (__any(mx > m[j] + 8.0f / c)) {
;       const float mnew = fmaxf(m[j], mx);
;       const float ms2 = (mnew == -INFINITY) ? 0.f : mnew;
;       const float alpha = ex2((m[j] - ms2) * c);
;       m[j] = mnew; l[j] *= alpha;
; #pragma unroll
;       for (int dt = 0; dt < NDT; ++dt) o[j][dt] *= alpha;
;     }
;     const float mc = ((m[j] == -INFINITY) ? 0.f : m[j]) * c;
;     float p[4][4], ps = 0.f;
; #pragma unroll
;     for (int t = 0; t < 4; ++t)
; #pragma unroll
;       for (int i = 0; i < 4; ++i) { p[t][i] = ex2(s[j][t][i] * c - mc); ps += p[t][i]; }
;     l[j] += ps;
.LBB0_1809:
	v_add_f32_e32 v196, v206, v205
	v_add_f32_e32 v196, v207, v196
	v_add_f32_e32 v196, v208, v196
	v_add_f32_e32 v196, v209, v196
	v_add_f32_e32 v196, v210, v196
	v_add_f32_e32 v196, v211, v196
	v_add_f32_e32 v196, v212, v196
	v_add_f32_e32 v196, v213, v196
	v_add_f32_e32 v196, v214, v196
	v_add_f32_e32 v196, v215, v196
	v_add_f32_e32 v196, v216, v196
	v_add_f32_e32 v196, v217, v196
	v_add_f32_e32 v196, v218, v196
	v_add_f32_e32 v196, v219, v196
	v_add_f32_e32 v196, v220, v196
	v_add_f32_e32 v195, v195, v196
	v_max3_f32 v196, v132, s81, v133
	v_max3_f32 v196, v196, v134, v135
	v_max3_f32 v196, v196, v136, v137
	v_max3_f32 v196, v196, v138, v139
	v_max3_f32 v196, v196, v140, v141
	v_max3_f32 v196, v196, v142, v143
	v_max3_f32 v196, v196, v144, v145
	v_max3_f32 v196, v196, v146, v147
	v_mov_b32_e32 v197, v196
	s_nop 1
	v_permlane16_swap_b32_e32 v196, v197
	v_max_f32_e32 v196, v196, v197
	v_mov_b32_e32 v197, v196
	s_nop 1
	v_permlane32_swap_b32_e32 v196, v197
	v_max_f32_e32 v196, v196, v197
	v_add_f32_e32 v197, 0x427af232, v201
	v_cmp_gt_f32_e32 vcc, v196, v197
	s_cbranch_vccz .LBB0_1772
	v_max_f32_e32 v3, v196, v196
	v_max_f32_e32 v196, v201, v201
	v_max_f32_e32 v197, v196, v3
	v_cmp_eq_f32_e32 vcc, s81, v197
	s_nop 1
	v_cndmask_b32_e64 v3, v197, 0, vcc
	v_sub_f32_e32 v3, v201, v3
	v_mul_f32_e32 v3, 0x3e0293ee, v3
	v_exp_f32_e32 v196, v3
	v_mul_f32_e32 v3, 0x3e0293ee, v197
	v_cndmask_b32_e64 v3, v3, 0, vcc
	v_mov_b32_e32 v201, v197
	v_mul_f32_e32 v195, v195, v196
	v_pk_mul_f32 v[74:75], v[74:75], v[196:197] op_sel_hi:[1,0]
	v_pk_mul_f32 v[72:73], v[72:73], v[196:197] op_sel_hi:[1,0]
	v_pk_mul_f32 v[130:131], v[130:131], v[196:197] op_sel_hi:[1,0]
	v_pk_mul_f32 v[128:129], v[128:129], v[196:197] op_sel_hi:[1,0]
	v_pk_mul_f32 v[122:123], v[122:123], v[196:197] op_sel_hi:[1,0]
	v_pk_mul_f32 v[120:121], v[120:121], v[196:197] op_sel_hi:[1,0]
	v_pk_mul_f32 v[118:119], v[118:119], v[196:197] op_sel_hi:[1,0]
	v_pk_mul_f32 v[116:117], v[116:117], v[196:197] op_sel_hi:[1,0]
	v_pk_mul_f32 v[114:115], v[114:115], v[196:197] op_sel_hi:[1,0]
	v_pk_mul_f32 v[112:113], v[112:113], v[196:197] op_sel_hi:[1,0]
	v_pk_mul_f32 v[110:111], v[110:111], v[196:197] op_sel_hi:[1,0]
	v_pk_mul_f32 v[108:109], v[108:109], v[196:197] op_sel_hi:[1,0]
	v_pk_mul_f32 v[106:107], v[106:107], v[196:197] op_sel_hi:[1,0]
	v_pk_mul_f32 v[104:105], v[104:105], v[196:197] op_sel_hi:[1,0]
	v_pk_mul_f32 v[102:103], v[102:103], v[196:197] op_sel_hi:[1,0]
	v_pk_mul_f32 v[100:101], v[100:101], v[196:197] op_sel_hi:[1,0]
	s_branch .LBB0_1772
